# K=1024 GEMM loops unrolled over 6 K steps so the 3-stage LDS ring positions are constants: fragment reads use fixed base registers + immediate offsets, LDS-DMA uses SGPR base addresses advanced by SAL
# speedup vs baseline: 1.0299x; 1.0044x over previous
; #define LAS __attribute__((address_space(3)))
;     ...
;   const int lane = tid & 63, wid = __builtin_amdgcn_readfirstlane(tid >> 6), wr = wid >> 1, wc = wid & 1;
;   const int m0 = mt * 128, n0 = nt * 256;
;   const int r = lane & 31, h = lane >> 5, key = (r >> 2) & 3;
;   constexpr int STG = 24576;
;   const int rowl = lane >> 2, cch = (lane & 3) ^ ((lane >> 4) & 3);
;   const unsigned voffA = (unsigned)(rowl * lda * 2 + cch * 16), voffB = (unsigned)(rowl * K * 2 + cch * 16);
;   const char* Abase = (const char*)(A + (size_t)m0 * lda) + (size_t)(wid * 2) * 32 * lda;
;   const char* Bbase = (const char*)(Bt + (size_t)n0 * K) + (size_t)(wid * 4) * 32 * K;
;   const size_t ablk = (size_t)32 * lda, bblk = (size_t)32 * K;
;   LAS char* lds = (LAS char*)smem;
;   LAS char* ldsA = lds + (wid * 2) * 1024;
;   LAS char* ldsB = lds + 8192 + (wid * 4) * 1024;
;     ...
;   const int x0 = ((0 + h) ^ key) * 16, x1 = ((2 + h) ^ key) * 16;
;   const int a_rd = (wr * 64 + r) * 64, b_rd = 8192 + (wc * 128 + r) * 64;
;   f32x16 acc[2][4];
; #pragma unroll
;   for (int i = 0; i < 2; ++i)
; #pragma unroll
;     for (int j = 0; j < 4; ++j)
; #pragma unroll
;       for (int e = 0; e < 16; ++e) acc[i][j][e] = 0.f;
;   const int nk = K >> 5;
;   DMA_STEP_(0, 0);
;   DMA_STEP_(1, STG);
;   asm volatile("s_waitcnt vmcnt(6)" ::: "memory");
;   __builtin_amdgcn_s_barrier();
;   asm volatile("" ::: "memory");
;   int s0 = 0, s2 = 2 * STG;
;   for (int kt = 0; kt < nk; ++kt) {
;     const int kn = (kt + 2 < nk) ? (kt + 2) : (nk - 1);
;     const LAS char* cur = lds + s0;
;     bf16x8 af[2][2], bfr[2][4];
; #pragma unroll
;     for (int kk = 0; kk < 2; ++kk) {
;       const int xo = kk ? x1 : x0;
;       af[kk][0] = *(const LAS bf16x8*)(cur + a_rd + xo);
;       bfr[kk][0] = *(const LAS bf16x8*)(cur + b_rd + xo);
;       bfr[kk][1] = *(const LAS bf16x8*)(cur + b_rd + 2048 + xo);
;       af[kk][1] = *(const LAS bf16x8*)(cur + a_rd + 2048 + xo);
;       bfr[kk][2] = *(const LAS bf16x8*)(cur + b_rd + 4096 + xo);
;       bfr[kk][3] = *(const LAS bf16x8*)(cur + b_rd + 6144 + xo);
.LBB0_20:
	s_ashr_i32 s10, s23, 31
	s_lshr_b32 s10, s10, 27
	s_add_i32 s10, s23, s10
	s_ashr_i32 s10, s10, 5
	v_readlane_b32 s11, v252, 18
	v_mov_b32_e32 v189, v188
	s_lshl_b32 s11, s10, s11
	v_readlane_b32 s12, v252, 41
	s_add_i32 s11, s11, s12
	v_readfirstlane_b32 s44, v189
	s_ashr_i32 s46, s44, 6
	s_lshl_b32 s12, s23, 7
	s_lshl_b32 s11, s11, 10
	s_and_b32 s12, s12, 0x380
	s_lshl_b32 s28, s46, 1
	s_or_b32 s12, s11, s12
	s_lshl_b32 s10, s10, 10
	s_lshl_b32 s11, s23, 5
	s_ashr_i32 s29, s28, 31
	s_sub_i32 s10, s11, s10
	s_lshl_b64 s[40:41], s[28:29], 15
	s_lshl_b32 s28, s46, 2
	s_ashr_i32 s11, s44, 1
	s_and_b32 s14, s10, 0xffffff00
	v_and_b32_e32 v0, 31, v189
	s_ashr_i32 s29, s28, 31
	s_lshl_b32 s10, s46, 12
	s_andn2_b32 s11, s11, 63
	v_lshlrev_b32_e32 v2, 4, v189
	s_ashr_i32 s13, s12, 31
	s_lshl_b64 s[42:43], s[28:29], 10
	s_add_i32 s29, s10, 16
	v_or_b32_e32 v197, s11, v0
	s_lshl_b32 s11, s46, 7
	v_bitop3_b32 v2, v2, 48, v189 bitop3:0x48
	v_lshlrev_b32_e32 v3, 9, v189
	s_ashr_i32 s15, s14, 31
	s_add_i32 s10, s29, 0x2000
	s_and_b32 s28, s11, 0x80
	s_movk_i32 s11, 0x7800
	s_lshl_b64 s[44:45], s[12:13], 11
	v_or_b32_e32 v4, s28, v0
	v_and_or_b32 v0, v3, s11, v2
	v_lshlrev_b32_e32 v10, 4, v189
	v_and_b32_e32 v10, 0x3c0, v10
	v_or_b32_e32 v10, v10, v2
	v_mov_b32_e32 v11, 0
	s_add_u32 s11, s21, s44
	s_addc_u32 s13, s22, s45
	s_add_u32 s40, s11, s40
	s_addc_u32 s41, s13, s41
	s_lshl_b64 s[44:45], s[14:15], 6
	s_add_u32 s11, s17, s44
	s_addc_u32 s13, s18, s45
	s_add_u32 s42, s11, s42
	s_addc_u32 s43, s13, s43
	s_lshl_b32 s11, s46, 11
	s_sub_i32 s13, s29, s11
	v_lshl_add_u64 v[192:193], s[40:41], 0, v[0:1]
	s_mov_b32 m0, s13
	v_lshl_add_u64 v[2:3], v[192:193], 0, s[72:73]
	global_load_lds_dwordx4 v0, s[40:41]
	s_add_i32 m0, s13, 0x400
	v_lshl_add_u64 v[194:195], s[42:43], 0, v[10:11]
	global_load_lds_dwordx4 v[2:3], off
	s_mov_b32 m0, s10
	s_nop 0
	global_load_lds_dwordx4 v[194:195], off
	global_load_lds_dwordx4 v[194:195], off offset:1024
	global_load_lds_dwordx4 v[194:195], off offset:2048
	global_load_lds_dwordx4 v[194:195], off offset:3072
	s_mov_b64 s[10:11], 0x10000
	s_mov_b64 s[10:11], 0x18000
	s_mov_b64 s[10:11], 0x8040
	s_add_i32 m0, s13, 0x6000
	v_lshl_add_u64 v[2:3], v[192:193], 0, 64
	global_load_lds_dwordx4 v[2:3], off
	v_lshl_add_u64 v[2:3], v[192:193], 0, s[10:11]
	s_add_i32 m0, s13, 0x6400
	v_bfe_u32 v196, v189, 5, 1
	global_load_lds_dwordx4 v[2:3], off
	s_add_i32 m0, s29, 0x8000
	s_mov_b32 s100, 0x10000
	v_lshl_add_u64 v[2:3], v[194:195], 0, s[100:101]
	global_load_lds_dwordx4 v[2:3], off
	global_load_lds_dwordx4 v[2:3], off offset:1024
	global_load_lds_dwordx4 v[2:3], off offset:2048
	global_load_lds_dwordx4 v[2:3], off offset:3072
	s_mov_b64 s[10:11], 0x10040
	s_mov_b64 s[10:11], 0x18040
	v_lshlrev_b32_e32 v218, 6, v4
	v_bfe_u32 v4, v189, 2, 2
	v_lshrrev_b32_e32 v5, 5, v189
	s_lshl_b32 s100, s100, 1
	v_lshl_add_u64 v[194:195], v[194:195], 0, s[100:101]
	s_waitcnt vmcnt(6)
	s_barrier
	v_bitop3_b32 v2, v196, v4, 2 bitop3:0x36
	v_bitop3_b32 v0, v5, v4, 1 bitop3:0x6c
	v_lshlrev_b32_e32 v220, 4, v2
	v_mov_b32_e32 v2, 0
	v_lshlrev_b32_e32 v219, 6, v197
	v_lshlrev_b32_e32 v0, 4, v0
	s_mov_b32 s41, 0xc000
	s_mov_b32 s40, 0
	s_mov_b32 s42, 0
	v_mov_b32_e32 v3, v2
	v_mov_b32_e32 v4, v2
	v_mov_b32_e32 v5, v2
	v_mov_b32_e32 v6, v2
	v_mov_b32_e32 v7, v2
	v_mov_b32_e32 v8, v2
	v_mov_b32_e32 v9, v2
	v_mov_b32_e32 v10, v2
	v_mov_b32_e32 v11, v2
	v_mov_b32_e32 v12, v2
	v_mov_b32_e32 v13, v2
	v_mov_b32_e32 v14, v2
	v_mov_b32_e32 v15, v2
	v_mov_b32_e32 v16, v2
	v_mov_b32_e32 v17, v2
	v_mov_b32_e32 v18, v2
	v_mov_b32_e32 v19, v2
	v_mov_b32_e32 v20, v2
	v_mov_b32_e32 v21, v2
	v_mov_b32_e32 v22, v2
	v_mov_b32_e32 v23, v2
	v_mov_b32_e32 v24, v2
	v_mov_b32_e32 v25, v2
	v_mov_b32_e32 v26, v2
	v_mov_b32_e32 v27, v2
	v_mov_b32_e32 v28, v2
	v_mov_b32_e32 v29, v2
	v_mov_b32_e32 v30, v2
	v_mov_b32_e32 v31, v2
	v_mov_b32_e32 v32, v2
	v_mov_b32_e32 v33, v2
	v_mov_b32_e32 v50, v2
	v_mov_b32_e32 v51, v2
	v_mov_b32_e32 v52, v2
	v_mov_b32_e32 v53, v2
	v_mov_b32_e32 v54, v2
	v_mov_b32_e32 v55, v2
	v_mov_b32_e32 v56, v2
	v_mov_b32_e32 v57, v2
	v_mov_b32_e32 v58, v2
	v_mov_b32_e32 v59, v2
	v_mov_b32_e32 v60, v2
	v_mov_b32_e32 v61, v2
	v_mov_b32_e32 v62, v2
	v_mov_b32_e32 v63, v2
	v_mov_b32_e32 v64, v2
	v_mov_b32_e32 v65, v2
	v_mov_b32_e32 v82, v2
	v_mov_b32_e32 v83, v2
	v_mov_b32_e32 v84, v2
	v_mov_b32_e32 v85, v2
	v_mov_b32_e32 v86, v2
	v_mov_b32_e32 v87, v2
	v_mov_b32_e32 v88, v2
	v_mov_b32_e32 v89, v2
	s_waitcnt vmcnt(0)
	v_mov_b32_e32 v90, v2
	v_mov_b32_e32 v91, v2
	v_mov_b32_e32 v92, v2
	v_mov_b32_e32 v93, v2
	v_mov_b32_e32 v94, v2
	v_mov_b32_e32 v95, v2
	v_mov_b32_e32 v96, v2
	v_mov_b32_e32 v97, v2
	v_mov_b32_e32 v34, v2
	v_mov_b32_e32 v35, v2
	v_mov_b32_e32 v36, v2
	v_mov_b32_e32 v37, v2
	v_mov_b32_e32 v38, v2
	v_mov_b32_e32 v39, v2
	v_mov_b32_e32 v40, v2
	v_mov_b32_e32 v41, v2
	v_mov_b32_e32 v42, v2
	v_mov_b32_e32 v43, v2
	v_mov_b32_e32 v44, v2
	v_mov_b32_e32 v45, v2
	v_mov_b32_e32 v46, v2
	v_mov_b32_e32 v47, v2
	v_mov_b32_e32 v48, v2
	v_mov_b32_e32 v49, v2
	v_mov_b32_e32 v66, v2
	v_mov_b32_e32 v67, v2
	v_mov_b32_e32 v68, v2
	v_mov_b32_e32 v69, v2
	v_mov_b32_e32 v70, v2
	v_mov_b32_e32 v71, v2
	v_mov_b32_e32 v72, v2
	v_mov_b32_e32 v73, v2
	v_mov_b32_e32 v74, v2
	v_mov_b32_e32 v75, v2
	v_mov_b32_e32 v76, v2
	v_mov_b32_e32 v77, v2
	v_mov_b32_e32 v78, v2
	v_mov_b32_e32 v79, v2
	v_mov_b32_e32 v80, v2
	v_mov_b32_e32 v81, v2
	v_mov_b32_e32 v98, v2
	v_mov_b32_e32 v99, v2
	v_mov_b32_e32 v100, v2
	v_mov_b32_e32 v101, v2
	v_mov_b32_e32 v102, v2
	v_mov_b32_e32 v103, v2
	v_mov_b32_e32 v104, v2
	v_mov_b32_e32 v105, v2
	v_mov_b32_e32 v106, v2
	v_mov_b32_e32 v107, v2
	v_mov_b32_e32 v108, v2
	v_mov_b32_e32 v109, v2
	v_mov_b32_e32 v110, v2
	v_mov_b32_e32 v111, v2
	v_mov_b32_e32 v112, v2
	v_mov_b32_e32 v113, v2
	v_mov_b32_e32 v114, v2
	v_mov_b32_e32 v115, v2
	v_mov_b32_e32 v116, v2
	v_mov_b32_e32 v117, v2
	v_mov_b32_e32 v118, v2
	v_mov_b32_e32 v119, v2
	v_mov_b32_e32 v120, v2
	v_mov_b32_e32 v121, v2
	v_mov_b32_e32 v122, v2
	v_mov_b32_e32 v123, v2
	v_mov_b32_e32 v124, v2
	v_mov_b32_e32 v125, v2
	v_mov_b32_e32 v126, v2
	v_mov_b32_e32 v127, v2
	v_mov_b32_e32 v128, v2
	v_mov_b32_e32 v129, v2
	v_readfirstlane_b32 s10, v192
	v_readfirstlane_b32 s11, v193
	v_readfirstlane_b32 s100, v194
	v_readfirstlane_b32 s101, v195
	s_sub_u32 s10, s10, 0x100000
	s_subb_u32 s11, s11, 0
	s_sub_u32 s100, s100, 0x100000
	s_subb_u32 s101, s101, 0
	v_subrev_u32_e32 v238, s10, v192
	v_subrev_u32_e32 v239, s100, v194
	s_add_u32 vcc_lo, s10, s24
	s_addc_u32 vcc_hi, s11, s25
	s_add_u32 s70, s10, s38
	s_addc_u32 s71, s11, s39
	v_add3_u32 v226, v219, v0, 16
	v_add3_u32 v227, v218, v0, 16
	v_add3_u32 v228, v219, v220, 16
	v_add3_u32 v229, v218, v220, 16
	ds_read_b128 v[154:157], v226 offset:0
	ds_read_b128 v[182:185], v227 offset:8192
	ds_read_b128 v[178:181], v227 offset:10240
	ds_read_b128 v[158:161], v226 offset:2048
	ds_read_b128 v[174:177], v227 offset:12288
	ds_read_b128 v[170:173], v227 offset:14336
	s_setprio 1
; #define LAS __attribute__((address_space(3)))
; DI f32x16 mfma32(bf16x8 a, bf16x8 b, f32x16 c) { return __builtin_amdgcn_mfma_f32_32x32x16_bf16(a, b, c, 0, 0, 0); }
;     ...
;   for (int kt = 0; kt < nk; ++kt) {
;     const int kn = (kt + 2 < nk) ? (kt + 2) : (nk - 1);
;     const LAS char* cur = lds + s0;
;     bf16x8 af[2][2], bfr[2][4];
; #pragma unroll
;     for (int kk = 0; kk < 2; ++kk) {
;       const int xo = kk ? x1 : x0;
;       af[kk][0] = *(const LAS bf16x8*)(cur + a_rd + xo);
;       bfr[kk][0] = *(const LAS bf16x8*)(cur + b_rd + xo);
;       bfr[kk][1] = *(const LAS bf16x8*)(cur + b_rd + 2048 + xo);
;       af[kk][1] = *(const LAS bf16x8*)(cur + a_rd + 2048 + xo);
;       bfr[kk][2] = *(const LAS bf16x8*)(cur + b_rd + 4096 + xo);
;       bfr[kk][3] = *(const LAS bf16x8*)(cur + b_rd + 6144 + xo);
;     }
;     DMA_STEP_(kn, s2);
; #pragma unroll
;     for (int kk = 0; kk < 2; ++kk) {
;       acc[0][0] = mfma32(bfr[kk][0], af[kk][0], acc[0][0]); acc[0][1] = mfma32(bfr[kk][1], af[kk][0], acc[0][1]);
;       acc[1][0] = mfma32(bfr[kk][0], af[kk][1], acc[1][0]); acc[1][1] = mfma32(bfr[kk][1], af[kk][1], acc[1][1]);
;       acc[0][2] = mfma32(bfr[kk][2], af[kk][0], acc[0][2]); acc[0][3] = mfma32(bfr[kk][3], af[kk][0], acc[0][3]);
;       acc[1][2] = mfma32(bfr[kk][2], af[kk][1], acc[1][2]); acc[1][3] = mfma32(bfr[kk][3], af[kk][1], acc[1][3]);
;     }
;     __builtin_amdgcn_sched_group_barrier(0x100, 12, 0);
;     __builtin_amdgcn_sched_group_barrier(0x010, 6, 0);
;     __builtin_amdgcn_sched_group_barrier(0x008, 16, 0);
;     asm volatile("s_waitcnt vmcnt(6) lgkmcnt(0)" ::: "memory");
;     __builtin_amdgcn_s_barrier();
;     asm volatile("" ::: "memory");
;     s0 = (s0 == 2 * STG) ? 0 : s0 + STG;
;     s2 = (s2 == 2 * STG) ? 0 : s2 + STG;
;   }
.LBB0_21:
	ds_read_b128 v[138:141], v228 offset:0
	ds_read_b128 v[162:165], v229 offset:8192
	ds_read_b128 v[166:169], v229 offset:10240
	ds_read_b128 v[142:145], v228 offset:2048
	ds_read_b128 v[146:149], v229 offset:12288
	ds_read_b128 v[150:153], v229 offset:14336
	s_add_i32 m0, s13, 0xc000
	s_waitcnt lgkmcnt(6)
	v_mfma_f32_32x32x16_bf16 v[114:129], v[182:185], v[154:157], v[114:129]
	global_load_lds_dwordx4 v238, vcc
	s_add_i32 m0, s13, 0xc400
	s_add_u32 vcc_lo, vcc_lo, 64
	s_addc_u32 vcc_hi, vcc_hi, 0
	v_mfma_f32_32x32x16_bf16 v[98:113], v[178:181], v[154:157], v[98:113]
	global_load_lds_dwordx4 v238, s[70:71]
	s_add_i32 m0, s29, 0xe000
	s_add_u32 s70, s70, 64
	s_addc_u32 s71, s71, 0
	v_mfma_f32_32x32x16_bf16 v[66:81], v[182:185], v[158:161], v[66:81]
	global_load_lds_dwordx4 v239, s[100:101]
	v_mfma_f32_32x32x16_bf16 v[34:49], v[178:181], v[158:161], v[34:49]
	global_load_lds_dwordx4 v239, s[100:101] offset:1024
	v_mfma_f32_32x32x16_bf16 v[82:97], v[174:177], v[154:157], v[82:97]
	global_load_lds_dwordx4 v239, s[100:101] offset:2048
	v_mfma_f32_32x32x16_bf16 v[50:65], v[170:173], v[154:157], v[50:65]
	global_load_lds_dwordx4 v239, s[100:101] offset:3072
	s_add_u32 s100, s100, 0x10000
	s_addc_u32 s101, s101, 0
	v_mfma_f32_32x32x16_bf16 v[18:33], v[174:177], v[158:161], v[18:33]
	v_mfma_f32_32x32x16_bf16 v[2:17], v[170:173], v[158:161], v[2:17]
	s_waitcnt vmcnt(6) lgkmcnt(0)
	s_barrier
	ds_read_b128 v[154:157], v226 offset:24576
	ds_read_b128 v[182:185], v227 offset:32768
	ds_read_b128 v[178:181], v227 offset:34816
	ds_read_b128 v[158:161], v226 offset:26624
	ds_read_b128 v[174:177], v227 offset:36864
	ds_read_b128 v[170:173], v227 offset:38912
	v_mfma_f32_32x32x16_bf16 v[114:129], v[162:165], v[138:141], v[114:129]
	v_mfma_f32_32x32x16_bf16 v[98:113], v[166:169], v[138:141], v[98:113]
	v_mfma_f32_32x32x16_bf16 v[66:81], v[162:165], v[142:145], v[66:81]
	v_mfma_f32_32x32x16_bf16 v[34:49], v[166:169], v[142:145], v[34:49]
	v_mfma_f32_32x32x16_bf16 v[82:97], v[146:149], v[138:141], v[82:97]
	v_mfma_f32_32x32x16_bf16 v[50:65], v[150:153], v[138:141], v[50:65]
	v_mfma_f32_32x32x16_bf16 v[18:33], v[146:149], v[142:145], v[18:33]
	v_mfma_f32_32x32x16_bf16 v[2:17], v[150:153], v[142:145], v[2:17]
	ds_read_b128 v[138:141], v228 offset:24576
	ds_read_b128 v[162:165], v229 offset:32768
	ds_read_b128 v[166:169], v229 offset:34816
	ds_read_b128 v[142:145], v228 offset:26624
	ds_read_b128 v[146:149], v229 offset:36864
	ds_read_b128 v[150:153], v229 offset:38912
	s_add_i32 m0, s13, 0x0
	s_waitcnt lgkmcnt(6)
	v_mfma_f32_32x32x16_bf16 v[114:129], v[182:185], v[154:157], v[114:129]
	global_load_lds_dwordx4 v238, vcc
	s_add_i32 m0, s13, 0x400
	s_add_u32 vcc_lo, vcc_lo, 64
	s_addc_u32 vcc_hi, vcc_hi, 0
	v_mfma_f32_32x32x16_bf16 v[98:113], v[178:181], v[154:157], v[98:113]
	global_load_lds_dwordx4 v238, s[70:71]
	s_add_i32 m0, s29, 0x2000
	s_add_u32 s70, s70, 64
	s_addc_u32 s71, s71, 0
	v_mfma_f32_32x32x16_bf16 v[66:81], v[182:185], v[158:161], v[66:81]
	global_load_lds_dwordx4 v239, s[100:101]
	v_mfma_f32_32x32x16_bf16 v[34:49], v[178:181], v[158:161], v[34:49]
	global_load_lds_dwordx4 v239, s[100:101] offset:1024
	v_mfma_f32_32x32x16_bf16 v[82:97], v[174:177], v[154:157], v[82:97]
	global_load_lds_dwordx4 v239, s[100:101] offset:2048
	v_mfma_f32_32x32x16_bf16 v[50:65], v[170:173], v[154:157], v[50:65]
	global_load_lds_dwordx4 v239, s[100:101] offset:3072
	s_add_u32 s100, s100, 0x10000
	s_addc_u32 s101, s101, 0
	v_mfma_f32_32x32x16_bf16 v[18:33], v[174:177], v[158:161], v[18:33]
	v_mfma_f32_32x32x16_bf16 v[2:17], v[170:173], v[158:161], v[2:17]
	s_waitcnt vmcnt(6) lgkmcnt(0)
	s_barrier
	ds_read_b128 v[154:157], v226 offset:49152
	ds_read_b128 v[182:185], v227 offset:57344
	ds_read_b128 v[178:181], v227 offset:59392
	ds_read_b128 v[158:161], v226 offset:51200
	ds_read_b128 v[174:177], v227 offset:61440
	ds_read_b128 v[170:173], v227 offset:63488
	v_mfma_f32_32x32x16_bf16 v[114:129], v[162:165], v[138:141], v[114:129]
	v_mfma_f32_32x32x16_bf16 v[98:113], v[166:169], v[138:141], v[98:113]
	v_mfma_f32_32x32x16_bf16 v[66:81], v[162:165], v[142:145], v[66:81]
	v_mfma_f32_32x32x16_bf16 v[34:49], v[166:169], v[142:145], v[34:49]
	v_mfma_f32_32x32x16_bf16 v[82:97], v[146:149], v[138:141], v[82:97]
	v_mfma_f32_32x32x16_bf16 v[50:65], v[150:153], v[138:141], v[50:65]
	v_mfma_f32_32x32x16_bf16 v[18:33], v[146:149], v[142:145], v[18:33]
	v_mfma_f32_32x32x16_bf16 v[2:17], v[150:153], v[142:145], v[2:17]
	ds_read_b128 v[138:141], v228 offset:49152
	ds_read_b128 v[162:165], v229 offset:57344
	ds_read_b128 v[166:169], v229 offset:59392
	ds_read_b128 v[142:145], v228 offset:51200
	ds_read_b128 v[146:149], v229 offset:61440
	ds_read_b128 v[150:153], v229 offset:63488
	s_add_i32 m0, s13, 0x6000
	s_waitcnt lgkmcnt(6)
	v_mfma_f32_32x32x16_bf16 v[114:129], v[182:185], v[154:157], v[114:129]
	global_load_lds_dwordx4 v238, vcc
	s_add_i32 m0, s13, 0x6400
	s_add_u32 vcc_lo, vcc_lo, 64
	s_addc_u32 vcc_hi, vcc_hi, 0
	v_mfma_f32_32x32x16_bf16 v[98:113], v[178:181], v[154:157], v[98:113]
	global_load_lds_dwordx4 v238, s[70:71]
	s_add_i32 m0, s29, 0x8000
	s_add_u32 s70, s70, 64
	s_addc_u32 s71, s71, 0
	v_mfma_f32_32x32x16_bf16 v[66:81], v[182:185], v[158:161], v[66:81]
	global_load_lds_dwordx4 v239, s[100:101]
	v_mfma_f32_32x32x16_bf16 v[34:49], v[178:181], v[158:161], v[34:49]
	global_load_lds_dwordx4 v239, s[100:101] offset:1024
	v_mfma_f32_32x32x16_bf16 v[82:97], v[174:177], v[154:157], v[82:97]
	global_load_lds_dwordx4 v239, s[100:101] offset:2048
	v_mfma_f32_32x32x16_bf16 v[50:65], v[170:173], v[154:157], v[50:65]
	global_load_lds_dwordx4 v239, s[100:101] offset:3072
	s_add_u32 s100, s100, 0x10000
	s_addc_u32 s101, s101, 0
	v_mfma_f32_32x32x16_bf16 v[18:33], v[174:177], v[158:161], v[18:33]
	v_mfma_f32_32x32x16_bf16 v[2:17], v[170:173], v[158:161], v[2:17]
	s_waitcnt vmcnt(6) lgkmcnt(0)
	s_barrier
; #define LAS __attribute__((address_space(3)))
; DI f32x16 mfma32(bf16x8 a, bf16x8 b, f32x16 c) { return __builtin_amdgcn_mfma_f32_32x32x16_bf16(a, b, c, 0, 0, 0); }
;     ...
;   for (int kt = 0; kt < nk; ++kt) {
;     const int kn = (kt + 2 < nk) ? (kt + 2) : (nk - 1);
;     const LAS char* cur = lds + s0;
;     bf16x8 af[2][2], bfr[2][4];
; #pragma unroll
;     for (int kk = 0; kk < 2; ++kk) {
;       const int xo = kk ? x1 : x0;
;       af[kk][0] = *(const LAS bf16x8*)(cur + a_rd + xo);
;       bfr[kk][0] = *(const LAS bf16x8*)(cur + b_rd + xo);
;       bfr[kk][1] = *(const LAS bf16x8*)(cur + b_rd + 2048 + xo);
;       af[kk][1] = *(const LAS bf16x8*)(cur + a_rd + 2048 + xo);
;       bfr[kk][2] = *(const LAS bf16x8*)(cur + b_rd + 4096 + xo);
;       bfr[kk][3] = *(const LAS bf16x8*)(cur + b_rd + 6144 + xo);
;     }
;     DMA_STEP_(kn, s2);
; #pragma unroll
;     for (int kk = 0; kk < 2; ++kk) {
;       acc[0][0] = mfma32(bfr[kk][0], af[kk][0], acc[0][0]); acc[0][1] = mfma32(bfr[kk][1], af[kk][0], acc[0][1]);
;       acc[1][0] = mfma32(bfr[kk][0], af[kk][1], acc[1][0]); acc[1][1] = mfma32(bfr[kk][1], af[kk][1], acc[1][1]);
;       acc[0][2] = mfma32(bfr[kk][2], af[kk][0], acc[0][2]); acc[0][3] = mfma32(bfr[kk][3], af[kk][0], acc[0][3]);
;       acc[1][2] = mfma32(bfr[kk][2], af[kk][1], acc[1][2]); acc[1][3] = mfma32(bfr[kk][3], af[kk][1], acc[1][3]);
;     }
;     __builtin_amdgcn_sched_group_barrier(0x100, 12, 0);
;     __builtin_amdgcn_sched_group_barrier(0x010, 6, 0);
;     __builtin_amdgcn_sched_group_barrier(0x008, 16, 0);
;     asm volatile("s_waitcnt vmcnt(6) lgkmcnt(0)" ::: "memory");
;     __builtin_amdgcn_s_barrier();
;     asm volatile("" ::: "memory");
;     s0 = (s0 == 2 * STG) ? 0 : s0 + STG;
;     s2 = (s2 == 2 * STG) ? 0 : s2 + STG;
;   }
	ds_read_b128 v[154:157], v226 offset:0
	ds_read_b128 v[182:185], v227 offset:8192
	ds_read_b128 v[178:181], v227 offset:10240
	ds_read_b128 v[158:161], v226 offset:2048
	ds_read_b128 v[174:177], v227 offset:12288
	ds_read_b128 v[170:173], v227 offset:14336
	v_mfma_f32_32x32x16_bf16 v[114:129], v[162:165], v[138:141], v[114:129]
	v_mfma_f32_32x32x16_bf16 v[98:113], v[166:169], v[138:141], v[98:113]
	v_mfma_f32_32x32x16_bf16 v[66:81], v[162:165], v[142:145], v[66:81]
	v_mfma_f32_32x32x16_bf16 v[34:49], v[166:169], v[142:145], v[34:49]
	v_mfma_f32_32x32x16_bf16 v[82:97], v[146:149], v[138:141], v[82:97]
	v_mfma_f32_32x32x16_bf16 v[50:65], v[150:153], v[138:141], v[50:65]
	v_mfma_f32_32x32x16_bf16 v[18:33], v[146:149], v[142:145], v[18:33]
	v_mfma_f32_32x32x16_bf16 v[2:17], v[150:153], v[142:145], v[2:17]
	ds_read_b128 v[138:141], v228 offset:0
	ds_read_b128 v[162:165], v229 offset:8192
	ds_read_b128 v[166:169], v229 offset:10240
	ds_read_b128 v[142:145], v228 offset:2048
	ds_read_b128 v[146:149], v229 offset:12288
	ds_read_b128 v[150:153], v229 offset:14336
	s_add_i32 m0, s13, 0xc000
	s_waitcnt lgkmcnt(6)
	v_mfma_f32_32x32x16_bf16 v[114:129], v[182:185], v[154:157], v[114:129]
	global_load_lds_dwordx4 v238, vcc
	s_add_i32 m0, s13, 0xc400
	s_add_u32 vcc_lo, vcc_lo, 64
	s_addc_u32 vcc_hi, vcc_hi, 0
	v_mfma_f32_32x32x16_bf16 v[98:113], v[178:181], v[154:157], v[98:113]
	global_load_lds_dwordx4 v238, s[70:71]
	s_add_i32 m0, s29, 0xe000
	s_add_u32 s70, s70, 64
	s_addc_u32 s71, s71, 0
	v_mfma_f32_32x32x16_bf16 v[66:81], v[182:185], v[158:161], v[66:81]
	global_load_lds_dwordx4 v239, s[100:101]
	v_mfma_f32_32x32x16_bf16 v[34:49], v[178:181], v[158:161], v[34:49]
	global_load_lds_dwordx4 v239, s[100:101] offset:1024
	v_mfma_f32_32x32x16_bf16 v[82:97], v[174:177], v[154:157], v[82:97]
	global_load_lds_dwordx4 v239, s[100:101] offset:2048
	v_mfma_f32_32x32x16_bf16 v[50:65], v[170:173], v[154:157], v[50:65]
	global_load_lds_dwordx4 v239, s[100:101] offset:3072
	s_add_u32 s100, s100, 0x10000
	s_addc_u32 s101, s101, 0
	v_mfma_f32_32x32x16_bf16 v[18:33], v[174:177], v[158:161], v[18:33]
	v_mfma_f32_32x32x16_bf16 v[2:17], v[170:173], v[158:161], v[2:17]
	s_waitcnt vmcnt(6) lgkmcnt(0)
	s_barrier
	ds_read_b128 v[154:157], v226 offset:24576
	ds_read_b128 v[182:185], v227 offset:32768
	ds_read_b128 v[178:181], v227 offset:34816
	ds_read_b128 v[158:161], v226 offset:26624
	ds_read_b128 v[174:177], v227 offset:36864
	ds_read_b128 v[170:173], v227 offset:38912
	v_mfma_f32_32x32x16_bf16 v[114:129], v[162:165], v[138:141], v[114:129]
	v_mfma_f32_32x32x16_bf16 v[98:113], v[166:169], v[138:141], v[98:113]
	v_mfma_f32_32x32x16_bf16 v[66:81], v[162:165], v[142:145], v[66:81]
	v_mfma_f32_32x32x16_bf16 v[34:49], v[166:169], v[142:145], v[34:49]
	v_mfma_f32_32x32x16_bf16 v[82:97], v[146:149], v[138:141], v[82:97]
	v_mfma_f32_32x32x16_bf16 v[50:65], v[150:153], v[138:141], v[50:65]
	v_mfma_f32_32x32x16_bf16 v[18:33], v[146:149], v[142:145], v[18:33]
	v_mfma_f32_32x32x16_bf16 v[2:17], v[150:153], v[142:145], v[2:17]
	ds_read_b128 v[138:141], v228 offset:24576
	ds_read_b128 v[162:165], v229 offset:32768
	ds_read_b128 v[166:169], v229 offset:34816
	ds_read_b128 v[142:145], v228 offset:26624
	ds_read_b128 v[146:149], v229 offset:36864
	ds_read_b128 v[150:153], v229 offset:38912
	s_add_i32 m0, s13, 0x0
	s_waitcnt lgkmcnt(6)
	v_mfma_f32_32x32x16_bf16 v[114:129], v[182:185], v[154:157], v[114:129]
	global_load_lds_dwordx4 v238, vcc
	s_add_i32 m0, s13, 0x400
	s_add_u32 vcc_lo, vcc_lo, 64
	s_addc_u32 vcc_hi, vcc_hi, 0
	v_mfma_f32_32x32x16_bf16 v[98:113], v[178:181], v[154:157], v[98:113]
	global_load_lds_dwordx4 v238, s[70:71]
	s_add_i32 m0, s29, 0x2000
	s_add_u32 s70, s70, 64
	s_addc_u32 s71, s71, 0
	v_mfma_f32_32x32x16_bf16 v[66:81], v[182:185], v[158:161], v[66:81]
	global_load_lds_dwordx4 v239, s[100:101]
	v_mfma_f32_32x32x16_bf16 v[34:49], v[178:181], v[158:161], v[34:49]
	global_load_lds_dwordx4 v239, s[100:101] offset:1024
	v_mfma_f32_32x32x16_bf16 v[82:97], v[174:177], v[154:157], v[82:97]
	global_load_lds_dwordx4 v239, s[100:101] offset:2048
	v_mfma_f32_32x32x16_bf16 v[50:65], v[170:173], v[154:157], v[50:65]
	global_load_lds_dwordx4 v239, s[100:101] offset:3072
	s_add_u32 s100, s100, 0x10000
	s_addc_u32 s101, s101, 0
	v_mfma_f32_32x32x16_bf16 v[18:33], v[174:177], v[158:161], v[18:33]
	v_mfma_f32_32x32x16_bf16 v[2:17], v[170:173], v[158:161], v[2:17]
	s_waitcnt vmcnt(6) lgkmcnt(0)
	s_barrier
	ds_read_b128 v[154:157], v226 offset:49152
	ds_read_b128 v[182:185], v227 offset:57344
	ds_read_b128 v[178:181], v227 offset:59392
	ds_read_b128 v[158:161], v226 offset:51200
	ds_read_b128 v[174:177], v227 offset:61440
	ds_read_b128 v[170:173], v227 offset:63488
	v_mfma_f32_32x32x16_bf16 v[114:129], v[162:165], v[138:141], v[114:129]
	v_mfma_f32_32x32x16_bf16 v[98:113], v[166:169], v[138:141], v[98:113]
	v_mfma_f32_32x32x16_bf16 v[66:81], v[162:165], v[142:145], v[66:81]
	v_mfma_f32_32x32x16_bf16 v[34:49], v[166:169], v[142:145], v[34:49]
	v_mfma_f32_32x32x16_bf16 v[82:97], v[146:149], v[138:141], v[82:97]
	v_mfma_f32_32x32x16_bf16 v[50:65], v[150:153], v[138:141], v[50:65]
	v_mfma_f32_32x32x16_bf16 v[18:33], v[146:149], v[142:145], v[18:33]
	v_mfma_f32_32x32x16_bf16 v[2:17], v[150:153], v[142:145], v[2:17]
	ds_read_b128 v[138:141], v228 offset:49152
	ds_read_b128 v[162:165], v229 offset:57344
	ds_read_b128 v[166:169], v229 offset:59392
	ds_read_b128 v[142:145], v228 offset:51200
	ds_read_b128 v[146:149], v229 offset:61440
	ds_read_b128 v[150:153], v229 offset:63488
	s_add_i32 m0, s13, 0x6000
	s_waitcnt lgkmcnt(6)
	v_mfma_f32_32x32x16_bf16 v[114:129], v[182:185], v[154:157], v[114:129]
	global_load_lds_dwordx4 v238, vcc
	s_add_i32 m0, s13, 0x6400
	s_add_u32 vcc_lo, vcc_lo, 64
	s_addc_u32 vcc_hi, vcc_hi, 0
	v_mfma_f32_32x32x16_bf16 v[98:113], v[178:181], v[154:157], v[98:113]
	global_load_lds_dwordx4 v238, s[70:71]
	s_add_i32 m0, s29, 0x8000
	s_add_u32 s70, s70, 64
	s_addc_u32 s71, s71, 0
	v_mfma_f32_32x32x16_bf16 v[66:81], v[182:185], v[158:161], v[66:81]
	global_load_lds_dwordx4 v239, s[100:101]
	v_mfma_f32_32x32x16_bf16 v[34:49], v[178:181], v[158:161], v[34:49]
	global_load_lds_dwordx4 v239, s[100:101] offset:1024
	v_mfma_f32_32x32x16_bf16 v[82:97], v[174:177], v[154:157], v[82:97]
	global_load_lds_dwordx4 v239, s[100:101] offset:2048
	v_mfma_f32_32x32x16_bf16 v[50:65], v[170:173], v[154:157], v[50:65]
	global_load_lds_dwordx4 v239, s[100:101] offset:3072
	s_add_u32 s100, s100, 0x10000
	s_addc_u32 s101, s101, 0
	v_mfma_f32_32x32x16_bf16 v[18:33], v[174:177], v[158:161], v[18:33]
	v_mfma_f32_32x32x16_bf16 v[2:17], v[170:173], v[158:161], v[2:17]
	s_waitcnt vmcnt(6) lgkmcnt(0)
	s_barrier
; #define LAS __attribute__((address_space(3)))
; DI unsigned pk2(float a, float b) { f32x2 v = {a, b}; bf2_t r = __builtin_convertvector(v, bf2_t); return __builtin_bit_cast(unsigned, r); }
;     ...
;   for (int kt = 0; kt < nk; ++kt) {
;     const int kn = (kt + 2 < nk) ? (kt + 2) : (nk - 1);
;     const LAS char* cur = lds + s0;
;     bf16x8 af[2][2], bfr[2][4];
; #pragma unroll
;     for (int kk = 0; kk < 2; ++kk) {
;       const int xo = kk ? x1 : x0;
;       af[kk][0] = *(const LAS bf16x8*)(cur + a_rd + xo);
;       bfr[kk][0] = *(const LAS bf16x8*)(cur + b_rd + xo);
;       bfr[kk][1] = *(const LAS bf16x8*)(cur + b_rd + 2048 + xo);
;       af[kk][1] = *(const LAS bf16x8*)(cur + a_rd + 2048 + xo);
;       bfr[kk][2] = *(const LAS bf16x8*)(cur + b_rd + 4096 + xo);
;       bfr[kk][3] = *(const LAS bf16x8*)(cur + b_rd + 6144 + xo);
;     }
;     DMA_STEP_(kn, s2);
; #pragma unroll
;     for (int kk = 0; kk < 2; ++kk) {
;       acc[0][0] = mfma32(bfr[kk][0], af[kk][0], acc[0][0]); acc[0][1] = mfma32(bfr[kk][1], af[kk][0], acc[0][1]);
;       acc[1][0] = mfma32(bfr[kk][0], af[kk][1], acc[1][0]); acc[1][1] = mfma32(bfr[kk][1], af[kk][1], acc[1][1]);
;       acc[0][2] = mfma32(bfr[kk][2], af[kk][0], acc[0][2]); acc[0][3] = mfma32(bfr[kk][3], af[kk][0], acc[0][3]);
;       acc[1][2] = mfma32(bfr[kk][2], af[kk][1], acc[1][2]); acc[1][3] = mfma32(bfr[kk][3], af[kk][1], acc[1][3]);
;     }
;     __builtin_amdgcn_sched_group_barrier(0x100, 12, 0);
;     __builtin_amdgcn_sched_group_barrier(0x010, 6, 0);
;     __builtin_amdgcn_sched_group_barrier(0x008, 16, 0);
;     asm volatile("s_waitcnt vmcnt(6) lgkmcnt(0)" ::: "memory");
;     __builtin_amdgcn_s_barrier();
;     asm volatile("" ::: "memory");
;     s0 = (s0 == 2 * STG) ? 0 : s0 + STG;
;     s2 = (s2 == 2 * STG) ? 0 : s2 + STG;
;   }
;   asm volatile("s_waitcnt vmcnt(0)" ::: "memory");
;   __builtin_amdgcn_s_barrier();
;   asm volatile("" ::: "memory");
;     ...
;   {
;     const int h = lane >> 5, cl = lane & 31;
; #pragma unroll
;     for (int i = 0; i < 2; ++i)
; #pragma unroll
;       for (int j = 0; j < 4; ++j)
; #pragma unroll
;         for (int g = 0; g < 4; ++g) {
;           u32x2 w; w.x = pk2(acc[i][j][4 * g], acc[i][j][4 * g + 1]); w.y = pk2(acc[i][j][4 * g + 2], acc[i][j][4 * g + 3]);
;           *(u32x2*)(smem + (wr * 64 + i * 32 + cl) * 528 + (wc * 128 + j * 32 + 8 * g + 4 * h) * 2) = w;
	ds_read_b128 v[154:157], v226 offset:0
	ds_read_b128 v[182:185], v227 offset:8192
	ds_read_b128 v[178:181], v227 offset:10240
	ds_read_b128 v[158:161], v226 offset:2048
	ds_read_b128 v[174:177], v227 offset:12288
	ds_read_b128 v[170:173], v227 offset:14336
	v_mfma_f32_32x32x16_bf16 v[114:129], v[162:165], v[138:141], v[114:129]
	v_mfma_f32_32x32x16_bf16 v[98:113], v[166:169], v[138:141], v[98:113]
	v_mfma_f32_32x32x16_bf16 v[66:81], v[162:165], v[142:145], v[66:81]
	v_mfma_f32_32x32x16_bf16 v[34:49], v[166:169], v[142:145], v[34:49]
	v_mfma_f32_32x32x16_bf16 v[82:97], v[146:149], v[138:141], v[82:97]
	v_mfma_f32_32x32x16_bf16 v[50:65], v[150:153], v[138:141], v[50:65]
	v_mfma_f32_32x32x16_bf16 v[18:33], v[146:149], v[142:145], v[18:33]
	v_mfma_f32_32x32x16_bf16 v[2:17], v[150:153], v[142:145], v[2:17]
	s_add_i32 s40, s40, 6
	s_cmp_lg_u32 s40, 30
	s_cbranch_scc1 .LBB0_21
	ds_read_b128 v[138:141], v228 offset:0
	ds_read_b128 v[162:165], v229 offset:8192
	ds_read_b128 v[166:169], v229 offset:10240
	ds_read_b128 v[142:145], v228 offset:2048
	ds_read_b128 v[146:149], v229 offset:12288
	ds_read_b128 v[150:153], v229 offset:14336
	s_waitcnt lgkmcnt(6)
	v_mfma_f32_32x32x16_bf16 v[114:129], v[182:185], v[154:157], v[114:129]
	v_mfma_f32_32x32x16_bf16 v[98:113], v[178:181], v[154:157], v[98:113]
	v_mfma_f32_32x32x16_bf16 v[66:81], v[182:185], v[158:161], v[66:81]
	v_mfma_f32_32x32x16_bf16 v[34:49], v[178:181], v[158:161], v[34:49]
	v_mfma_f32_32x32x16_bf16 v[82:97], v[174:177], v[154:157], v[82:97]
	v_mfma_f32_32x32x16_bf16 v[50:65], v[170:173], v[154:157], v[50:65]
	v_mfma_f32_32x32x16_bf16 v[18:33], v[174:177], v[158:161], v[18:33]
	v_mfma_f32_32x32x16_bf16 v[2:17], v[170:173], v[158:161], v[2:17]
	s_waitcnt vmcnt(0) lgkmcnt(0)
	s_barrier
	ds_read_b128 v[154:157], v226 offset:24576
	ds_read_b128 v[182:185], v227 offset:32768
	ds_read_b128 v[178:181], v227 offset:34816
	ds_read_b128 v[158:161], v226 offset:26624
	ds_read_b128 v[174:177], v227 offset:36864
	ds_read_b128 v[170:173], v227 offset:38912
	v_mfma_f32_32x32x16_bf16 v[114:129], v[162:165], v[138:141], v[114:129]
	v_mfma_f32_32x32x16_bf16 v[98:113], v[166:169], v[138:141], v[98:113]
	v_mfma_f32_32x32x16_bf16 v[66:81], v[162:165], v[142:145], v[66:81]
	v_mfma_f32_32x32x16_bf16 v[34:49], v[166:169], v[142:145], v[34:49]
	v_mfma_f32_32x32x16_bf16 v[82:97], v[146:149], v[138:141], v[82:97]
	v_mfma_f32_32x32x16_bf16 v[50:65], v[150:153], v[138:141], v[50:65]
	v_mfma_f32_32x32x16_bf16 v[18:33], v[146:149], v[142:145], v[18:33]
	v_mfma_f32_32x32x16_bf16 v[2:17], v[150:153], v[142:145], v[2:17]
	ds_read_b128 v[138:141], v228 offset:24576
	ds_read_b128 v[162:165], v229 offset:32768
	ds_read_b128 v[166:169], v229 offset:34816
	ds_read_b128 v[142:145], v228 offset:26624
	ds_read_b128 v[146:149], v229 offset:36864
	ds_read_b128 v[150:153], v229 offset:38912
	s_waitcnt lgkmcnt(6)
	v_mfma_f32_32x32x16_bf16 v[114:129], v[182:185], v[154:157], v[114:129]
	v_mfma_f32_32x32x16_bf16 v[98:113], v[178:181], v[154:157], v[98:113]
	v_mfma_f32_32x32x16_bf16 v[66:81], v[182:185], v[158:161], v[66:81]
	v_mfma_f32_32x32x16_bf16 v[34:49], v[178:181], v[158:161], v[34:49]
	v_mfma_f32_32x32x16_bf16 v[82:97], v[174:177], v[154:157], v[82:97]
	v_mfma_f32_32x32x16_bf16 v[50:65], v[170:173], v[154:157], v[50:65]
	v_mfma_f32_32x32x16_bf16 v[18:33], v[174:177], v[158:161], v[18:33]
	v_mfma_f32_32x32x16_bf16 v[2:17], v[170:173], v[158:161], v[2:17]
	s_waitcnt lgkmcnt(0)
	v_mfma_f32_32x32x16_bf16 v[114:129], v[162:165], v[138:141], v[114:129]
	v_mfma_f32_32x32x16_bf16 v[98:113], v[166:169], v[138:141], v[98:113]
	v_mfma_f32_32x32x16_bf16 v[66:81], v[162:165], v[142:145], v[66:81]
	v_mfma_f32_32x32x16_bf16 v[34:49], v[166:169], v[142:145], v[34:49]
	v_mfma_f32_32x32x16_bf16 v[82:97], v[146:149], v[138:141], v[82:97]
	v_mfma_f32_32x32x16_bf16 v[50:65], v[150:153], v[138:141], v[50:65]
	v_mfma_f32_32x32x16_bf16 v[18:33], v[146:149], v[142:145], v[18:33]
	v_mfma_f32_32x32x16_bf16 v[2:17], v[150:153], v[142:145], v[2:17]
	s_waitcnt lgkmcnt(0)
	s_mov_b32 s101, 0
	s_mov_b32 s71, 0
	s_setprio 0
	v_mul_lo_u32 v0, v197, s55
	v_add_u32_e32 v0, 16, v0
	s_nop 1
	v_cvt_pk_bf16_f32 v114, v114, v115
	v_cvt_pk_bf16_f32 v115, v116, v117
	v_lshlrev_b32_e32 v116, 3, v196
	s_lshl_b32 s10, s28, 1
	v_add3_u32 v0, v0, v116, s10
	v_cvt_pk_bf16_f32 v116, v118, v119
	v_cvt_pk_bf16_f32 v117, v120, v121
	v_cvt_pk_bf16_f32 v98, v98, v99
	v_cvt_pk_bf16_f32 v99, v100, v101
	v_cvt_pk_bf16_f32 v100, v102, v103
	v_cvt_pk_bf16_f32 v101, v104, v105
	v_cvt_pk_bf16_f32 v82, v82, v83
	v_cvt_pk_bf16_f32 v83, v84, v85
	v_cvt_pk_bf16_f32 v84, v86, v87
	v_cvt_pk_bf16_f32 v85, v88, v89
	v_cvt_pk_bf16_f32 v50, v50, v51
	v_cvt_pk_bf16_f32 v51, v52, v53
	v_cvt_pk_bf16_f32 v52, v54, v55
	v_cvt_pk_bf16_f32 v53, v56, v57
	s_waitcnt vmcnt(0)
	s_barrier
; DI unsigned pk2(float a, float b) { f32x2 v = {a, b}; bf2_t r = __builtin_convertvector(v, bf2_t); return __builtin_bit_cast(unsigned, r); }
;     ...
;   {
;     const int h = lane >> 5, cl = lane & 31;
; #pragma unroll
;     for (int i = 0; i < 2; ++i)
; #pragma unroll
;       for (int j = 0; j < 4; ++j)
; #pragma unroll
;         for (int g = 0; g < 4; ++g) {
;           u32x2 w; w.x = pk2(acc[i][j][4 * g], acc[i][j][4 * g + 1]); w.y = pk2(acc[i][j][4 * g + 2], acc[i][j][4 * g + 3]);
;           *(u32x2*)(smem + (wr * 64 + i * 32 + cl) * 528 + (wc * 128 + j * 32 + 8 * g + 4 * h) * 2) = w;
;         }
;   }
;   __syncthreads();
	ds_write2_b64 v0, v[114:115], v[116:117] offset1:2
	v_cvt_pk_bf16_f32 v114, v122, v123
	v_cvt_pk_bf16_f32 v115, v124, v125
	v_cvt_pk_bf16_f32 v116, v126, v127
	v_cvt_pk_bf16_f32 v117, v128, v129
	ds_write2_b64 v0, v[98:99], v[100:101] offset0:8 offset1:10
	v_cvt_pk_bf16_f32 v98, v106, v107
	v_cvt_pk_bf16_f32 v99, v108, v109
	v_cvt_pk_bf16_f32 v100, v110, v111
	v_cvt_pk_bf16_f32 v101, v112, v113
	ds_write2_b64 v0, v[82:83], v[84:85] offset0:16 offset1:18
	v_cvt_pk_bf16_f32 v82, v90, v91
	v_cvt_pk_bf16_f32 v83, v92, v93
	v_cvt_pk_bf16_f32 v84, v94, v95
	v_cvt_pk_bf16_f32 v85, v96, v97
	ds_write2_b64 v0, v[50:51], v[52:53] offset0:24 offset1:26
	v_cvt_pk_bf16_f32 v50, v58, v59
	v_cvt_pk_bf16_f32 v51, v60, v61
	v_cvt_pk_bf16_f32 v52, v62, v63
	v_cvt_pk_bf16_f32 v53, v64, v65
	ds_write2_b64 v0, v[114:115], v[116:117] offset0:4 offset1:6
	ds_write2_b64 v0, v[98:99], v[100:101] offset0:12 offset1:14
	ds_write2_b64 v0, v[82:83], v[84:85] offset0:20 offset1:22
	ds_write2_b64 v0, v[50:51], v[52:53] offset0:28 offset1:30
	v_cvt_pk_bf16_f32 v50, v66, v67
	v_cvt_pk_bf16_f32 v51, v68, v69
	v_cvt_pk_bf16_f32 v52, v70, v71
	v_cvt_pk_bf16_f32 v53, v72, v73
	v_add_u32_e32 v0, 0x4000, v0
	v_cvt_pk_bf16_f32 v34, v34, v35
	v_cvt_pk_bf16_f32 v35, v36, v37
	v_cvt_pk_bf16_f32 v36, v38, v39
	v_cvt_pk_bf16_f32 v37, v40, v41
	v_cvt_pk_bf16_f32 v18, v18, v19
	v_cvt_pk_bf16_f32 v19, v20, v21
	v_cvt_pk_bf16_f32 v20, v22, v23
	v_cvt_pk_bf16_f32 v21, v24, v25
	v_cvt_pk_bf16_f32 v2, v2, v3
	v_cvt_pk_bf16_f32 v3, v4, v5
	v_cvt_pk_bf16_f32 v4, v6, v7
	v_cvt_pk_bf16_f32 v5, v8, v9
	ds_write2_b64 v0, v[50:51], v[52:53] offset0:64 offset1:66
	v_cvt_pk_bf16_f32 v50, v74, v75
	v_cvt_pk_bf16_f32 v51, v76, v77
	v_cvt_pk_bf16_f32 v52, v78, v79
	v_cvt_pk_bf16_f32 v53, v80, v81
	ds_write2_b64 v0, v[34:35], v[36:37] offset0:72 offset1:74
	v_cvt_pk_bf16_f32 v34, v42, v43
	v_cvt_pk_bf16_f32 v35, v44, v45
	v_cvt_pk_bf16_f32 v36, v46, v47
	v_cvt_pk_bf16_f32 v37, v48, v49
	ds_write2_b64 v0, v[18:19], v[20:21] offset0:80 offset1:82
	v_cvt_pk_bf16_f32 v18, v26, v27
	v_cvt_pk_bf16_f32 v19, v28, v29
	v_cvt_pk_bf16_f32 v20, v30, v31
	v_cvt_pk_bf16_f32 v21, v32, v33
	ds_write2_b64 v0, v[2:3], v[4:5] offset0:88 offset1:90
	v_cvt_pk_bf16_f32 v2, v10, v11
	v_cvt_pk_bf16_f32 v3, v12, v13
	v_cvt_pk_bf16_f32 v4, v14, v15
	v_cvt_pk_bf16_f32 v5, v16, v17
	s_lshl_b64 s[14:15], s[14:15], 1
	ds_write2_b64 v0, v[50:51], v[52:53] offset0:68 offset1:70
	ds_write2_b64 v0, v[34:35], v[36:37] offset0:76 offset1:78
	ds_write2_b64 v0, v[18:19], v[20:21] offset0:84 offset1:86
	ds_write2_b64 v0, v[2:3], v[4:5] offset0:92 offset1:94
	s_waitcnt vmcnt(0) lgkmcnt(0)
	s_barrier
; #define GAS __attribute__((address_space(1)))
;     ...
;   if (EPI == 0) {
; #pragma unroll
;     for (int i = 0; i < 16; ++i) {
;       const int id = tid2 + 256 * i, r = id >> 5, c8 = (id & 31) * 8;
;       const u32x4 v = *(const u32x4*)(smem + r * 528 + c8 * 2);
;       *(GAS u32x4*)(ea.out + (size_t)(m0 + r) * ea.ldo + n0 + c8) = v;
;     }
	s_add_u32 s14, s19, s14
	v_lshlrev_b32_e32 v0, 4, v189
	v_and_b32_e32 v0, 0x1f0, v0
	s_addc_u32 s15, s20, s15
	v_add_u32_e32 v10, 16, v0
	v_lshl_add_u64 v[12:13], s[14:15], 0, v[0:1]
	v_ashrrev_i32_e32 v0, 5, v189
	v_mad_u64_u32 v[2:3], s[14:15], v0, s55, v[10:11]
	ds_read_b128 v[2:5], v2
	v_add_u32_e32 v6, s12, v0
	v_ashrrev_i32_e32 v7, 31, v6
	v_add_u32_e32 v0, 0x100, v189
	v_lshlrev_b64 v[6:7], 11, v[6:7]
	v_ashrrev_i32_e32 v0, 5, v0
	v_lshl_add_u64 v[14:15], v[12:13], 0, v[6:7]
	v_mad_u64_u32 v[6:7], s[14:15], v0, s55, v[10:11]
	ds_read_b128 v[6:9], v6
	s_waitcnt lgkmcnt(1)
	global_store_dwordx4 v[14:15], v[2:5], off nt
	v_readlane_b32 s10, v252, 12
	s_add_i32 s23, s23, s10
	v_add_u32_e32 v2, s12, v0
	v_ashrrev_i32_e32 v3, 31, v2
	v_lshlrev_b64 v[2:3], 11, v[2:3]
	v_add_u32_e32 v0, 0x200, v189
	v_lshl_add_u64 v[2:3], v[12:13], 0, v[2:3]
	v_ashrrev_i32_e32 v0, 5, v0
	s_waitcnt lgkmcnt(0)
	global_store_dwordx4 v[2:3], v[6:9], off nt
	v_mad_u64_u32 v[2:3], s[14:15], v0, s55, v[10:11]
	ds_read_b128 v[2:5], v2
	v_add_u32_e32 v6, s12, v0
	v_ashrrev_i32_e32 v7, 31, v6
	v_add_u32_e32 v0, 0x300, v189
	v_lshlrev_b64 v[6:7], 11, v[6:7]
	v_ashrrev_i32_e32 v0, 5, v0
	v_lshl_add_u64 v[14:15], v[12:13], 0, v[6:7]
	v_mad_u64_u32 v[6:7], s[14:15], v0, s55, v[10:11]
	ds_read_b128 v[6:9], v6
	s_waitcnt lgkmcnt(1)
	global_store_dwordx4 v[14:15], v[2:5], off nt
	s_cmp_ge_i32 s23, s16
	s_nop 0
	v_add_u32_e32 v2, s12, v0
	v_ashrrev_i32_e32 v3, 31, v2
	v_lshlrev_b64 v[2:3], 11, v[2:3]
	v_add_u32_e32 v0, 0x400, v189
	v_lshl_add_u64 v[2:3], v[12:13], 0, v[2:3]
	v_ashrrev_i32_e32 v0, 5, v0
	s_waitcnt lgkmcnt(0)
	global_store_dwordx4 v[2:3], v[6:9], off nt
	v_mad_u64_u32 v[2:3], s[14:15], v0, s55, v[10:11]
	ds_read_b128 v[2:5], v2
	v_add_u32_e32 v6, s12, v0
	v_ashrrev_i32_e32 v7, 31, v6
	v_add_u32_e32 v0, 0x500, v189
	v_lshlrev_b64 v[6:7], 11, v[6:7]
	v_ashrrev_i32_e32 v0, 5, v0
	v_lshl_add_u64 v[14:15], v[12:13], 0, v[6:7]
	v_mad_u64_u32 v[6:7], s[14:15], v0, s55, v[10:11]
	ds_read_b128 v[6:9], v6
	s_waitcnt lgkmcnt(1)
	global_store_dwordx4 v[14:15], v[2:5], off nt
	s_nop 1
	v_add_u32_e32 v2, s12, v0
	v_ashrrev_i32_e32 v3, 31, v2
	v_lshlrev_b64 v[2:3], 11, v[2:3]
	v_add_u32_e32 v0, 0x600, v189
	v_lshl_add_u64 v[2:3], v[12:13], 0, v[2:3]
	v_ashrrev_i32_e32 v0, 5, v0
	s_waitcnt lgkmcnt(0)
	global_store_dwordx4 v[2:3], v[6:9], off nt
	v_mad_u64_u32 v[2:3], s[14:15], v0, s55, v[10:11]
	ds_read_b128 v[2:5], v2
	v_add_u32_e32 v6, s12, v0
	v_ashrrev_i32_e32 v7, 31, v6
	v_add_u32_e32 v0, 0x700, v189
	v_lshlrev_b64 v[6:7], 11, v[6:7]
	v_ashrrev_i32_e32 v0, 5, v0
	v_lshl_add_u64 v[14:15], v[12:13], 0, v[6:7]
	v_mad_u64_u32 v[6:7], s[14:15], v0, s55, v[10:11]
	ds_read_b128 v[6:9], v6
	s_waitcnt lgkmcnt(1)
	global_store_dwordx4 v[14:15], v[2:5], off nt
	s_nop 1
	v_add_u32_e32 v2, s12, v0
	v_ashrrev_i32_e32 v3, 31, v2
	v_lshlrev_b64 v[2:3], 11, v[2:3]
	v_add_u32_e32 v0, 0x800, v189
	v_lshl_add_u64 v[2:3], v[12:13], 0, v[2:3]
	v_ashrrev_i32_e32 v0, 5, v0
	s_waitcnt lgkmcnt(0)
	global_store_dwordx4 v[2:3], v[6:9], off nt
	v_mad_u64_u32 v[2:3], s[14:15], v0, s55, v[10:11]
	ds_read_b128 v[2:5], v2
	v_add_u32_e32 v6, s12, v0
	v_ashrrev_i32_e32 v7, 31, v6
	v_add_u32_e32 v0, 0x900, v189
	v_lshlrev_b64 v[6:7], 11, v[6:7]
	v_ashrrev_i32_e32 v0, 5, v0
	v_lshl_add_u64 v[14:15], v[12:13], 0, v[6:7]
	v_mad_u64_u32 v[6:7], s[14:15], v0, s55, v[10:11]
	ds_read_b128 v[6:9], v6
	s_waitcnt lgkmcnt(1)
	global_store_dwordx4 v[14:15], v[2:5], off nt
	s_nop 1
	v_add_u32_e32 v2, s12, v0
	v_ashrrev_i32_e32 v3, 31, v2
	v_lshlrev_b64 v[2:3], 11, v[2:3]
	v_add_u32_e32 v0, 0xa00, v189
	v_lshl_add_u64 v[2:3], v[12:13], 0, v[2:3]
	v_ashrrev_i32_e32 v0, 5, v0
	s_waitcnt lgkmcnt(0)
	global_store_dwordx4 v[2:3], v[6:9], off nt
	v_mad_u64_u32 v[2:3], s[14:15], v0, s55, v[10:11]
	ds_read_b128 v[2:5], v2
	v_add_u32_e32 v6, s12, v0
	v_ashrrev_i32_e32 v7, 31, v6
	v_add_u32_e32 v0, 0xb00, v189
	v_lshlrev_b64 v[6:7], 11, v[6:7]
	v_ashrrev_i32_e32 v0, 5, v0
	v_lshl_add_u64 v[14:15], v[12:13], 0, v[6:7]
	v_mad_u64_u32 v[6:7], s[14:15], v0, s55, v[10:11]
	ds_read_b128 v[6:9], v6
	s_waitcnt lgkmcnt(1)
	global_store_dwordx4 v[14:15], v[2:5], off nt
	s_nop 1
	v_add_u32_e32 v2, s12, v0
	v_ashrrev_i32_e32 v3, 31, v2
	v_lshlrev_b64 v[2:3], 11, v[2:3]
	v_add_u32_e32 v0, 0xc00, v189
	v_lshl_add_u64 v[2:3], v[12:13], 0, v[2:3]
	v_ashrrev_i32_e32 v0, 5, v0
	s_waitcnt lgkmcnt(0)
	global_store_dwordx4 v[2:3], v[6:9], off nt
	v_mad_u64_u32 v[2:3], s[14:15], v0, s55, v[10:11]
	ds_read_b128 v[2:5], v2
	v_add_u32_e32 v6, s12, v0
	v_ashrrev_i32_e32 v7, 31, v6
	v_add_u32_e32 v0, 0xd00, v189
	v_lshlrev_b64 v[6:7], 11, v[6:7]
	v_ashrrev_i32_e32 v0, 5, v0
	v_lshl_add_u64 v[14:15], v[12:13], 0, v[6:7]
	v_mad_u64_u32 v[6:7], s[14:15], v0, s55, v[10:11]
	ds_read_b128 v[6:9], v6
	s_waitcnt lgkmcnt(1)
	global_store_dwordx4 v[14:15], v[2:5], off nt
	s_nop 1
	v_add_u32_e32 v2, s12, v0
	v_ashrrev_i32_e32 v3, 31, v2
	v_lshlrev_b64 v[2:3], 11, v[2:3]
	v_add_u32_e32 v0, 0xe00, v189
	v_lshl_add_u64 v[2:3], v[12:13], 0, v[2:3]
	v_ashrrev_i32_e32 v0, 5, v0
	s_waitcnt lgkmcnt(0)
	global_store_dwordx4 v[2:3], v[6:9], off nt
	v_mad_u64_u32 v[2:3], s[14:15], v0, s55, v[10:11]
	ds_read_b128 v[2:5], v2
	v_add_u32_e32 v6, s12, v0
	v_ashrrev_i32_e32 v7, 31, v6
	v_add_u32_e32 v0, 0xf00, v189
	v_lshlrev_b64 v[6:7], 11, v[6:7]
	v_ashrrev_i32_e32 v0, 5, v0
	v_lshl_add_u64 v[14:15], v[12:13], 0, v[6:7]
	v_mad_u64_u32 v[6:7], s[14:15], v0, s55, v[10:11]
	ds_read_b128 v[6:9], v6
	s_waitcnt lgkmcnt(1)
	global_store_dwordx4 v[14:15], v[2:5], off nt
	s_nop 1
	v_add_u32_e32 v2, s12, v0
	v_ashrrev_i32_e32 v3, 31, v2
	v_lshlrev_b64 v[2:3], 11, v[2:3]
	v_lshl_add_u64 v[2:3], v[12:13], 0, v[2:3]
	s_waitcnt lgkmcnt(0)
	global_store_dwordx4 v[2:3], v[6:9], off nt
	s_barrier
	s_cbranch_scc0 .LBB0_20

; #define LAS __attribute__((address_space(3)))
;     ...
;   const int lane = tid & 63, wid = __builtin_amdgcn_readfirstlane(tid >> 6), wr = wid >> 1, wc = wid & 1;
;   const int m0 = mt * 128, n0 = nt * 256;
;   const int r = lane & 31, h = lane >> 5, key = (r >> 2) & 3;
;   constexpr int STG = 24576;
;   const int rowl = lane >> 2, cch = (lane & 3) ^ ((lane >> 4) & 3);
;   const unsigned voffA = (unsigned)(rowl * lda * 2 + cch * 16), voffB = (unsigned)(rowl * K * 2 + cch * 16);
;   const char* Abase = (const char*)(A + (size_t)m0 * lda) + (size_t)(wid * 2) * 32 * lda;
;   const char* Bbase = (const char*)(Bt + (size_t)n0 * K) + (size_t)(wid * 4) * 32 * K;
;   const size_t ablk = (size_t)32 * lda, bblk = (size_t)32 * K;
;   LAS char* lds = (LAS char*)smem;
;   LAS char* ldsA = lds + (wid * 2) * 1024;
;   LAS char* ldsB = lds + 8192 + (wid * 4) * 1024;
;     ...
;   const int x0 = ((0 + h) ^ key) * 16, x1 = ((2 + h) ^ key) * 16;
;   const int a_rd = (wr * 64 + r) * 64, b_rd = 8192 + (wc * 128 + r) * 64;
;   f32x16 acc[2][4];
; #pragma unroll
;   for (int i = 0; i < 2; ++i)
; #pragma unroll
;     for (int j = 0; j < 4; ++j)
; #pragma unroll
;       for (int e = 0; e < 16; ++e) acc[i][j][e] = 0.f;
;   const int nk = K >> 5;
;   DMA_STEP_(0, 0);
;   DMA_STEP_(1, STG);
;   asm volatile("s_waitcnt vmcnt(6)" ::: "memory");
;   __builtin_amdgcn_s_barrier();
;   asm volatile("" ::: "memory");
;   int s0 = 0, s2 = 2 * STG;
.LBB0_183:
	s_mul_hi_i32 s10, s20, 0x38e38e39
	s_lshr_b32 s11, s10, 31
	s_ashr_i32 s10, s10, 4
	v_mov_b32_e32 v189, v188
	s_add_i32 s10, s10, s11
	v_readlane_b32 s12, v252, 18
	s_mul_i32 s11, s10, 0xffffffb8
	v_readfirstlane_b32 s21, v189
	s_lshl_b32 s10, s10, s12
	v_readlane_b32 s12, v252, 41
	s_ashr_i32 s44, s21, 6
	s_add_i32 s10, s10, s12
	s_lshl_b32 s12, s20, 7
	s_lshl_b32 s22, s44, 1
	s_add_i32 s11, s11, s20
	s_lshl_b32 s10, s10, 10
	s_and_b32 s12, s12, 0x380
	s_ashr_i32 s23, s22, 31
	s_or_b32 s12, s10, s12
	s_lshl_b32 s10, s11, 5
	s_lshl_b64 s[28:29], s[22:23], 10
	s_lshl_b32 s22, s44, 2
	s_ashr_i32 s11, s21, 1
	s_and_b32 s14, s10, 0xffffff00
	v_and_b32_e32 v0, 31, v189
	s_ashr_i32 s23, s22, 31
	s_lshl_b32 s10, s44, 12
	s_andn2_b32 s11, s11, 63
	v_lshlrev_b32_e32 v2, 4, v189
	s_ashr_i32 s13, s12, 31
	s_lshl_b64 s[40:41], s[22:23], 10
	s_add_i32 s22, s10, 16
	v_or_b32_e32 v197, s11, v0
	s_lshl_b32 s11, s44, 7
	v_bitop3_b32 v2, v2, 48, v189 bitop3:0x48
	v_lshlrev_b32_e32 v3, 9, v189
	s_ashr_i32 s15, s14, 31
	s_add_i32 s10, s22, 0x2000
	s_and_b32 s21, s11, 0x80
	s_movk_i32 s11, 0x7800
	s_lshl_b64 s[42:43], s[12:13], 6
	v_or_b32_e32 v4, s21, v0
	v_and_or_b32 v0, v3, s11, v2
	v_lshlrev_b32_e32 v10, 4, v189
	v_and_b32_e32 v10, 0x3c0, v10
	v_or_b32_e32 v10, v10, v2
	v_mov_b32_e32 v11, 0
	s_add_u32 s11, s18, s42
	s_addc_u32 s13, s19, s43
	s_add_u32 s28, s11, s28
	s_addc_u32 s29, s13, s29
	s_lshl_b64 s[42:43], s[14:15], 6
	v_readlane_b32 s46, v250, 18
	v_readlane_b32 s47, v250, 19
	s_add_u32 s11, s46, s42
	s_addc_u32 s13, s47, s43
	s_add_u32 s40, s11, s40
	s_addc_u32 s41, s13, s41
	s_lshl_b32 s11, s44, 11
	s_sub_i32 s13, s22, s11
	v_lshl_add_u64 v[192:193], s[28:29], 0, v[10:11]
	s_mov_b32 m0, s13
	s_nop 0
	global_load_lds_dwordx4 v[192:193], off
	global_load_lds_dwordx4 v[192:193], off offset:1024
	v_lshl_add_u64 v[194:195], s[40:41], 0, v[10:11]
	s_mov_b32 m0, s10
	s_nop 0
	global_load_lds_dwordx4 v[194:195], off
	global_load_lds_dwordx4 v[194:195], off offset:1024
	global_load_lds_dwordx4 v[194:195], off offset:2048
	global_load_lds_dwordx4 v[194:195], off offset:3072
	s_mov_b64 s[10:11], 0x10000
	s_mov_b64 s[10:11], 0x18000
	s_mov_b64 s[10:11], 0x8040
	s_add_i32 m0, s13, 0x6000
	s_mov_b32 vcc_lo, 0x480000
	s_mov_b32 vcc_hi, 0
	v_lshl_add_u64 v[2:3], v[192:193], 0, vcc
	global_load_lds_dwordx4 v[2:3], off
	global_load_lds_dwordx4 v[2:3], off offset:1024
	v_bfe_u32 v196, v189, 5, 1
	s_add_i32 m0, s22, 0x8000
	s_mov_b32 s100, 0x24000
	v_lshl_add_u64 v[2:3], v[194:195], 0, s[100:101]
	global_load_lds_dwordx4 v[2:3], off
	global_load_lds_dwordx4 v[2:3], off offset:1024
	global_load_lds_dwordx4 v[2:3], off offset:2048
	global_load_lds_dwordx4 v[2:3], off offset:3072
	s_mov_b64 s[10:11], 0x10040
	s_mov_b64 s[10:11], 0x18040
	v_lshlrev_b32_e32 v218, 6, v4
	v_bfe_u32 v4, v189, 2, 2
	v_lshrrev_b32_e32 v5, 5, v189
	s_lshl_b32 s100, s100, 1
	v_lshl_add_u64 v[194:195], v[194:195], 0, s[100:101]
	s_lshl_b32 vcc_lo, vcc_lo, 1
	v_lshl_add_u64 v[192:193], v[192:193], 0, vcc
	s_waitcnt vmcnt(6)
	s_barrier
	v_bitop3_b32 v2, v196, v4, 2 bitop3:0x36
	v_bitop3_b32 v0, v5, v4, 1 bitop3:0x6c
	v_lshlrev_b32_e32 v220, 4, v2
	v_mov_b32_e32 v2, 0
	v_lshlrev_b32_e32 v219, 6, v197
	v_lshlrev_b32_e32 v0, 4, v0
	s_mov_b32 s28, 0xc000
	s_mov_b32 s23, 0
	s_mov_b32 s29, 0
	v_mov_b32_e32 v3, v2
	v_mov_b32_e32 v4, v2
	v_mov_b32_e32 v5, v2
	v_mov_b32_e32 v6, v2
	v_mov_b32_e32 v7, v2
	v_mov_b32_e32 v8, v2
	v_mov_b32_e32 v9, v2
	v_mov_b32_e32 v10, v2
	v_mov_b32_e32 v11, v2
	v_mov_b32_e32 v12, v2
	v_mov_b32_e32 v13, v2
	v_mov_b32_e32 v14, v2
	v_mov_b32_e32 v15, v2
	v_mov_b32_e32 v16, v2
	v_mov_b32_e32 v17, v2
	v_mov_b32_e32 v18, v2
	v_mov_b32_e32 v19, v2
	v_mov_b32_e32 v20, v2
	v_mov_b32_e32 v21, v2
	v_mov_b32_e32 v22, v2
	v_mov_b32_e32 v23, v2
	v_mov_b32_e32 v24, v2
	v_mov_b32_e32 v25, v2
	v_mov_b32_e32 v26, v2
	v_mov_b32_e32 v27, v2
	v_mov_b32_e32 v28, v2
	v_mov_b32_e32 v29, v2
	v_mov_b32_e32 v30, v2
	v_mov_b32_e32 v31, v2
	v_mov_b32_e32 v32, v2
	v_mov_b32_e32 v33, v2
	v_mov_b32_e32 v50, v2
	v_mov_b32_e32 v51, v2
	v_mov_b32_e32 v52, v2
	v_mov_b32_e32 v53, v2
	v_mov_b32_e32 v54, v2
	v_mov_b32_e32 v55, v2
	v_mov_b32_e32 v56, v2
	v_mov_b32_e32 v57, v2
	v_mov_b32_e32 v58, v2
	v_mov_b32_e32 v59, v2
	v_mov_b32_e32 v60, v2
	v_mov_b32_e32 v61, v2
	v_mov_b32_e32 v62, v2
	v_mov_b32_e32 v63, v2
	v_mov_b32_e32 v64, v2
	v_mov_b32_e32 v65, v2
	v_mov_b32_e32 v82, v2
	v_mov_b32_e32 v83, v2
	v_mov_b32_e32 v84, v2
	v_mov_b32_e32 v85, v2
	v_mov_b32_e32 v86, v2
	v_mov_b32_e32 v87, v2
	v_mov_b32_e32 v88, v2
	v_mov_b32_e32 v89, v2
	v_mov_b32_e32 v90, v2
	v_mov_b32_e32 v91, v2
	v_mov_b32_e32 v92, v2
	v_mov_b32_e32 v93, v2
	v_mov_b32_e32 v94, v2
	v_mov_b32_e32 v95, v2
	v_mov_b32_e32 v96, v2
	v_mov_b32_e32 v97, v2
	v_mov_b32_e32 v34, v2
	v_mov_b32_e32 v35, v2
	v_mov_b32_e32 v36, v2
	v_mov_b32_e32 v37, v2
	v_mov_b32_e32 v38, v2
	v_mov_b32_e32 v39, v2
	v_mov_b32_e32 v40, v2
	v_mov_b32_e32 v41, v2
	v_mov_b32_e32 v42, v2
	v_mov_b32_e32 v43, v2
	v_mov_b32_e32 v44, v2
	v_mov_b32_e32 v45, v2
	v_mov_b32_e32 v46, v2
	v_mov_b32_e32 v47, v2
	v_mov_b32_e32 v48, v2
	v_mov_b32_e32 v49, v2
	v_mov_b32_e32 v66, v2
	v_mov_b32_e32 v67, v2
	v_mov_b32_e32 v68, v2
	v_mov_b32_e32 v69, v2
	v_mov_b32_e32 v70, v2
	v_mov_b32_e32 v71, v2
	v_mov_b32_e32 v72, v2
	v_mov_b32_e32 v73, v2
	v_mov_b32_e32 v74, v2
	v_mov_b32_e32 v75, v2
	v_mov_b32_e32 v76, v2
	v_mov_b32_e32 v77, v2
	v_mov_b32_e32 v78, v2
	v_mov_b32_e32 v79, v2
	v_mov_b32_e32 v80, v2
	v_mov_b32_e32 v81, v2
	v_mov_b32_e32 v98, v2
	v_mov_b32_e32 v99, v2
	v_mov_b32_e32 v100, v2
	v_mov_b32_e32 v101, v2
	v_mov_b32_e32 v102, v2
	v_mov_b32_e32 v103, v2
	v_mov_b32_e32 v104, v2
	v_mov_b32_e32 v105, v2
	v_mov_b32_e32 v106, v2
	v_mov_b32_e32 v107, v2
	v_mov_b32_e32 v108, v2
	v_mov_b32_e32 v109, v2
	v_mov_b32_e32 v110, v2
	v_mov_b32_e32 v111, v2
	v_mov_b32_e32 v112, v2
	v_mov_b32_e32 v113, v2
	v_mov_b32_e32 v114, v2
	v_mov_b32_e32 v115, v2
	v_mov_b32_e32 v116, v2
	v_mov_b32_e32 v117, v2
	v_mov_b32_e32 v118, v2
	v_mov_b32_e32 v119, v2
	v_mov_b32_e32 v120, v2
	v_mov_b32_e32 v121, v2
	v_mov_b32_e32 v122, v2
	v_mov_b32_e32 v123, v2
	v_mov_b32_e32 v124, v2
	v_mov_b32_e32 v125, v2
	v_mov_b32_e32 v126, v2
	v_mov_b32_e32 v127, v2
	v_mov_b32_e32 v128, v2
	v_mov_b32_e32 v129, v2
	v_readfirstlane_b32 vcc_lo, v192
	v_readfirstlane_b32 vcc_hi, v193
	v_readfirstlane_b32 s100, v194
	v_readfirstlane_b32 s101, v195
	s_sub_u32 vcc_lo, vcc_lo, 0x100000
	s_subb_u32 vcc_hi, vcc_hi, 0
	s_sub_u32 s100, s100, 0x100000
	s_subb_u32 s101, s101, 0
	v_subrev_u32_e32 v238, vcc_lo, v192
	v_subrev_u32_e32 v239, s100, v194
	v_add3_u32 v226, v219, v0, 16
	v_add3_u32 v227, v218, v0, 16
	v_add3_u32 v228, v219, v220, 16
	v_add3_u32 v229, v218, v220, 16
	ds_read_b128 v[154:157], v226 offset:0
	ds_read_b128 v[182:185], v227 offset:8192
	ds_read_b128 v[178:181], v227 offset:10240
	ds_read_b128 v[158:161], v226 offset:2048
	ds_read_b128 v[174:177], v227 offset:12288
	ds_read_b128 v[170:173], v227 offset:14336
	s_setprio 1
; #define LAS __attribute__((address_space(3)))
; DI f32x16 mfma32(bf16x8 a, bf16x8 b, f32x16 c) { return __builtin_amdgcn_mfma_f32_32x32x16_bf16(a, b, c, 0, 0, 0); }
;     ...
;   for (int kt = 0; kt < nk; ++kt) {
;     const int kn = (kt + 2 < nk) ? (kt + 2) : (nk - 1);
;     const LAS char* cur = lds + s0;
;     bf16x8 af[2][2], bfr[2][4];
; #pragma unroll
;     for (int kk = 0; kk < 2; ++kk) {
;       const int xo = kk ? x1 : x0;
;       af[kk][0] = *(const LAS bf16x8*)(cur + a_rd + xo);
;       bfr[kk][0] = *(const LAS bf16x8*)(cur + b_rd + xo);
;       bfr[kk][1] = *(const LAS bf16x8*)(cur + b_rd + 2048 + xo);
;       af[kk][1] = *(const LAS bf16x8*)(cur + a_rd + 2048 + xo);
;       bfr[kk][2] = *(const LAS bf16x8*)(cur + b_rd + 4096 + xo);
;       bfr[kk][3] = *(const LAS bf16x8*)(cur + b_rd + 6144 + xo);
;     }
;     DMA_STEP_(kn, s2);
; #pragma unroll
;     for (int kk = 0; kk < 2; ++kk) {
;       acc[0][0] = mfma32(bfr[kk][0], af[kk][0], acc[0][0]); acc[0][1] = mfma32(bfr[kk][1], af[kk][0], acc[0][1]);
;       acc[1][0] = mfma32(bfr[kk][0], af[kk][1], acc[1][0]); acc[1][1] = mfma32(bfr[kk][1], af[kk][1], acc[1][1]);
;       acc[0][2] = mfma32(bfr[kk][2], af[kk][0], acc[0][2]); acc[0][3] = mfma32(bfr[kk][3], af[kk][0], acc[0][3]);
;       acc[1][2] = mfma32(bfr[kk][2], af[kk][1], acc[1][2]); acc[1][3] = mfma32(bfr[kk][3], af[kk][1], acc[1][3]);
;     }
;     __builtin_amdgcn_sched_group_barrier(0x100, 12, 0);
;     __builtin_amdgcn_sched_group_barrier(0x010, 6, 0);
;     __builtin_amdgcn_sched_group_barrier(0x008, 16, 0);
;     asm volatile("s_waitcnt vmcnt(6) lgkmcnt(0)" ::: "memory");
;     __builtin_amdgcn_s_barrier();
;     asm volatile("" ::: "memory");
;     s0 = (s0 == 2 * STG) ? 0 : s0 + STG;
;     s2 = (s2 == 2 * STG) ? 0 : s2 + STG;
;   }
.LBB0_184:
	ds_read_b128 v[138:141], v228 offset:0
	ds_read_b128 v[162:165], v229 offset:8192
	ds_read_b128 v[166:169], v229 offset:10240
	ds_read_b128 v[142:145], v228 offset:2048
	ds_read_b128 v[146:149], v229 offset:12288
	ds_read_b128 v[150:153], v229 offset:14336
	s_add_i32 m0, s13, 0xc000
	s_waitcnt lgkmcnt(6)
	v_mfma_f32_32x32x16_bf16 v[114:129], v[182:185], v[154:157], v[114:129]
	global_load_lds_dwordx4 v238, vcc
	v_mfma_f32_32x32x16_bf16 v[98:113], v[178:181], v[154:157], v[98:113]
	global_load_lds_dwordx4 v238, vcc offset:1024
	s_add_i32 m0, s22, 0xe000
	s_add_u32 vcc_lo, vcc_lo, 0x480000
	s_addc_u32 vcc_hi, vcc_hi, 0
	v_mfma_f32_32x32x16_bf16 v[66:81], v[182:185], v[158:161], v[66:81]
	global_load_lds_dwordx4 v239, s[100:101]
	v_mfma_f32_32x32x16_bf16 v[34:49], v[178:181], v[158:161], v[34:49]
	global_load_lds_dwordx4 v239, s[100:101] offset:1024
	v_mfma_f32_32x32x16_bf16 v[82:97], v[174:177], v[154:157], v[82:97]
	global_load_lds_dwordx4 v239, s[100:101] offset:2048
	v_mfma_f32_32x32x16_bf16 v[50:65], v[170:173], v[154:157], v[50:65]
	global_load_lds_dwordx4 v239, s[100:101] offset:3072
	s_add_u32 s100, s100, 0x24000
	s_addc_u32 s101, s101, 0
	v_mfma_f32_32x32x16_bf16 v[18:33], v[174:177], v[158:161], v[18:33]
	v_mfma_f32_32x32x16_bf16 v[2:17], v[170:173], v[158:161], v[2:17]
	s_waitcnt vmcnt(6) lgkmcnt(0)
	s_barrier
	ds_read_b128 v[154:157], v226 offset:24576
	ds_read_b128 v[182:185], v227 offset:32768
	ds_read_b128 v[178:181], v227 offset:34816
	ds_read_b128 v[158:161], v226 offset:26624
	ds_read_b128 v[174:177], v227 offset:36864
	ds_read_b128 v[170:173], v227 offset:38912
	v_mfma_f32_32x32x16_bf16 v[114:129], v[162:165], v[138:141], v[114:129]
	v_mfma_f32_32x32x16_bf16 v[98:113], v[166:169], v[138:141], v[98:113]
	v_mfma_f32_32x32x16_bf16 v[66:81], v[162:165], v[142:145], v[66:81]
	v_mfma_f32_32x32x16_bf16 v[34:49], v[166:169], v[142:145], v[34:49]
	v_mfma_f32_32x32x16_bf16 v[82:97], v[146:149], v[138:141], v[82:97]
	v_mfma_f32_32x32x16_bf16 v[50:65], v[150:153], v[138:141], v[50:65]
	v_mfma_f32_32x32x16_bf16 v[18:33], v[146:149], v[142:145], v[18:33]
	v_mfma_f32_32x32x16_bf16 v[2:17], v[150:153], v[142:145], v[2:17]
	ds_read_b128 v[138:141], v228 offset:24576
	ds_read_b128 v[162:165], v229 offset:32768
	ds_read_b128 v[166:169], v229 offset:34816
	ds_read_b128 v[142:145], v228 offset:26624
	ds_read_b128 v[146:149], v229 offset:36864
	ds_read_b128 v[150:153], v229 offset:38912
	s_add_i32 m0, s13, 0x0
	s_waitcnt lgkmcnt(6)
	v_mfma_f32_32x32x16_bf16 v[114:129], v[182:185], v[154:157], v[114:129]
	global_load_lds_dwordx4 v238, vcc
	v_mfma_f32_32x32x16_bf16 v[98:113], v[178:181], v[154:157], v[98:113]
	global_load_lds_dwordx4 v238, vcc offset:1024
	s_add_i32 m0, s22, 0x2000
	s_add_u32 vcc_lo, vcc_lo, 0x480000
	s_addc_u32 vcc_hi, vcc_hi, 0
	v_mfma_f32_32x32x16_bf16 v[66:81], v[182:185], v[158:161], v[66:81]
	global_load_lds_dwordx4 v239, s[100:101]
	v_mfma_f32_32x32x16_bf16 v[34:49], v[178:181], v[158:161], v[34:49]
	global_load_lds_dwordx4 v239, s[100:101] offset:1024
	v_mfma_f32_32x32x16_bf16 v[82:97], v[174:177], v[154:157], v[82:97]
	global_load_lds_dwordx4 v239, s[100:101] offset:2048
	v_mfma_f32_32x32x16_bf16 v[50:65], v[170:173], v[154:157], v[50:65]
	global_load_lds_dwordx4 v239, s[100:101] offset:3072
	s_add_u32 s100, s100, 0x24000
	s_addc_u32 s101, s101, 0
	v_mfma_f32_32x32x16_bf16 v[18:33], v[174:177], v[158:161], v[18:33]
	v_mfma_f32_32x32x16_bf16 v[2:17], v[170:173], v[158:161], v[2:17]
	s_waitcnt vmcnt(6) lgkmcnt(0)
	s_barrier
	ds_read_b128 v[154:157], v226 offset:49152
	ds_read_b128 v[182:185], v227 offset:57344
	ds_read_b128 v[178:181], v227 offset:59392
	ds_read_b128 v[158:161], v226 offset:51200
	ds_read_b128 v[174:177], v227 offset:61440
	ds_read_b128 v[170:173], v227 offset:63488
	v_mfma_f32_32x32x16_bf16 v[114:129], v[162:165], v[138:141], v[114:129]
	v_mfma_f32_32x32x16_bf16 v[98:113], v[166:169], v[138:141], v[98:113]
	v_mfma_f32_32x32x16_bf16 v[66:81], v[162:165], v[142:145], v[66:81]
	v_mfma_f32_32x32x16_bf16 v[34:49], v[166:169], v[142:145], v[34:49]
	v_mfma_f32_32x32x16_bf16 v[82:97], v[146:149], v[138:141], v[82:97]
	v_mfma_f32_32x32x16_bf16 v[50:65], v[150:153], v[138:141], v[50:65]
	v_mfma_f32_32x32x16_bf16 v[18:33], v[146:149], v[142:145], v[18:33]
	v_mfma_f32_32x32x16_bf16 v[2:17], v[150:153], v[142:145], v[2:17]
	ds_read_b128 v[138:141], v228 offset:49152
	ds_read_b128 v[162:165], v229 offset:57344
	ds_read_b128 v[166:169], v229 offset:59392
	ds_read_b128 v[142:145], v228 offset:51200
	ds_read_b128 v[146:149], v229 offset:61440
	ds_read_b128 v[150:153], v229 offset:63488
	s_add_i32 m0, s13, 0x6000
	s_waitcnt lgkmcnt(6)
	v_mfma_f32_32x32x16_bf16 v[114:129], v[182:185], v[154:157], v[114:129]
	global_load_lds_dwordx4 v238, vcc
	v_mfma_f32_32x32x16_bf16 v[98:113], v[178:181], v[154:157], v[98:113]
	global_load_lds_dwordx4 v238, vcc offset:1024
	s_add_i32 m0, s22, 0x8000
	s_add_u32 vcc_lo, vcc_lo, 0x480000
	s_addc_u32 vcc_hi, vcc_hi, 0
	v_mfma_f32_32x32x16_bf16 v[66:81], v[182:185], v[158:161], v[66:81]
	global_load_lds_dwordx4 v239, s[100:101]
	v_mfma_f32_32x32x16_bf16 v[34:49], v[178:181], v[158:161], v[34:49]
	global_load_lds_dwordx4 v239, s[100:101] offset:1024
	v_mfma_f32_32x32x16_bf16 v[82:97], v[174:177], v[154:157], v[82:97]
	global_load_lds_dwordx4 v239, s[100:101] offset:2048
	v_mfma_f32_32x32x16_bf16 v[50:65], v[170:173], v[154:157], v[50:65]
	global_load_lds_dwordx4 v239, s[100:101] offset:3072
	s_add_u32 s100, s100, 0x24000
	s_addc_u32 s101, s101, 0
	v_mfma_f32_32x32x16_bf16 v[18:33], v[174:177], v[158:161], v[18:33]
	v_mfma_f32_32x32x16_bf16 v[2:17], v[170:173], v[158:161], v[2:17]
	s_waitcnt vmcnt(6) lgkmcnt(0)
	s_barrier
; #define LAS __attribute__((address_space(3)))
; DI f32x16 mfma32(bf16x8 a, bf16x8 b, f32x16 c) { return __builtin_amdgcn_mfma_f32_32x32x16_bf16(a, b, c, 0, 0, 0); }
;     ...
;   for (int kt = 0; kt < nk; ++kt) {
;     const int kn = (kt + 2 < nk) ? (kt + 2) : (nk - 1);
;     const LAS char* cur = lds + s0;
;     bf16x8 af[2][2], bfr[2][4];
; #pragma unroll
;     for (int kk = 0; kk < 2; ++kk) {
;       const int xo = kk ? x1 : x0;
;       af[kk][0] = *(const LAS bf16x8*)(cur + a_rd + xo);
;       bfr[kk][0] = *(const LAS bf16x8*)(cur + b_rd + xo);
;       bfr[kk][1] = *(const LAS bf16x8*)(cur + b_rd + 2048 + xo);
;       af[kk][1] = *(const LAS bf16x8*)(cur + a_rd + 2048 + xo);
;       bfr[kk][2] = *(const LAS bf16x8*)(cur + b_rd + 4096 + xo);
;       bfr[kk][3] = *(const LAS bf16x8*)(cur + b_rd + 6144 + xo);
;     }
;     DMA_STEP_(kn, s2);
; #pragma unroll
;     for (int kk = 0; kk < 2; ++kk) {
;       acc[0][0] = mfma32(bfr[kk][0], af[kk][0], acc[0][0]); acc[0][1] = mfma32(bfr[kk][1], af[kk][0], acc[0][1]);
;       acc[1][0] = mfma32(bfr[kk][0], af[kk][1], acc[1][0]); acc[1][1] = mfma32(bfr[kk][1], af[kk][1], acc[1][1]);
;       acc[0][2] = mfma32(bfr[kk][2], af[kk][0], acc[0][2]); acc[0][3] = mfma32(bfr[kk][3], af[kk][0], acc[0][3]);
;       acc[1][2] = mfma32(bfr[kk][2], af[kk][1], acc[1][2]); acc[1][3] = mfma32(bfr[kk][3], af[kk][1], acc[1][3]);
;     }
;     __builtin_amdgcn_sched_group_barrier(0x100, 12, 0);
;     __builtin_amdgcn_sched_group_barrier(0x010, 6, 0);
;     __builtin_amdgcn_sched_group_barrier(0x008, 16, 0);
;     asm volatile("s_waitcnt vmcnt(6) lgkmcnt(0)" ::: "memory");
;     __builtin_amdgcn_s_barrier();
;     asm volatile("" ::: "memory");
;     s0 = (s0 == 2 * STG) ? 0 : s0 + STG;
;     s2 = (s2 == 2 * STG) ? 0 : s2 + STG;
;   }
	ds_read_b128 v[154:157], v226 offset:0
	ds_read_b128 v[182:185], v227 offset:8192
	ds_read_b128 v[178:181], v227 offset:10240
	ds_read_b128 v[158:161], v226 offset:2048
	ds_read_b128 v[174:177], v227 offset:12288
	ds_read_b128 v[170:173], v227 offset:14336
	v_mfma_f32_32x32x16_bf16 v[114:129], v[162:165], v[138:141], v[114:129]
	v_mfma_f32_32x32x16_bf16 v[98:113], v[166:169], v[138:141], v[98:113]
	v_mfma_f32_32x32x16_bf16 v[66:81], v[162:165], v[142:145], v[66:81]
	v_mfma_f32_32x32x16_bf16 v[34:49], v[166:169], v[142:145], v[34:49]
	v_mfma_f32_32x32x16_bf16 v[82:97], v[146:149], v[138:141], v[82:97]
	v_mfma_f32_32x32x16_bf16 v[50:65], v[150:153], v[138:141], v[50:65]
	v_mfma_f32_32x32x16_bf16 v[18:33], v[146:149], v[142:145], v[18:33]
	v_mfma_f32_32x32x16_bf16 v[2:17], v[150:153], v[142:145], v[2:17]
	ds_read_b128 v[138:141], v228 offset:0
	ds_read_b128 v[162:165], v229 offset:8192
	ds_read_b128 v[166:169], v229 offset:10240
	ds_read_b128 v[142:145], v228 offset:2048
	ds_read_b128 v[146:149], v229 offset:12288
	ds_read_b128 v[150:153], v229 offset:14336
	s_add_i32 m0, s13, 0xc000
	s_waitcnt lgkmcnt(6)
	v_mfma_f32_32x32x16_bf16 v[114:129], v[182:185], v[154:157], v[114:129]
	global_load_lds_dwordx4 v238, vcc
	v_mfma_f32_32x32x16_bf16 v[98:113], v[178:181], v[154:157], v[98:113]
	global_load_lds_dwordx4 v238, vcc offset:1024
	s_add_i32 m0, s22, 0xe000
	s_add_u32 vcc_lo, vcc_lo, 0x480000
	s_addc_u32 vcc_hi, vcc_hi, 0
	v_mfma_f32_32x32x16_bf16 v[66:81], v[182:185], v[158:161], v[66:81]
	global_load_lds_dwordx4 v239, s[100:101]
	v_mfma_f32_32x32x16_bf16 v[34:49], v[178:181], v[158:161], v[34:49]
	global_load_lds_dwordx4 v239, s[100:101] offset:1024
	v_mfma_f32_32x32x16_bf16 v[82:97], v[174:177], v[154:157], v[82:97]
	global_load_lds_dwordx4 v239, s[100:101] offset:2048
	v_mfma_f32_32x32x16_bf16 v[50:65], v[170:173], v[154:157], v[50:65]
	global_load_lds_dwordx4 v239, s[100:101] offset:3072
	s_add_u32 s100, s100, 0x24000
	s_addc_u32 s101, s101, 0
	v_mfma_f32_32x32x16_bf16 v[18:33], v[174:177], v[158:161], v[18:33]
	v_mfma_f32_32x32x16_bf16 v[2:17], v[170:173], v[158:161], v[2:17]
	s_waitcnt vmcnt(6) lgkmcnt(0)
	s_barrier
	ds_read_b128 v[154:157], v226 offset:24576
	ds_read_b128 v[182:185], v227 offset:32768
	ds_read_b128 v[178:181], v227 offset:34816
	ds_read_b128 v[158:161], v226 offset:26624
	ds_read_b128 v[174:177], v227 offset:36864
	ds_read_b128 v[170:173], v227 offset:38912
	v_mfma_f32_32x32x16_bf16 v[114:129], v[162:165], v[138:141], v[114:129]
	v_mfma_f32_32x32x16_bf16 v[98:113], v[166:169], v[138:141], v[98:113]
	v_mfma_f32_32x32x16_bf16 v[66:81], v[162:165], v[142:145], v[66:81]
	v_mfma_f32_32x32x16_bf16 v[34:49], v[166:169], v[142:145], v[34:49]
	v_mfma_f32_32x32x16_bf16 v[82:97], v[146:149], v[138:141], v[82:97]
	v_mfma_f32_32x32x16_bf16 v[50:65], v[150:153], v[138:141], v[50:65]
	v_mfma_f32_32x32x16_bf16 v[18:33], v[146:149], v[142:145], v[18:33]
	v_mfma_f32_32x32x16_bf16 v[2:17], v[150:153], v[142:145], v[2:17]
	ds_read_b128 v[138:141], v228 offset:24576
	ds_read_b128 v[162:165], v229 offset:32768
	ds_read_b128 v[166:169], v229 offset:34816
	ds_read_b128 v[142:145], v228 offset:26624
	ds_read_b128 v[146:149], v229 offset:36864
	ds_read_b128 v[150:153], v229 offset:38912
	s_add_i32 m0, s13, 0x0
	s_waitcnt lgkmcnt(6)
	v_mfma_f32_32x32x16_bf16 v[114:129], v[182:185], v[154:157], v[114:129]
	global_load_lds_dwordx4 v238, vcc
	v_mfma_f32_32x32x16_bf16 v[98:113], v[178:181], v[154:157], v[98:113]
	global_load_lds_dwordx4 v238, vcc offset:1024
	s_add_i32 m0, s22, 0x2000
	s_add_u32 vcc_lo, vcc_lo, 0x480000
	s_addc_u32 vcc_hi, vcc_hi, 0
	v_mfma_f32_32x32x16_bf16 v[66:81], v[182:185], v[158:161], v[66:81]
	global_load_lds_dwordx4 v239, s[100:101]
	v_mfma_f32_32x32x16_bf16 v[34:49], v[178:181], v[158:161], v[34:49]
	global_load_lds_dwordx4 v239, s[100:101] offset:1024
	v_mfma_f32_32x32x16_bf16 v[82:97], v[174:177], v[154:157], v[82:97]
	global_load_lds_dwordx4 v239, s[100:101] offset:2048
	v_mfma_f32_32x32x16_bf16 v[50:65], v[170:173], v[154:157], v[50:65]
	global_load_lds_dwordx4 v239, s[100:101] offset:3072
	s_add_u32 s100, s100, 0x24000
	s_addc_u32 s101, s101, 0
	v_mfma_f32_32x32x16_bf16 v[18:33], v[174:177], v[158:161], v[18:33]
	v_mfma_f32_32x32x16_bf16 v[2:17], v[170:173], v[158:161], v[2:17]
	s_waitcnt vmcnt(6) lgkmcnt(0)
	s_barrier
	ds_read_b128 v[154:157], v226 offset:49152
	ds_read_b128 v[182:185], v227 offset:57344
	ds_read_b128 v[178:181], v227 offset:59392
	ds_read_b128 v[158:161], v226 offset:51200
	ds_read_b128 v[174:177], v227 offset:61440
	ds_read_b128 v[170:173], v227 offset:63488
	v_mfma_f32_32x32x16_bf16 v[114:129], v[162:165], v[138:141], v[114:129]
	v_mfma_f32_32x32x16_bf16 v[98:113], v[166:169], v[138:141], v[98:113]
	v_mfma_f32_32x32x16_bf16 v[66:81], v[162:165], v[142:145], v[66:81]
	v_mfma_f32_32x32x16_bf16 v[34:49], v[166:169], v[142:145], v[34:49]
	v_mfma_f32_32x32x16_bf16 v[82:97], v[146:149], v[138:141], v[82:97]
	v_mfma_f32_32x32x16_bf16 v[50:65], v[150:153], v[138:141], v[50:65]
	v_mfma_f32_32x32x16_bf16 v[18:33], v[146:149], v[142:145], v[18:33]
	v_mfma_f32_32x32x16_bf16 v[2:17], v[150:153], v[142:145], v[2:17]
	ds_read_b128 v[138:141], v228 offset:49152
	ds_read_b128 v[162:165], v229 offset:57344
	ds_read_b128 v[166:169], v229 offset:59392
	ds_read_b128 v[142:145], v228 offset:51200
	ds_read_b128 v[146:149], v229 offset:61440
	ds_read_b128 v[150:153], v229 offset:63488
	s_add_i32 m0, s13, 0x6000
	s_waitcnt lgkmcnt(6)
	v_mfma_f32_32x32x16_bf16 v[114:129], v[182:185], v[154:157], v[114:129]
	global_load_lds_dwordx4 v238, vcc
	v_mfma_f32_32x32x16_bf16 v[98:113], v[178:181], v[154:157], v[98:113]
	global_load_lds_dwordx4 v238, vcc offset:1024
	s_add_i32 m0, s22, 0x8000
	s_add_u32 vcc_lo, vcc_lo, 0x480000
	s_addc_u32 vcc_hi, vcc_hi, 0
	v_mfma_f32_32x32x16_bf16 v[66:81], v[182:185], v[158:161], v[66:81]
	global_load_lds_dwordx4 v239, s[100:101]
	v_mfma_f32_32x32x16_bf16 v[34:49], v[178:181], v[158:161], v[34:49]
	global_load_lds_dwordx4 v239, s[100:101] offset:1024
	v_mfma_f32_32x32x16_bf16 v[82:97], v[174:177], v[154:157], v[82:97]
	global_load_lds_dwordx4 v239, s[100:101] offset:2048
	v_mfma_f32_32x32x16_bf16 v[50:65], v[170:173], v[154:157], v[50:65]
	global_load_lds_dwordx4 v239, s[100:101] offset:3072
	s_add_u32 s100, s100, 0x24000
	s_addc_u32 s101, s101, 0
	v_mfma_f32_32x32x16_bf16 v[18:33], v[174:177], v[158:161], v[18:33]
	v_mfma_f32_32x32x16_bf16 v[2:17], v[170:173], v[158:161], v[2:17]
	s_waitcnt vmcnt(6) lgkmcnt(0)
	s_barrier
; #define LAS __attribute__((address_space(3)))
; DI unsigned pk2(float a, float b) { f32x2 v = {a, b}; bf2_t r = __builtin_convertvector(v, bf2_t); return __builtin_bit_cast(unsigned, r); }
;     ...
;   for (int kt = 0; kt < nk; ++kt) {
;     const int kn = (kt + 2 < nk) ? (kt + 2) : (nk - 1);
;     const LAS char* cur = lds + s0;
;     bf16x8 af[2][2], bfr[2][4];
; #pragma unroll
;     for (int kk = 0; kk < 2; ++kk) {
;       const int xo = kk ? x1 : x0;
;       af[kk][0] = *(const LAS bf16x8*)(cur + a_rd + xo);
;       bfr[kk][0] = *(const LAS bf16x8*)(cur + b_rd + xo);
;       bfr[kk][1] = *(const LAS bf16x8*)(cur + b_rd + 2048 + xo);
;       af[kk][1] = *(const LAS bf16x8*)(cur + a_rd + 2048 + xo);
;       bfr[kk][2] = *(const LAS bf16x8*)(cur + b_rd + 4096 + xo);
;       bfr[kk][3] = *(const LAS bf16x8*)(cur + b_rd + 6144 + xo);
;     }
;     DMA_STEP_(kn, s2);
; #pragma unroll
;     for (int kk = 0; kk < 2; ++kk) {
;       acc[0][0] = mfma32(bfr[kk][0], af[kk][0], acc[0][0]); acc[0][1] = mfma32(bfr[kk][1], af[kk][0], acc[0][1]);
;       acc[1][0] = mfma32(bfr[kk][0], af[kk][1], acc[1][0]); acc[1][1] = mfma32(bfr[kk][1], af[kk][1], acc[1][1]);
;       acc[0][2] = mfma32(bfr[kk][2], af[kk][0], acc[0][2]); acc[0][3] = mfma32(bfr[kk][3], af[kk][0], acc[0][3]);
;       acc[1][2] = mfma32(bfr[kk][2], af[kk][1], acc[1][2]); acc[1][3] = mfma32(bfr[kk][3], af[kk][1], acc[1][3]);
;     }
;     __builtin_amdgcn_sched_group_barrier(0x100, 12, 0);
;     __builtin_amdgcn_sched_group_barrier(0x010, 6, 0);
;     __builtin_amdgcn_sched_group_barrier(0x008, 16, 0);
;     asm volatile("s_waitcnt vmcnt(6) lgkmcnt(0)" ::: "memory");
;     __builtin_amdgcn_s_barrier();
;     asm volatile("" ::: "memory");
;     s0 = (s0 == 2 * STG) ? 0 : s0 + STG;
;     s2 = (s2 == 2 * STG) ? 0 : s2 + STG;
;   }
;   asm volatile("s_waitcnt vmcnt(0)" ::: "memory");
;   __builtin_amdgcn_s_barrier();
;   asm volatile("" ::: "memory");
;     ...
;   {
;     const int h = lane >> 5, cl = lane & 31;
; #pragma unroll
;     for (int i = 0; i < 2; ++i)
; #pragma unroll
;       for (int j = 0; j < 4; ++j)
; #pragma unroll
;         for (int g = 0; g < 4; ++g) {
;           u32x2 w; w.x = pk2(acc[i][j][4 * g], acc[i][j][4 * g + 1]); w.y = pk2(acc[i][j][4 * g + 2], acc[i][j][4 * g + 3]);
;           *(u32x2*)(smem + (wr * 64 + i * 32 + cl) * 528 + (wc * 128 + j * 32 + 8 * g + 4 * h) * 2) = w;
	ds_read_b128 v[154:157], v226 offset:0
	ds_read_b128 v[182:185], v227 offset:8192
	ds_read_b128 v[178:181], v227 offset:10240
	ds_read_b128 v[158:161], v226 offset:2048
	ds_read_b128 v[174:177], v227 offset:12288
	ds_read_b128 v[170:173], v227 offset:14336
	v_mfma_f32_32x32x16_bf16 v[114:129], v[162:165], v[138:141], v[114:129]
	v_mfma_f32_32x32x16_bf16 v[98:113], v[166:169], v[138:141], v[98:113]
	v_mfma_f32_32x32x16_bf16 v[66:81], v[162:165], v[142:145], v[66:81]
	v_mfma_f32_32x32x16_bf16 v[34:49], v[166:169], v[142:145], v[34:49]
	v_mfma_f32_32x32x16_bf16 v[82:97], v[146:149], v[138:141], v[82:97]
	v_mfma_f32_32x32x16_bf16 v[50:65], v[150:153], v[138:141], v[50:65]
	v_mfma_f32_32x32x16_bf16 v[18:33], v[146:149], v[142:145], v[18:33]
	v_mfma_f32_32x32x16_bf16 v[2:17], v[150:153], v[142:145], v[2:17]
	s_add_i32 s23, s23, 6
	s_cmp_lg_u32 s23, 30
	s_cbranch_scc1 .LBB0_184
	ds_read_b128 v[138:141], v228 offset:0
	ds_read_b128 v[162:165], v229 offset:8192
	ds_read_b128 v[166:169], v229 offset:10240
	ds_read_b128 v[142:145], v228 offset:2048
	ds_read_b128 v[146:149], v229 offset:12288
	ds_read_b128 v[150:153], v229 offset:14336
	s_waitcnt lgkmcnt(6)
	v_mfma_f32_32x32x16_bf16 v[114:129], v[182:185], v[154:157], v[114:129]
	v_mfma_f32_32x32x16_bf16 v[98:113], v[178:181], v[154:157], v[98:113]
	v_mfma_f32_32x32x16_bf16 v[66:81], v[182:185], v[158:161], v[66:81]
	v_mfma_f32_32x32x16_bf16 v[34:49], v[178:181], v[158:161], v[34:49]
	v_mfma_f32_32x32x16_bf16 v[82:97], v[174:177], v[154:157], v[82:97]
	v_mfma_f32_32x32x16_bf16 v[50:65], v[170:173], v[154:157], v[50:65]
	v_mfma_f32_32x32x16_bf16 v[18:33], v[174:177], v[158:161], v[18:33]
	v_mfma_f32_32x32x16_bf16 v[2:17], v[170:173], v[158:161], v[2:17]
	s_waitcnt vmcnt(0) lgkmcnt(0)
	s_barrier
	ds_read_b128 v[154:157], v226 offset:24576
	ds_read_b128 v[182:185], v227 offset:32768
	ds_read_b128 v[178:181], v227 offset:34816
	ds_read_b128 v[158:161], v226 offset:26624
	ds_read_b128 v[174:177], v227 offset:36864
	ds_read_b128 v[170:173], v227 offset:38912
	v_mfma_f32_32x32x16_bf16 v[114:129], v[162:165], v[138:141], v[114:129]
	v_mfma_f32_32x32x16_bf16 v[98:113], v[166:169], v[138:141], v[98:113]
	v_mfma_f32_32x32x16_bf16 v[66:81], v[162:165], v[142:145], v[66:81]
	v_mfma_f32_32x32x16_bf16 v[34:49], v[166:169], v[142:145], v[34:49]
	v_mfma_f32_32x32x16_bf16 v[82:97], v[146:149], v[138:141], v[82:97]
	v_mfma_f32_32x32x16_bf16 v[50:65], v[150:153], v[138:141], v[50:65]
	v_mfma_f32_32x32x16_bf16 v[18:33], v[146:149], v[142:145], v[18:33]
	v_mfma_f32_32x32x16_bf16 v[2:17], v[150:153], v[142:145], v[2:17]
	ds_read_b128 v[138:141], v228 offset:24576
	ds_read_b128 v[162:165], v229 offset:32768
	ds_read_b128 v[166:169], v229 offset:34816
	ds_read_b128 v[142:145], v228 offset:26624
	ds_read_b128 v[146:149], v229 offset:36864
	ds_read_b128 v[150:153], v229 offset:38912
	s_waitcnt lgkmcnt(6)
	v_mfma_f32_32x32x16_bf16 v[114:129], v[182:185], v[154:157], v[114:129]
	v_mfma_f32_32x32x16_bf16 v[98:113], v[178:181], v[154:157], v[98:113]
	v_mfma_f32_32x32x16_bf16 v[66:81], v[182:185], v[158:161], v[66:81]
	v_mfma_f32_32x32x16_bf16 v[34:49], v[178:181], v[158:161], v[34:49]
	v_mfma_f32_32x32x16_bf16 v[82:97], v[174:177], v[154:157], v[82:97]
	v_mfma_f32_32x32x16_bf16 v[50:65], v[170:173], v[154:157], v[50:65]
	v_mfma_f32_32x32x16_bf16 v[18:33], v[174:177], v[158:161], v[18:33]
	v_mfma_f32_32x32x16_bf16 v[2:17], v[170:173], v[158:161], v[2:17]
	s_waitcnt lgkmcnt(0)
	v_mfma_f32_32x32x16_bf16 v[114:129], v[162:165], v[138:141], v[114:129]
	v_mfma_f32_32x32x16_bf16 v[98:113], v[166:169], v[138:141], v[98:113]
	v_mfma_f32_32x32x16_bf16 v[66:81], v[162:165], v[142:145], v[66:81]
	v_mfma_f32_32x32x16_bf16 v[34:49], v[166:169], v[142:145], v[34:49]
	v_mfma_f32_32x32x16_bf16 v[82:97], v[146:149], v[138:141], v[82:97]
	v_mfma_f32_32x32x16_bf16 v[50:65], v[150:153], v[138:141], v[50:65]
	v_mfma_f32_32x32x16_bf16 v[18:33], v[146:149], v[142:145], v[18:33]
	v_mfma_f32_32x32x16_bf16 v[2:17], v[150:153], v[142:145], v[2:17]
	s_waitcnt lgkmcnt(0)
	s_mov_b32 s101, 0
	s_setprio 0
	v_mul_lo_u32 v0, v197, s55
	v_add_u32_e32 v0, 16, v0
	s_nop 1
	v_cvt_pk_bf16_f32 v114, v114, v115
	v_cvt_pk_bf16_f32 v115, v116, v117
	v_lshlrev_b32_e32 v116, 3, v196
	s_lshl_b32 s10, s21, 1
	v_add3_u32 v0, v0, v116, s10
	v_cvt_pk_bf16_f32 v116, v118, v119
	v_cvt_pk_bf16_f32 v117, v120, v121
	v_cvt_pk_bf16_f32 v98, v98, v99
	v_cvt_pk_bf16_f32 v99, v100, v101
	v_cvt_pk_bf16_f32 v100, v102, v103
	v_cvt_pk_bf16_f32 v101, v104, v105
	v_cvt_pk_bf16_f32 v82, v82, v83
	v_cvt_pk_bf16_f32 v83, v84, v85
	v_cvt_pk_bf16_f32 v84, v86, v87
	v_cvt_pk_bf16_f32 v85, v88, v89
	v_cvt_pk_bf16_f32 v50, v50, v51
	v_cvt_pk_bf16_f32 v51, v52, v53
	v_cvt_pk_bf16_f32 v52, v54, v55
	v_cvt_pk_bf16_f32 v53, v56, v57
	s_waitcnt vmcnt(0)
	s_barrier
; DI unsigned pk2(float a, float b) { f32x2 v = {a, b}; bf2_t r = __builtin_convertvector(v, bf2_t); return __builtin_bit_cast(unsigned, r); }
;     ...
;   {
;     const int h = lane >> 5, cl = lane & 31;
; #pragma unroll
;     for (int i = 0; i < 2; ++i)
; #pragma unroll
;       for (int j = 0; j < 4; ++j)
; #pragma unroll
;         for (int g = 0; g < 4; ++g) {
;           u32x2 w; w.x = pk2(acc[i][j][4 * g], acc[i][j][4 * g + 1]); w.y = pk2(acc[i][j][4 * g + 2], acc[i][j][4 * g + 3]);
;           *(u32x2*)(smem + (wr * 64 + i * 32 + cl) * 528 + (wc * 128 + j * 32 + 8 * g + 4 * h) * 2) = w;
;         }
;   }
;   __syncthreads();
	ds_write2_b64 v0, v[114:115], v[116:117] offset1:2
	v_cvt_pk_bf16_f32 v114, v122, v123
	v_cvt_pk_bf16_f32 v115, v124, v125
	v_cvt_pk_bf16_f32 v116, v126, v127
	v_cvt_pk_bf16_f32 v117, v128, v129
	ds_write2_b64 v0, v[98:99], v[100:101] offset0:8 offset1:10
	v_cvt_pk_bf16_f32 v98, v106, v107
	v_cvt_pk_bf16_f32 v99, v108, v109
	v_cvt_pk_bf16_f32 v100, v110, v111
	v_cvt_pk_bf16_f32 v101, v112, v113
	ds_write2_b64 v0, v[82:83], v[84:85] offset0:16 offset1:18
	v_cvt_pk_bf16_f32 v82, v90, v91
	v_cvt_pk_bf16_f32 v83, v92, v93
	v_cvt_pk_bf16_f32 v84, v94, v95
	v_cvt_pk_bf16_f32 v85, v96, v97
	ds_write2_b64 v0, v[50:51], v[52:53] offset0:24 offset1:26
	v_cvt_pk_bf16_f32 v50, v58, v59
	v_cvt_pk_bf16_f32 v51, v60, v61
	v_cvt_pk_bf16_f32 v52, v62, v63
	v_cvt_pk_bf16_f32 v53, v64, v65
	ds_write2_b64 v0, v[114:115], v[116:117] offset0:4 offset1:6
	ds_write2_b64 v0, v[98:99], v[100:101] offset0:12 offset1:14
	ds_write2_b64 v0, v[82:83], v[84:85] offset0:20 offset1:22
	ds_write2_b64 v0, v[50:51], v[52:53] offset0:28 offset1:30
	v_cvt_pk_bf16_f32 v50, v66, v67
	v_cvt_pk_bf16_f32 v51, v68, v69
	v_cvt_pk_bf16_f32 v52, v70, v71
	v_cvt_pk_bf16_f32 v53, v72, v73
	v_add_u32_e32 v0, 0x4000, v0
	v_cvt_pk_bf16_f32 v34, v34, v35
	v_cvt_pk_bf16_f32 v35, v36, v37
	v_cvt_pk_bf16_f32 v36, v38, v39
	v_cvt_pk_bf16_f32 v37, v40, v41
	v_cvt_pk_bf16_f32 v18, v18, v19
	v_cvt_pk_bf16_f32 v19, v20, v21
	v_cvt_pk_bf16_f32 v20, v22, v23
	v_cvt_pk_bf16_f32 v21, v24, v25
	v_cvt_pk_bf16_f32 v2, v2, v3
	v_cvt_pk_bf16_f32 v3, v4, v5
	v_cvt_pk_bf16_f32 v4, v6, v7
	v_cvt_pk_bf16_f32 v5, v8, v9
	ds_write2_b64 v0, v[50:51], v[52:53] offset0:64 offset1:66
	v_cvt_pk_bf16_f32 v50, v74, v75
	v_cvt_pk_bf16_f32 v51, v76, v77
	v_cvt_pk_bf16_f32 v52, v78, v79
	v_cvt_pk_bf16_f32 v53, v80, v81
	ds_write2_b64 v0, v[34:35], v[36:37] offset0:72 offset1:74
	v_cvt_pk_bf16_f32 v34, v42, v43
	v_cvt_pk_bf16_f32 v35, v44, v45
	v_cvt_pk_bf16_f32 v36, v46, v47
	v_cvt_pk_bf16_f32 v37, v48, v49
	ds_write2_b64 v0, v[18:19], v[20:21] offset0:80 offset1:82
	v_cvt_pk_bf16_f32 v18, v26, v27
	v_cvt_pk_bf16_f32 v19, v28, v29
	v_cvt_pk_bf16_f32 v20, v30, v31
	v_cvt_pk_bf16_f32 v21, v32, v33
	ds_write2_b64 v0, v[2:3], v[4:5] offset0:88 offset1:90
	v_cvt_pk_bf16_f32 v2, v10, v11
	v_cvt_pk_bf16_f32 v3, v12, v13
	v_cvt_pk_bf16_f32 v4, v14, v15
	v_cvt_pk_bf16_f32 v5, v16, v17
	s_lshl_b64 s[14:15], s[14:15], 1
	ds_write2_b64 v0, v[50:51], v[52:53] offset0:68 offset1:70
	ds_write2_b64 v0, v[34:35], v[36:37] offset0:76 offset1:78
	ds_write2_b64 v0, v[18:19], v[20:21] offset0:84 offset1:86
	ds_write2_b64 v0, v[2:3], v[4:5] offset0:92 offset1:94
	s_waitcnt vmcnt(0) lgkmcnt(0)
	s_barrier
; #define GAS __attribute__((address_space(1)))
;     ...
;   if (EPI == 0) {
; #pragma unroll
;     for (int i = 0; i < 16; ++i) {
;       const int id = tid2 + 256 * i, r = id >> 5, c8 = (id & 31) * 8;
;       const u32x4 v = *(const u32x4*)(smem + r * 528 + c8 * 2);
;       *(GAS u32x4*)(ea.out + (size_t)(m0 + r) * ea.ldo + n0 + c8) = v;
;     }
	s_add_u32 s14, s16, s14
	v_lshlrev_b32_e32 v0, 4, v189
	v_and_b32_e32 v0, 0x1f0, v0
	s_addc_u32 s15, s17, s15
	v_add_u32_e32 v10, 16, v0
	v_lshl_add_u64 v[12:13], s[14:15], 0, v[0:1]
	v_ashrrev_i32_e32 v0, 5, v189
	v_mad_u64_u32 v[2:3], s[14:15], v0, s55, v[10:11]
	v_add_u32_e32 v0, s12, v0
	v_mad_i64_i32 v[14:15], s[14:15], v0, s35, v[12:13]
	v_add_u32_e32 v0, 0x100, v189
	ds_read_b128 v[2:5], v2
	v_ashrrev_i32_e32 v0, 5, v0
	v_mad_u64_u32 v[6:7], s[14:15], v0, s55, v[10:11]
	ds_read_b128 v[6:9], v6
	v_add_u32_e32 v0, s12, v0
	s_waitcnt lgkmcnt(1)
	global_store_dwordx4 v[14:15], v[2:5], off nt
	v_readlane_b32 s10, v252, 12
	s_add_i32 s20, s20, s10
	v_mad_i64_i32 v[2:3], s[14:15], v0, s35, v[12:13]
	v_add_u32_e32 v0, 0x200, v189
	v_ashrrev_i32_e32 v0, 5, v0
	s_waitcnt lgkmcnt(0)
	global_store_dwordx4 v[2:3], v[6:9], off nt
	v_mad_u64_u32 v[2:3], s[14:15], v0, s55, v[10:11]
	v_add_u32_e32 v0, s12, v0
	v_mad_i64_i32 v[14:15], s[14:15], v0, s35, v[12:13]
	v_add_u32_e32 v0, 0x300, v189
	ds_read_b128 v[2:5], v2
	v_ashrrev_i32_e32 v0, 5, v0
	v_mad_u64_u32 v[6:7], s[14:15], v0, s55, v[10:11]
	ds_read_b128 v[6:9], v6
	v_add_u32_e32 v0, s12, v0
	s_waitcnt lgkmcnt(1)
	global_store_dwordx4 v[14:15], v[2:5], off nt
	s_cmp_ge_i32 s20, s45
	s_nop 0
	v_mad_i64_i32 v[2:3], s[14:15], v0, s35, v[12:13]
	v_add_u32_e32 v0, 0x400, v189
	v_ashrrev_i32_e32 v0, 5, v0
	s_waitcnt lgkmcnt(0)
	global_store_dwordx4 v[2:3], v[6:9], off nt
	v_mad_u64_u32 v[2:3], s[14:15], v0, s55, v[10:11]
	v_add_u32_e32 v0, s12, v0
	v_mad_i64_i32 v[14:15], s[14:15], v0, s35, v[12:13]
	v_add_u32_e32 v0, 0x500, v189
	ds_read_b128 v[2:5], v2
	v_ashrrev_i32_e32 v0, 5, v0
	v_mad_u64_u32 v[6:7], s[14:15], v0, s55, v[10:11]
	ds_read_b128 v[6:9], v6
	v_add_u32_e32 v0, s12, v0
	s_waitcnt lgkmcnt(1)
	global_store_dwordx4 v[14:15], v[2:5], off nt
	s_nop 1
	v_mad_i64_i32 v[2:3], s[14:15], v0, s35, v[12:13]
	v_add_u32_e32 v0, 0x600, v189
	v_ashrrev_i32_e32 v0, 5, v0
	s_waitcnt lgkmcnt(0)
	global_store_dwordx4 v[2:3], v[6:9], off nt
	v_mad_u64_u32 v[2:3], s[14:15], v0, s55, v[10:11]
	v_add_u32_e32 v0, s12, v0
	v_mad_i64_i32 v[14:15], s[14:15], v0, s35, v[12:13]
	v_add_u32_e32 v0, 0x700, v189
	ds_read_b128 v[2:5], v2
	v_ashrrev_i32_e32 v0, 5, v0
	v_mad_u64_u32 v[6:7], s[14:15], v0, s55, v[10:11]
	ds_read_b128 v[6:9], v6
	v_add_u32_e32 v0, s12, v0
	s_waitcnt lgkmcnt(1)
	global_store_dwordx4 v[14:15], v[2:5], off nt
	s_nop 1
	v_mad_i64_i32 v[2:3], s[14:15], v0, s35, v[12:13]
	v_add_u32_e32 v0, 0x800, v189
	v_ashrrev_i32_e32 v0, 5, v0
	s_waitcnt lgkmcnt(0)
	global_store_dwordx4 v[2:3], v[6:9], off nt
	v_mad_u64_u32 v[2:3], s[14:15], v0, s55, v[10:11]
	v_add_u32_e32 v0, s12, v0
	v_mad_i64_i32 v[14:15], s[14:15], v0, s35, v[12:13]
	v_add_u32_e32 v0, 0x900, v189
	ds_read_b128 v[2:5], v2
	v_ashrrev_i32_e32 v0, 5, v0
	v_mad_u64_u32 v[6:7], s[14:15], v0, s55, v[10:11]
	ds_read_b128 v[6:9], v6
	v_add_u32_e32 v0, s12, v0
	s_waitcnt lgkmcnt(1)
	global_store_dwordx4 v[14:15], v[2:5], off nt
	s_nop 1
	v_mad_i64_i32 v[2:3], s[14:15], v0, s35, v[12:13]
	v_add_u32_e32 v0, 0xa00, v189
	v_ashrrev_i32_e32 v0, 5, v0
	s_waitcnt lgkmcnt(0)
	global_store_dwordx4 v[2:3], v[6:9], off nt
	v_mad_u64_u32 v[2:3], s[14:15], v0, s55, v[10:11]
	v_add_u32_e32 v0, s12, v0
	v_mad_i64_i32 v[14:15], s[14:15], v0, s35, v[12:13]
	v_add_u32_e32 v0, 0xb00, v189
	ds_read_b128 v[2:5], v2
	v_ashrrev_i32_e32 v0, 5, v0
	v_mad_u64_u32 v[6:7], s[14:15], v0, s55, v[10:11]
	ds_read_b128 v[6:9], v6
	v_add_u32_e32 v0, s12, v0
	s_waitcnt lgkmcnt(1)
	global_store_dwordx4 v[14:15], v[2:5], off nt
	s_nop 1
	v_mad_i64_i32 v[2:3], s[14:15], v0, s35, v[12:13]
	v_add_u32_e32 v0, 0xc00, v189
	v_ashrrev_i32_e32 v0, 5, v0
	s_waitcnt lgkmcnt(0)
	global_store_dwordx4 v[2:3], v[6:9], off nt
	v_mad_u64_u32 v[2:3], s[14:15], v0, s55, v[10:11]
	v_add_u32_e32 v0, s12, v0
	v_mad_i64_i32 v[14:15], s[14:15], v0, s35, v[12:13]
	v_add_u32_e32 v0, 0xd00, v189
	ds_read_b128 v[2:5], v2
	v_ashrrev_i32_e32 v0, 5, v0
	v_mad_u64_u32 v[6:7], s[14:15], v0, s55, v[10:11]
	ds_read_b128 v[6:9], v6
	v_add_u32_e32 v0, s12, v0
	s_waitcnt lgkmcnt(1)
	global_store_dwordx4 v[14:15], v[2:5], off nt
	s_nop 1
	v_mad_i64_i32 v[2:3], s[14:15], v0, s35, v[12:13]
	v_add_u32_e32 v0, 0xe00, v189
	v_ashrrev_i32_e32 v0, 5, v0
	s_waitcnt lgkmcnt(0)
	global_store_dwordx4 v[2:3], v[6:9], off nt
	v_mad_u64_u32 v[2:3], s[14:15], v0, s55, v[10:11]
	v_add_u32_e32 v0, s12, v0
	v_mad_i64_i32 v[14:15], s[14:15], v0, s35, v[12:13]
	v_add_u32_e32 v0, 0xf00, v189
	v_ashrrev_i32_e32 v0, 5, v0
	ds_read_b128 v[2:5], v2
	v_mad_u64_u32 v[6:7], s[14:15], v0, s55, v[10:11]
	ds_read_b128 v[6:9], v6
	v_add_u32_e32 v0, s12, v0
	s_waitcnt lgkmcnt(1)
	global_store_dwordx4 v[14:15], v[2:5], off nt
	s_nop 1
	v_mad_i64_i32 v[2:3], s[12:13], v0, s35, v[12:13]
	s_waitcnt lgkmcnt(0)
	global_store_dwordx4 v[2:3], v[6:9], off nt
	s_barrier
	s_cbranch_scc0 .LBB0_183
	v_mov_b64_e32 v[6:7], v[130:131]
	v_mov_b64_e32 v[2:3], v[134:135]
	v_mov_b32_e32 v31, v214
	v_mov_b32_e32 v30, v215
	v_mov_b32_e32 v29, v216
	v_mov_b32_e32 v28, v217
	v_mov_b64_e32 v[8:9], v[132:133]
	v_mov_b64_e32 v[4:5], v[136:137]
	v_readlane_b32 s44, v250, 17

; #define LAS __attribute__((address_space(3)))
;     ...
;   const int lane = tid & 63, wid = __builtin_amdgcn_readfirstlane(tid >> 6), wr = wid >> 1, wc = wid & 1;
;   const int m0 = mt * 128, n0 = nt * 256;
;   const int r = lane & 31, h = lane >> 5, key = (r >> 2) & 3;
;   constexpr int STG = 24576;
;   const int rowl = lane >> 2, cch = (lane & 3) ^ ((lane >> 4) & 3);
;   const unsigned voffA = (unsigned)(rowl * lda * 2 + cch * 16), voffB = (unsigned)(rowl * K * 2 + cch * 16);
;   const char* Abase = (const char*)(A + (size_t)m0 * lda) + (size_t)(wid * 2) * 32 * lda;
;   const char* Bbase = (const char*)(Bt + (size_t)n0 * K) + (size_t)(wid * 4) * 32 * K;
;   const size_t ablk = (size_t)32 * lda, bblk = (size_t)32 * K;
;   LAS char* lds = (LAS char*)smem;
;   LAS char* ldsA = lds + (wid * 2) * 1024;
;   LAS char* ldsB = lds + 8192 + (wid * 4) * 1024;
;     ...
;   const int x0 = ((0 + h) ^ key) * 16, x1 = ((2 + h) ^ key) * 16;
;   const int a_rd = (wr * 64 + r) * 64, b_rd = 8192 + (wc * 128 + r) * 64;
;   f32x16 acc[2][4];
; #pragma unroll
;   for (int i = 0; i < 2; ++i)
; #pragma unroll
;     for (int j = 0; j < 4; ++j)
; #pragma unroll
;       for (int e = 0; e < 16; ++e) acc[i][j][e] = 0.f;
;   const int nk = K >> 5;
;   DMA_STEP_(0, 0);
;   DMA_STEP_(1, STG);
;   asm volatile("s_waitcnt vmcnt(6)" ::: "memory");
;   __builtin_amdgcn_s_barrier();
;   asm volatile("" ::: "memory");
;   int s0 = 0, s2 = 2 * STG;
.LBB0_234:
	v_mov_b32_e32 v189, v188
	s_lshl_b32 s12, s23, 7
	v_readfirstlane_b32 s42, v189
	s_ashr_i32 s44, s42, 6
	s_lshl_b32 s28, s44, 2
	s_ashr_i32 s29, s28, 31
	s_lshl_b32 s23, s44, 12
	s_lshl_b64 s[40:41], s[28:29], 10
	s_add_i32 s28, s23, 16
	s_ashr_i32 s23, s42, 1
	v_and_b32_e32 v0, 31, v189
	s_andn2_b32 s23, s23, 63
	v_lshlrev_b32_e32 v2, 4, v189
	s_lshl_b32 s10, s44, 1
	v_or_b32_e32 v197, s23, v0
	s_lshl_b32 s23, s44, 7
	v_bitop3_b32 v2, v2, 48, v189 bitop3:0x48
	v_lshlrev_b32_e32 v3, 9, v189
	s_ashr_i32 s13, s12, 31
	s_ashr_i32 s11, s10, 31
	s_and_b32 s23, s23, 0x80
	s_movk_i32 s42, 0x7800
	s_lshl_b64 s[10:11], s[10:11], 10
	s_add_i32 s29, s28, 0x2000
	v_or_b32_e32 v4, s23, v0
	v_and_or_b32 v0, v3, s42, v2
	v_lshlrev_b32_e32 v10, 4, v189
	v_and_b32_e32 v10, 0x3c0, v10
	v_or_b32_e32 v10, v10, v2
	v_mov_b32_e32 v11, 0
	s_lshl_b64 s[42:43], s[12:13], 6
	s_add_u32 s13, s18, s42
	s_addc_u32 s42, s19, s43
	s_add_u32 s10, s13, s10
	s_addc_u32 s11, s42, s11
	s_lshl_b64 s[42:43], s[14:15], 6
	s_add_u32 s13, s20, s42
	s_addc_u32 s42, s21, s43
	s_add_u32 s40, s13, s40
	s_addc_u32 s41, s42, s41
	s_lshl_b32 s13, s44, 11
	s_sub_i32 s13, s28, s13
	v_lshl_add_u64 v[192:193], s[10:11], 0, v[10:11]
	s_mov_b32 m0, s13
	s_nop 0
	global_load_lds_dwordx4 v[192:193], off
	global_load_lds_dwordx4 v[192:193], off offset:1024
	v_lshl_add_u64 v[194:195], s[40:41], 0, v[10:11]
	s_mov_b32 m0, s29
	s_nop 0
	global_load_lds_dwordx4 v[194:195], off
	global_load_lds_dwordx4 v[194:195], off offset:1024
	global_load_lds_dwordx4 v[194:195], off offset:2048
	global_load_lds_dwordx4 v[194:195], off offset:3072
	s_mov_b64 s[10:11], 0x10000
	s_mov_b64 s[10:11], 0x18000
	s_mov_b64 s[10:11], 0x8040
	s_add_i32 m0, s13, 0x6000
	s_mov_b32 vcc_lo, 0x480000
	s_mov_b32 vcc_hi, 0
	v_lshl_add_u64 v[2:3], v[192:193], 0, vcc
	global_load_lds_dwordx4 v[2:3], off
	global_load_lds_dwordx4 v[2:3], off offset:1024
	v_bfe_u32 v196, v189, 5, 1
	s_add_i32 m0, s28, 0x8000
	s_mov_b32 s100, 0x24000
	v_lshl_add_u64 v[2:3], v[194:195], 0, s[100:101]
	global_load_lds_dwordx4 v[2:3], off
	global_load_lds_dwordx4 v[2:3], off offset:1024
	global_load_lds_dwordx4 v[2:3], off offset:2048
	global_load_lds_dwordx4 v[2:3], off offset:3072
	s_mov_b64 s[10:11], 0x10040
	s_mov_b64 s[10:11], 0x18040
	v_lshlrev_b32_e32 v218, 6, v4
	v_bfe_u32 v4, v189, 2, 2
	v_lshrrev_b32_e32 v5, 5, v189
	s_lshl_b32 s100, s100, 1
	v_lshl_add_u64 v[194:195], v[194:195], 0, s[100:101]
	s_lshl_b32 vcc_lo, vcc_lo, 1
	v_lshl_add_u64 v[192:193], v[192:193], 0, vcc
	s_waitcnt vmcnt(6)
	s_barrier
	v_bitop3_b32 v2, v196, v4, 2 bitop3:0x36
	v_bitop3_b32 v0, v5, v4, 1 bitop3:0x6c
	v_lshlrev_b32_e32 v220, 4, v2
	v_mov_b32_e32 v2, 0
	v_lshlrev_b32_e32 v219, 6, v197
	v_lshlrev_b32_e32 v0, 4, v0
	s_mov_b32 s40, 0xc000
	s_mov_b32 s29, 0
	s_mov_b32 s41, 0
	v_mov_b32_e32 v3, v2
	v_mov_b32_e32 v4, v2
	v_mov_b32_e32 v5, v2
	v_mov_b32_e32 v6, v2
	v_mov_b32_e32 v7, v2
	v_mov_b32_e32 v8, v2
	v_mov_b32_e32 v9, v2
	v_mov_b32_e32 v10, v2
	v_mov_b32_e32 v11, v2
	v_mov_b32_e32 v12, v2
	v_mov_b32_e32 v13, v2
	v_mov_b32_e32 v14, v2
	v_mov_b32_e32 v15, v2
	v_mov_b32_e32 v16, v2
	v_mov_b32_e32 v17, v2
	v_mov_b32_e32 v18, v2
	v_mov_b32_e32 v19, v2
	v_mov_b32_e32 v20, v2
	v_mov_b32_e32 v21, v2
	v_mov_b32_e32 v22, v2
	v_mov_b32_e32 v23, v2
	v_mov_b32_e32 v24, v2
	v_mov_b32_e32 v25, v2
	v_mov_b32_e32 v26, v2
	v_mov_b32_e32 v27, v2
	v_mov_b32_e32 v28, v2
	v_mov_b32_e32 v29, v2
	v_mov_b32_e32 v30, v2
	v_mov_b32_e32 v31, v2
	v_mov_b32_e32 v32, v2
	v_mov_b32_e32 v33, v2
	v_mov_b32_e32 v50, v2
	v_mov_b32_e32 v51, v2
	v_mov_b32_e32 v52, v2
	v_mov_b32_e32 v53, v2
	v_mov_b32_e32 v54, v2
	v_mov_b32_e32 v55, v2
	v_mov_b32_e32 v56, v2
	v_mov_b32_e32 v57, v2
	v_mov_b32_e32 v58, v2
	v_mov_b32_e32 v59, v2
	v_mov_b32_e32 v60, v2
	v_mov_b32_e32 v61, v2
	v_mov_b32_e32 v62, v2
	v_mov_b32_e32 v63, v2
	v_mov_b32_e32 v64, v2
	v_mov_b32_e32 v65, v2
	v_mov_b32_e32 v82, v2
	v_mov_b32_e32 v83, v2
	v_mov_b32_e32 v84, v2
	v_mov_b32_e32 v85, v2
	v_mov_b32_e32 v86, v2
	v_mov_b32_e32 v87, v2
	v_mov_b32_e32 v88, v2
	v_mov_b32_e32 v89, v2
	v_mov_b32_e32 v90, v2
	v_mov_b32_e32 v91, v2
	v_mov_b32_e32 v92, v2
	v_mov_b32_e32 v93, v2
	v_mov_b32_e32 v94, v2
	v_mov_b32_e32 v95, v2
	v_mov_b32_e32 v96, v2
	v_mov_b32_e32 v97, v2
	v_mov_b32_e32 v34, v2
	v_mov_b32_e32 v35, v2
	v_mov_b32_e32 v36, v2
	v_mov_b32_e32 v37, v2
	v_mov_b32_e32 v38, v2
	v_mov_b32_e32 v39, v2
	v_mov_b32_e32 v40, v2
	v_mov_b32_e32 v41, v2
	v_mov_b32_e32 v42, v2
	v_mov_b32_e32 v43, v2
	v_mov_b32_e32 v44, v2
	v_mov_b32_e32 v45, v2
	v_mov_b32_e32 v46, v2
	v_mov_b32_e32 v47, v2
	v_mov_b32_e32 v48, v2
	v_mov_b32_e32 v49, v2
	v_mov_b32_e32 v66, v2
	v_mov_b32_e32 v67, v2
	v_mov_b32_e32 v68, v2
	v_mov_b32_e32 v69, v2
	v_mov_b32_e32 v70, v2
	v_mov_b32_e32 v71, v2
	v_mov_b32_e32 v72, v2
	v_mov_b32_e32 v73, v2
	v_mov_b32_e32 v74, v2
	v_mov_b32_e32 v75, v2
	v_mov_b32_e32 v76, v2
	v_mov_b32_e32 v77, v2
	v_mov_b32_e32 v78, v2
	v_mov_b32_e32 v79, v2
	v_mov_b32_e32 v80, v2
	v_mov_b32_e32 v81, v2
	v_mov_b32_e32 v98, v2
	v_mov_b32_e32 v99, v2
	v_mov_b32_e32 v100, v2
	v_mov_b32_e32 v101, v2
	v_mov_b32_e32 v102, v2
	v_mov_b32_e32 v103, v2
	v_mov_b32_e32 v104, v2
	v_mov_b32_e32 v105, v2
	v_mov_b32_e32 v106, v2
	v_mov_b32_e32 v107, v2
	v_mov_b32_e32 v108, v2
	v_mov_b32_e32 v109, v2
	v_mov_b32_e32 v110, v2
	v_mov_b32_e32 v111, v2
	v_mov_b32_e32 v112, v2
	v_mov_b32_e32 v113, v2
	v_mov_b32_e32 v114, v2
	v_mov_b32_e32 v115, v2
	v_mov_b32_e32 v116, v2
	v_mov_b32_e32 v117, v2
	v_mov_b32_e32 v118, v2
	v_mov_b32_e32 v119, v2
	v_mov_b32_e32 v120, v2
	v_mov_b32_e32 v121, v2
	v_mov_b32_e32 v122, v2
	v_mov_b32_e32 v123, v2
	v_mov_b32_e32 v124, v2
	v_mov_b32_e32 v125, v2
	v_mov_b32_e32 v126, v2
	v_mov_b32_e32 v127, v2
	v_mov_b32_e32 v128, v2
	v_mov_b32_e32 v129, v2
	v_readfirstlane_b32 vcc_lo, v192
	v_readfirstlane_b32 vcc_hi, v193
	v_readfirstlane_b32 s100, v194
	v_readfirstlane_b32 s101, v195
	s_sub_u32 vcc_lo, vcc_lo, 0x100000
	s_subb_u32 vcc_hi, vcc_hi, 0
	s_sub_u32 s100, s100, 0x100000
	s_subb_u32 s101, s101, 0
	v_subrev_u32_e32 v238, vcc_lo, v192
	v_subrev_u32_e32 v239, s100, v194
	v_add3_u32 v226, v219, v0, 16
	v_add3_u32 v227, v218, v0, 16
	v_add3_u32 v228, v219, v220, 16
	v_add3_u32 v229, v218, v220, 16
	ds_read_b128 v[154:157], v226 offset:0
	ds_read_b128 v[182:185], v227 offset:8192
	ds_read_b128 v[178:181], v227 offset:10240
	ds_read_b128 v[158:161], v226 offset:2048
	ds_read_b128 v[174:177], v227 offset:12288
	ds_read_b128 v[170:173], v227 offset:14336
	s_setprio 1
; #define LAS __attribute__((address_space(3)))
; DI f32x16 mfma32(bf16x8 a, bf16x8 b, f32x16 c) { return __builtin_amdgcn_mfma_f32_32x32x16_bf16(a, b, c, 0, 0, 0); }
;     ...
;   for (int kt = 0; kt < nk; ++kt) {
;     const int kn = (kt + 2 < nk) ? (kt + 2) : (nk - 1);
;     const LAS char* cur = lds + s0;
;     bf16x8 af[2][2], bfr[2][4];
; #pragma unroll
;     for (int kk = 0; kk < 2; ++kk) {
;       const int xo = kk ? x1 : x0;
;       af[kk][0] = *(const LAS bf16x8*)(cur + a_rd + xo);
;       bfr[kk][0] = *(const LAS bf16x8*)(cur + b_rd + xo);
;       bfr[kk][1] = *(const LAS bf16x8*)(cur + b_rd + 2048 + xo);
;       af[kk][1] = *(const LAS bf16x8*)(cur + a_rd + 2048 + xo);
;       bfr[kk][2] = *(const LAS bf16x8*)(cur + b_rd + 4096 + xo);
;       bfr[kk][3] = *(const LAS bf16x8*)(cur + b_rd + 6144 + xo);
;     }
;     DMA_STEP_(kn, s2);
; #pragma unroll
;     for (int kk = 0; kk < 2; ++kk) {
;       acc[0][0] = mfma32(bfr[kk][0], af[kk][0], acc[0][0]); acc[0][1] = mfma32(bfr[kk][1], af[kk][0], acc[0][1]);
;       acc[1][0] = mfma32(bfr[kk][0], af[kk][1], acc[1][0]); acc[1][1] = mfma32(bfr[kk][1], af[kk][1], acc[1][1]);
;       acc[0][2] = mfma32(bfr[kk][2], af[kk][0], acc[0][2]); acc[0][3] = mfma32(bfr[kk][3], af[kk][0], acc[0][3]);
;       acc[1][2] = mfma32(bfr[kk][2], af[kk][1], acc[1][2]); acc[1][3] = mfma32(bfr[kk][3], af[kk][1], acc[1][3]);
;     }
;     __builtin_amdgcn_sched_group_barrier(0x100, 12, 0);
;     __builtin_amdgcn_sched_group_barrier(0x010, 6, 0);
;     __builtin_amdgcn_sched_group_barrier(0x008, 16, 0);
;     asm volatile("s_waitcnt vmcnt(6) lgkmcnt(0)" ::: "memory");
;     __builtin_amdgcn_s_barrier();
;     asm volatile("" ::: "memory");
;     s0 = (s0 == 2 * STG) ? 0 : s0 + STG;
;     s2 = (s2 == 2 * STG) ? 0 : s2 + STG;
;   }
.LBB0_235:
	ds_read_b128 v[138:141], v228 offset:0
	ds_read_b128 v[162:165], v229 offset:8192
	ds_read_b128 v[166:169], v229 offset:10240
	ds_read_b128 v[142:145], v228 offset:2048
	ds_read_b128 v[146:149], v229 offset:12288
	ds_read_b128 v[150:153], v229 offset:14336
	s_add_i32 m0, s13, 0xc000
	s_waitcnt lgkmcnt(6)
	v_mfma_f32_32x32x16_bf16 v[114:129], v[182:185], v[154:157], v[114:129]
	global_load_lds_dwordx4 v238, vcc
	v_mfma_f32_32x32x16_bf16 v[98:113], v[178:181], v[154:157], v[98:113]
	global_load_lds_dwordx4 v238, vcc offset:1024
	s_add_i32 m0, s28, 0xe000
	s_add_u32 vcc_lo, vcc_lo, 0x480000
	s_addc_u32 vcc_hi, vcc_hi, 0
	v_mfma_f32_32x32x16_bf16 v[66:81], v[182:185], v[158:161], v[66:81]
	global_load_lds_dwordx4 v239, s[100:101]
	v_mfma_f32_32x32x16_bf16 v[34:49], v[178:181], v[158:161], v[34:49]
	global_load_lds_dwordx4 v239, s[100:101] offset:1024
	v_mfma_f32_32x32x16_bf16 v[82:97], v[174:177], v[154:157], v[82:97]
	global_load_lds_dwordx4 v239, s[100:101] offset:2048
	v_mfma_f32_32x32x16_bf16 v[50:65], v[170:173], v[154:157], v[50:65]
	global_load_lds_dwordx4 v239, s[100:101] offset:3072
	s_add_u32 s100, s100, 0x24000
	s_addc_u32 s101, s101, 0
	v_mfma_f32_32x32x16_bf16 v[18:33], v[174:177], v[158:161], v[18:33]
	v_mfma_f32_32x32x16_bf16 v[2:17], v[170:173], v[158:161], v[2:17]
	s_waitcnt vmcnt(6) lgkmcnt(0)
	s_barrier
	ds_read_b128 v[154:157], v226 offset:24576
	ds_read_b128 v[182:185], v227 offset:32768
	ds_read_b128 v[178:181], v227 offset:34816
	ds_read_b128 v[158:161], v226 offset:26624
	ds_read_b128 v[174:177], v227 offset:36864
	ds_read_b128 v[170:173], v227 offset:38912
	v_mfma_f32_32x32x16_bf16 v[114:129], v[162:165], v[138:141], v[114:129]
	v_mfma_f32_32x32x16_bf16 v[98:113], v[166:169], v[138:141], v[98:113]
	v_mfma_f32_32x32x16_bf16 v[66:81], v[162:165], v[142:145], v[66:81]
	v_mfma_f32_32x32x16_bf16 v[34:49], v[166:169], v[142:145], v[34:49]
	v_mfma_f32_32x32x16_bf16 v[82:97], v[146:149], v[138:141], v[82:97]
	v_mfma_f32_32x32x16_bf16 v[50:65], v[150:153], v[138:141], v[50:65]
	v_mfma_f32_32x32x16_bf16 v[18:33], v[146:149], v[142:145], v[18:33]
	v_mfma_f32_32x32x16_bf16 v[2:17], v[150:153], v[142:145], v[2:17]
	ds_read_b128 v[138:141], v228 offset:24576
	ds_read_b128 v[162:165], v229 offset:32768
	ds_read_b128 v[166:169], v229 offset:34816
	ds_read_b128 v[142:145], v228 offset:26624
	ds_read_b128 v[146:149], v229 offset:36864
	ds_read_b128 v[150:153], v229 offset:38912
	s_add_i32 m0, s13, 0x0
	s_waitcnt lgkmcnt(6)
	v_mfma_f32_32x32x16_bf16 v[114:129], v[182:185], v[154:157], v[114:129]
	global_load_lds_dwordx4 v238, vcc
	v_mfma_f32_32x32x16_bf16 v[98:113], v[178:181], v[154:157], v[98:113]
	global_load_lds_dwordx4 v238, vcc offset:1024
	s_add_i32 m0, s28, 0x2000
	s_add_u32 vcc_lo, vcc_lo, 0x480000
	s_addc_u32 vcc_hi, vcc_hi, 0
	v_mfma_f32_32x32x16_bf16 v[66:81], v[182:185], v[158:161], v[66:81]
	global_load_lds_dwordx4 v239, s[100:101]
	v_mfma_f32_32x32x16_bf16 v[34:49], v[178:181], v[158:161], v[34:49]
	global_load_lds_dwordx4 v239, s[100:101] offset:1024
	v_mfma_f32_32x32x16_bf16 v[82:97], v[174:177], v[154:157], v[82:97]
	global_load_lds_dwordx4 v239, s[100:101] offset:2048
	v_mfma_f32_32x32x16_bf16 v[50:65], v[170:173], v[154:157], v[50:65]
	global_load_lds_dwordx4 v239, s[100:101] offset:3072
	s_add_u32 s100, s100, 0x24000
	s_addc_u32 s101, s101, 0
	v_mfma_f32_32x32x16_bf16 v[18:33], v[174:177], v[158:161], v[18:33]
	v_mfma_f32_32x32x16_bf16 v[2:17], v[170:173], v[158:161], v[2:17]
	s_waitcnt vmcnt(6) lgkmcnt(0)
	s_barrier
	ds_read_b128 v[154:157], v226 offset:49152
	ds_read_b128 v[182:185], v227 offset:57344
	ds_read_b128 v[178:181], v227 offset:59392
	ds_read_b128 v[158:161], v226 offset:51200
	ds_read_b128 v[174:177], v227 offset:61440
	ds_read_b128 v[170:173], v227 offset:63488
	v_mfma_f32_32x32x16_bf16 v[114:129], v[162:165], v[138:141], v[114:129]
	v_mfma_f32_32x32x16_bf16 v[98:113], v[166:169], v[138:141], v[98:113]
	v_mfma_f32_32x32x16_bf16 v[66:81], v[162:165], v[142:145], v[66:81]
	v_mfma_f32_32x32x16_bf16 v[34:49], v[166:169], v[142:145], v[34:49]
	v_mfma_f32_32x32x16_bf16 v[82:97], v[146:149], v[138:141], v[82:97]
	v_mfma_f32_32x32x16_bf16 v[50:65], v[150:153], v[138:141], v[50:65]
	v_mfma_f32_32x32x16_bf16 v[18:33], v[146:149], v[142:145], v[18:33]
	v_mfma_f32_32x32x16_bf16 v[2:17], v[150:153], v[142:145], v[2:17]
	ds_read_b128 v[138:141], v228 offset:49152
	ds_read_b128 v[162:165], v229 offset:57344
	ds_read_b128 v[166:169], v229 offset:59392
	ds_read_b128 v[142:145], v228 offset:51200
	ds_read_b128 v[146:149], v229 offset:61440
	ds_read_b128 v[150:153], v229 offset:63488
	s_add_i32 m0, s13, 0x6000
	s_waitcnt lgkmcnt(6)
	v_mfma_f32_32x32x16_bf16 v[114:129], v[182:185], v[154:157], v[114:129]
	global_load_lds_dwordx4 v238, vcc
	v_mfma_f32_32x32x16_bf16 v[98:113], v[178:181], v[154:157], v[98:113]
	global_load_lds_dwordx4 v238, vcc offset:1024
	s_add_i32 m0, s28, 0x8000
	s_add_u32 vcc_lo, vcc_lo, 0x480000
	s_addc_u32 vcc_hi, vcc_hi, 0
	v_mfma_f32_32x32x16_bf16 v[66:81], v[182:185], v[158:161], v[66:81]
	global_load_lds_dwordx4 v239, s[100:101]
	v_mfma_f32_32x32x16_bf16 v[34:49], v[178:181], v[158:161], v[34:49]
	global_load_lds_dwordx4 v239, s[100:101] offset:1024
	v_mfma_f32_32x32x16_bf16 v[82:97], v[174:177], v[154:157], v[82:97]
	global_load_lds_dwordx4 v239, s[100:101] offset:2048
	v_mfma_f32_32x32x16_bf16 v[50:65], v[170:173], v[154:157], v[50:65]
	global_load_lds_dwordx4 v239, s[100:101] offset:3072
	s_add_u32 s100, s100, 0x24000
	s_addc_u32 s101, s101, 0
	v_mfma_f32_32x32x16_bf16 v[18:33], v[174:177], v[158:161], v[18:33]
	v_mfma_f32_32x32x16_bf16 v[2:17], v[170:173], v[158:161], v[2:17]
	s_waitcnt vmcnt(6) lgkmcnt(0)
	s_barrier
; #define LAS __attribute__((address_space(3)))
; DI f32x16 mfma32(bf16x8 a, bf16x8 b, f32x16 c) { return __builtin_amdgcn_mfma_f32_32x32x16_bf16(a, b, c, 0, 0, 0); }
;     ...
;   for (int kt = 0; kt < nk; ++kt) {
;     const int kn = (kt + 2 < nk) ? (kt + 2) : (nk - 1);
;     const LAS char* cur = lds + s0;
;     bf16x8 af[2][2], bfr[2][4];
; #pragma unroll
;     for (int kk = 0; kk < 2; ++kk) {
;       const int xo = kk ? x1 : x0;
;       af[kk][0] = *(const LAS bf16x8*)(cur + a_rd + xo);
;       bfr[kk][0] = *(const LAS bf16x8*)(cur + b_rd + xo);
;       bfr[kk][1] = *(const LAS bf16x8*)(cur + b_rd + 2048 + xo);
;       af[kk][1] = *(const LAS bf16x8*)(cur + a_rd + 2048 + xo);
;       bfr[kk][2] = *(const LAS bf16x8*)(cur + b_rd + 4096 + xo);
;       bfr[kk][3] = *(const LAS bf16x8*)(cur + b_rd + 6144 + xo);
;     }
;     DMA_STEP_(kn, s2);
; #pragma unroll
;     for (int kk = 0; kk < 2; ++kk) {
;       acc[0][0] = mfma32(bfr[kk][0], af[kk][0], acc[0][0]); acc[0][1] = mfma32(bfr[kk][1], af[kk][0], acc[0][1]);
;       acc[1][0] = mfma32(bfr[kk][0], af[kk][1], acc[1][0]); acc[1][1] = mfma32(bfr[kk][1], af[kk][1], acc[1][1]);
;       acc[0][2] = mfma32(bfr[kk][2], af[kk][0], acc[0][2]); acc[0][3] = mfma32(bfr[kk][3], af[kk][0], acc[0][3]);
;       acc[1][2] = mfma32(bfr[kk][2], af[kk][1], acc[1][2]); acc[1][3] = mfma32(bfr[kk][3], af[kk][1], acc[1][3]);
;     }
;     __builtin_amdgcn_sched_group_barrier(0x100, 12, 0);
;     __builtin_amdgcn_sched_group_barrier(0x010, 6, 0);
;     __builtin_amdgcn_sched_group_barrier(0x008, 16, 0);
;     asm volatile("s_waitcnt vmcnt(6) lgkmcnt(0)" ::: "memory");
;     __builtin_amdgcn_s_barrier();
;     asm volatile("" ::: "memory");
;     s0 = (s0 == 2 * STG) ? 0 : s0 + STG;
;     s2 = (s2 == 2 * STG) ? 0 : s2 + STG;
;   }
	ds_read_b128 v[154:157], v226 offset:0
	ds_read_b128 v[182:185], v227 offset:8192
	ds_read_b128 v[178:181], v227 offset:10240
	ds_read_b128 v[158:161], v226 offset:2048
	ds_read_b128 v[174:177], v227 offset:12288
	ds_read_b128 v[170:173], v227 offset:14336
	v_mfma_f32_32x32x16_bf16 v[114:129], v[162:165], v[138:141], v[114:129]
	v_mfma_f32_32x32x16_bf16 v[98:113], v[166:169], v[138:141], v[98:113]
	v_mfma_f32_32x32x16_bf16 v[66:81], v[162:165], v[142:145], v[66:81]
	v_mfma_f32_32x32x16_bf16 v[34:49], v[166:169], v[142:145], v[34:49]
	v_mfma_f32_32x32x16_bf16 v[82:97], v[146:149], v[138:141], v[82:97]
	v_mfma_f32_32x32x16_bf16 v[50:65], v[150:153], v[138:141], v[50:65]
	v_mfma_f32_32x32x16_bf16 v[18:33], v[146:149], v[142:145], v[18:33]
	v_mfma_f32_32x32x16_bf16 v[2:17], v[150:153], v[142:145], v[2:17]
	ds_read_b128 v[138:141], v228 offset:0
	ds_read_b128 v[162:165], v229 offset:8192
	ds_read_b128 v[166:169], v229 offset:10240
	ds_read_b128 v[142:145], v228 offset:2048
	ds_read_b128 v[146:149], v229 offset:12288
	ds_read_b128 v[150:153], v229 offset:14336
	s_add_i32 m0, s13, 0xc000
	s_waitcnt lgkmcnt(6)
	v_mfma_f32_32x32x16_bf16 v[114:129], v[182:185], v[154:157], v[114:129]
	global_load_lds_dwordx4 v238, vcc
	v_mfma_f32_32x32x16_bf16 v[98:113], v[178:181], v[154:157], v[98:113]
	global_load_lds_dwordx4 v238, vcc offset:1024
	s_add_i32 m0, s28, 0xe000
	s_add_u32 vcc_lo, vcc_lo, 0x480000
	s_addc_u32 vcc_hi, vcc_hi, 0
	v_mfma_f32_32x32x16_bf16 v[66:81], v[182:185], v[158:161], v[66:81]
	global_load_lds_dwordx4 v239, s[100:101]
	v_mfma_f32_32x32x16_bf16 v[34:49], v[178:181], v[158:161], v[34:49]
	global_load_lds_dwordx4 v239, s[100:101] offset:1024
	v_mfma_f32_32x32x16_bf16 v[82:97], v[174:177], v[154:157], v[82:97]
	global_load_lds_dwordx4 v239, s[100:101] offset:2048
	v_mfma_f32_32x32x16_bf16 v[50:65], v[170:173], v[154:157], v[50:65]
	global_load_lds_dwordx4 v239, s[100:101] offset:3072
	s_add_u32 s100, s100, 0x24000
	s_addc_u32 s101, s101, 0
	v_mfma_f32_32x32x16_bf16 v[18:33], v[174:177], v[158:161], v[18:33]
	v_mfma_f32_32x32x16_bf16 v[2:17], v[170:173], v[158:161], v[2:17]
	s_waitcnt vmcnt(6) lgkmcnt(0)
	s_barrier
	ds_read_b128 v[154:157], v226 offset:24576
	ds_read_b128 v[182:185], v227 offset:32768
	ds_read_b128 v[178:181], v227 offset:34816
	ds_read_b128 v[158:161], v226 offset:26624
	ds_read_b128 v[174:177], v227 offset:36864
	ds_read_b128 v[170:173], v227 offset:38912
	v_mfma_f32_32x32x16_bf16 v[114:129], v[162:165], v[138:141], v[114:129]
	v_mfma_f32_32x32x16_bf16 v[98:113], v[166:169], v[138:141], v[98:113]
	v_mfma_f32_32x32x16_bf16 v[66:81], v[162:165], v[142:145], v[66:81]
	v_mfma_f32_32x32x16_bf16 v[34:49], v[166:169], v[142:145], v[34:49]
	v_mfma_f32_32x32x16_bf16 v[82:97], v[146:149], v[138:141], v[82:97]
	v_mfma_f32_32x32x16_bf16 v[50:65], v[150:153], v[138:141], v[50:65]
	v_mfma_f32_32x32x16_bf16 v[18:33], v[146:149], v[142:145], v[18:33]
	v_mfma_f32_32x32x16_bf16 v[2:17], v[150:153], v[142:145], v[2:17]
	ds_read_b128 v[138:141], v228 offset:24576
	ds_read_b128 v[162:165], v229 offset:32768
	ds_read_b128 v[166:169], v229 offset:34816
	ds_read_b128 v[142:145], v228 offset:26624
	ds_read_b128 v[146:149], v229 offset:36864
	ds_read_b128 v[150:153], v229 offset:38912
	s_add_i32 m0, s13, 0x0
	s_waitcnt lgkmcnt(6)
	v_mfma_f32_32x32x16_bf16 v[114:129], v[182:185], v[154:157], v[114:129]
	global_load_lds_dwordx4 v238, vcc
	v_mfma_f32_32x32x16_bf16 v[98:113], v[178:181], v[154:157], v[98:113]
	global_load_lds_dwordx4 v238, vcc offset:1024
	s_add_i32 m0, s28, 0x2000
	s_add_u32 vcc_lo, vcc_lo, 0x480000
	s_addc_u32 vcc_hi, vcc_hi, 0
	v_mfma_f32_32x32x16_bf16 v[66:81], v[182:185], v[158:161], v[66:81]
	global_load_lds_dwordx4 v239, s[100:101]
	v_mfma_f32_32x32x16_bf16 v[34:49], v[178:181], v[158:161], v[34:49]
	global_load_lds_dwordx4 v239, s[100:101] offset:1024
	v_mfma_f32_32x32x16_bf16 v[82:97], v[174:177], v[154:157], v[82:97]
	global_load_lds_dwordx4 v239, s[100:101] offset:2048
	v_mfma_f32_32x32x16_bf16 v[50:65], v[170:173], v[154:157], v[50:65]
	global_load_lds_dwordx4 v239, s[100:101] offset:3072
	s_add_u32 s100, s100, 0x24000
	s_addc_u32 s101, s101, 0
	v_mfma_f32_32x32x16_bf16 v[18:33], v[174:177], v[158:161], v[18:33]
	v_mfma_f32_32x32x16_bf16 v[2:17], v[170:173], v[158:161], v[2:17]
	s_waitcnt vmcnt(6) lgkmcnt(0)
	s_barrier
	ds_read_b128 v[154:157], v226 offset:49152
	ds_read_b128 v[182:185], v227 offset:57344
	ds_read_b128 v[178:181], v227 offset:59392
	ds_read_b128 v[158:161], v226 offset:51200
	ds_read_b128 v[174:177], v227 offset:61440
	ds_read_b128 v[170:173], v227 offset:63488
	v_mfma_f32_32x32x16_bf16 v[114:129], v[162:165], v[138:141], v[114:129]
	v_mfma_f32_32x32x16_bf16 v[98:113], v[166:169], v[138:141], v[98:113]
	v_mfma_f32_32x32x16_bf16 v[66:81], v[162:165], v[142:145], v[66:81]
	v_mfma_f32_32x32x16_bf16 v[34:49], v[166:169], v[142:145], v[34:49]
	v_mfma_f32_32x32x16_bf16 v[82:97], v[146:149], v[138:141], v[82:97]
	v_mfma_f32_32x32x16_bf16 v[50:65], v[150:153], v[138:141], v[50:65]
	v_mfma_f32_32x32x16_bf16 v[18:33], v[146:149], v[142:145], v[18:33]
	v_mfma_f32_32x32x16_bf16 v[2:17], v[150:153], v[142:145], v[2:17]
	ds_read_b128 v[138:141], v228 offset:49152
	ds_read_b128 v[162:165], v229 offset:57344
	ds_read_b128 v[166:169], v229 offset:59392
	ds_read_b128 v[142:145], v228 offset:51200
	ds_read_b128 v[146:149], v229 offset:61440
	ds_read_b128 v[150:153], v229 offset:63488
	s_add_i32 m0, s13, 0x6000
	s_waitcnt lgkmcnt(6)
	v_mfma_f32_32x32x16_bf16 v[114:129], v[182:185], v[154:157], v[114:129]
	global_load_lds_dwordx4 v238, vcc
	v_mfma_f32_32x32x16_bf16 v[98:113], v[178:181], v[154:157], v[98:113]
	global_load_lds_dwordx4 v238, vcc offset:1024
	s_add_i32 m0, s28, 0x8000
	s_add_u32 vcc_lo, vcc_lo, 0x480000
	s_addc_u32 vcc_hi, vcc_hi, 0
	v_mfma_f32_32x32x16_bf16 v[66:81], v[182:185], v[158:161], v[66:81]
	global_load_lds_dwordx4 v239, s[100:101]
	v_mfma_f32_32x32x16_bf16 v[34:49], v[178:181], v[158:161], v[34:49]
	global_load_lds_dwordx4 v239, s[100:101] offset:1024
	v_mfma_f32_32x32x16_bf16 v[82:97], v[174:177], v[154:157], v[82:97]
	global_load_lds_dwordx4 v239, s[100:101] offset:2048
	v_mfma_f32_32x32x16_bf16 v[50:65], v[170:173], v[154:157], v[50:65]
	global_load_lds_dwordx4 v239, s[100:101] offset:3072
	s_add_u32 s100, s100, 0x24000
	s_addc_u32 s101, s101, 0
	v_mfma_f32_32x32x16_bf16 v[18:33], v[174:177], v[158:161], v[18:33]
	v_mfma_f32_32x32x16_bf16 v[2:17], v[170:173], v[158:161], v[2:17]
	s_waitcnt vmcnt(6) lgkmcnt(0)
	s_barrier
; #define LAS __attribute__((address_space(3)))
; DI unsigned pk2(float a, float b) { f32x2 v = {a, b}; bf2_t r = __builtin_convertvector(v, bf2_t); return __builtin_bit_cast(unsigned, r); }
;     ...
;   for (int kt = 0; kt < nk; ++kt) {
;     const int kn = (kt + 2 < nk) ? (kt + 2) : (nk - 1);
;     const LAS char* cur = lds + s0;
;     bf16x8 af[2][2], bfr[2][4];
; #pragma unroll
;     for (int kk = 0; kk < 2; ++kk) {
;       const int xo = kk ? x1 : x0;
;       af[kk][0] = *(const LAS bf16x8*)(cur + a_rd + xo);
;       bfr[kk][0] = *(const LAS bf16x8*)(cur + b_rd + xo);
;       bfr[kk][1] = *(const LAS bf16x8*)(cur + b_rd + 2048 + xo);
;       af[kk][1] = *(const LAS bf16x8*)(cur + a_rd + 2048 + xo);
;       bfr[kk][2] = *(const LAS bf16x8*)(cur + b_rd + 4096 + xo);
;       bfr[kk][3] = *(const LAS bf16x8*)(cur + b_rd + 6144 + xo);
;     }
;     DMA_STEP_(kn, s2);
; #pragma unroll
;     for (int kk = 0; kk < 2; ++kk) {
;       acc[0][0] = mfma32(bfr[kk][0], af[kk][0], acc[0][0]); acc[0][1] = mfma32(bfr[kk][1], af[kk][0], acc[0][1]);
;       acc[1][0] = mfma32(bfr[kk][0], af[kk][1], acc[1][0]); acc[1][1] = mfma32(bfr[kk][1], af[kk][1], acc[1][1]);
;       acc[0][2] = mfma32(bfr[kk][2], af[kk][0], acc[0][2]); acc[0][3] = mfma32(bfr[kk][3], af[kk][0], acc[0][3]);
;       acc[1][2] = mfma32(bfr[kk][2], af[kk][1], acc[1][2]); acc[1][3] = mfma32(bfr[kk][3], af[kk][1], acc[1][3]);
;     }
;     __builtin_amdgcn_sched_group_barrier(0x100, 12, 0);
;     __builtin_amdgcn_sched_group_barrier(0x010, 6, 0);
;     __builtin_amdgcn_sched_group_barrier(0x008, 16, 0);
;     asm volatile("s_waitcnt vmcnt(6) lgkmcnt(0)" ::: "memory");
;     __builtin_amdgcn_s_barrier();
;     asm volatile("" ::: "memory");
;     s0 = (s0 == 2 * STG) ? 0 : s0 + STG;
;     s2 = (s2 == 2 * STG) ? 0 : s2 + STG;
;   }
;   asm volatile("s_waitcnt vmcnt(0)" ::: "memory");
;   __builtin_amdgcn_s_barrier();
;   asm volatile("" ::: "memory");
;     ...
;   {
;     const int h = lane >> 5, cl = lane & 31;
; #pragma unroll
;     for (int i = 0; i < 2; ++i)
; #pragma unroll
;       for (int j = 0; j < 4; ++j)
; #pragma unroll
;         for (int g = 0; g < 4; ++g) {
;           u32x2 w; w.x = pk2(acc[i][j][4 * g], acc[i][j][4 * g + 1]); w.y = pk2(acc[i][j][4 * g + 2], acc[i][j][4 * g + 3]);
;           *(u32x2*)(smem + (wr * 64 + i * 32 + cl) * 528 + (wc * 128 + j * 32 + 8 * g + 4 * h) * 2) = w;
	ds_read_b128 v[154:157], v226 offset:0
	ds_read_b128 v[182:185], v227 offset:8192
	ds_read_b128 v[178:181], v227 offset:10240
	ds_read_b128 v[158:161], v226 offset:2048
	ds_read_b128 v[174:177], v227 offset:12288
	ds_read_b128 v[170:173], v227 offset:14336
	v_mfma_f32_32x32x16_bf16 v[114:129], v[162:165], v[138:141], v[114:129]
	v_mfma_f32_32x32x16_bf16 v[98:113], v[166:169], v[138:141], v[98:113]
	v_mfma_f32_32x32x16_bf16 v[66:81], v[162:165], v[142:145], v[66:81]
	v_mfma_f32_32x32x16_bf16 v[34:49], v[166:169], v[142:145], v[34:49]
	v_mfma_f32_32x32x16_bf16 v[82:97], v[146:149], v[138:141], v[82:97]
	v_mfma_f32_32x32x16_bf16 v[50:65], v[150:153], v[138:141], v[50:65]
	v_mfma_f32_32x32x16_bf16 v[18:33], v[146:149], v[142:145], v[18:33]
	v_mfma_f32_32x32x16_bf16 v[2:17], v[150:153], v[142:145], v[2:17]
	s_add_i32 s29, s29, 6
	s_cmp_lg_u32 s29, 30
	s_cbranch_scc1 .LBB0_235
	ds_read_b128 v[138:141], v228 offset:0
	ds_read_b128 v[162:165], v229 offset:8192
	ds_read_b128 v[166:169], v229 offset:10240
	ds_read_b128 v[142:145], v228 offset:2048
	ds_read_b128 v[146:149], v229 offset:12288
	ds_read_b128 v[150:153], v229 offset:14336
	s_waitcnt lgkmcnt(6)
	v_mfma_f32_32x32x16_bf16 v[114:129], v[182:185], v[154:157], v[114:129]
	v_mfma_f32_32x32x16_bf16 v[98:113], v[178:181], v[154:157], v[98:113]
	v_mfma_f32_32x32x16_bf16 v[66:81], v[182:185], v[158:161], v[66:81]
	v_mfma_f32_32x32x16_bf16 v[34:49], v[178:181], v[158:161], v[34:49]
	v_mfma_f32_32x32x16_bf16 v[82:97], v[174:177], v[154:157], v[82:97]
	v_mfma_f32_32x32x16_bf16 v[50:65], v[170:173], v[154:157], v[50:65]
	v_mfma_f32_32x32x16_bf16 v[18:33], v[174:177], v[158:161], v[18:33]
	v_mfma_f32_32x32x16_bf16 v[2:17], v[170:173], v[158:161], v[2:17]
	s_waitcnt vmcnt(0) lgkmcnt(0)
	s_barrier
	ds_read_b128 v[154:157], v226 offset:24576
	ds_read_b128 v[182:185], v227 offset:32768
	ds_read_b128 v[178:181], v227 offset:34816
	ds_read_b128 v[158:161], v226 offset:26624
	ds_read_b128 v[174:177], v227 offset:36864
	ds_read_b128 v[170:173], v227 offset:38912
	v_mfma_f32_32x32x16_bf16 v[114:129], v[162:165], v[138:141], v[114:129]
	v_mfma_f32_32x32x16_bf16 v[98:113], v[166:169], v[138:141], v[98:113]
	v_mfma_f32_32x32x16_bf16 v[66:81], v[162:165], v[142:145], v[66:81]
	v_mfma_f32_32x32x16_bf16 v[34:49], v[166:169], v[142:145], v[34:49]
	v_mfma_f32_32x32x16_bf16 v[82:97], v[146:149], v[138:141], v[82:97]
	v_mfma_f32_32x32x16_bf16 v[50:65], v[150:153], v[138:141], v[50:65]
	v_mfma_f32_32x32x16_bf16 v[18:33], v[146:149], v[142:145], v[18:33]
	v_mfma_f32_32x32x16_bf16 v[2:17], v[150:153], v[142:145], v[2:17]
	ds_read_b128 v[138:141], v228 offset:24576
	ds_read_b128 v[162:165], v229 offset:32768
	ds_read_b128 v[166:169], v229 offset:34816
	ds_read_b128 v[142:145], v228 offset:26624
	ds_read_b128 v[146:149], v229 offset:36864
	ds_read_b128 v[150:153], v229 offset:38912
	s_waitcnt lgkmcnt(6)
	v_mfma_f32_32x32x16_bf16 v[114:129], v[182:185], v[154:157], v[114:129]
	v_mfma_f32_32x32x16_bf16 v[98:113], v[178:181], v[154:157], v[98:113]
	v_mfma_f32_32x32x16_bf16 v[66:81], v[182:185], v[158:161], v[66:81]
	v_mfma_f32_32x32x16_bf16 v[34:49], v[178:181], v[158:161], v[34:49]
	v_mfma_f32_32x32x16_bf16 v[82:97], v[174:177], v[154:157], v[82:97]
	v_mfma_f32_32x32x16_bf16 v[50:65], v[170:173], v[154:157], v[50:65]
	v_mfma_f32_32x32x16_bf16 v[18:33], v[174:177], v[158:161], v[18:33]
	v_mfma_f32_32x32x16_bf16 v[2:17], v[170:173], v[158:161], v[2:17]
	s_waitcnt lgkmcnt(0)
	v_mfma_f32_32x32x16_bf16 v[114:129], v[162:165], v[138:141], v[114:129]
	v_mfma_f32_32x32x16_bf16 v[98:113], v[166:169], v[138:141], v[98:113]
	v_mfma_f32_32x32x16_bf16 v[66:81], v[162:165], v[142:145], v[66:81]
	v_mfma_f32_32x32x16_bf16 v[34:49], v[166:169], v[142:145], v[34:49]
	v_mfma_f32_32x32x16_bf16 v[82:97], v[146:149], v[138:141], v[82:97]
	v_mfma_f32_32x32x16_bf16 v[50:65], v[150:153], v[138:141], v[50:65]
	v_mfma_f32_32x32x16_bf16 v[18:33], v[146:149], v[142:145], v[18:33]
	v_mfma_f32_32x32x16_bf16 v[2:17], v[150:153], v[142:145], v[2:17]
	s_waitcnt lgkmcnt(0)
	s_mov_b32 s101, 0
	s_setprio 0
	v_mul_lo_u32 v0, v197, s55
	v_add_u32_e32 v0, 16, v0
	s_nop 1
	v_cvt_pk_bf16_f32 v114, v114, v115
	v_cvt_pk_bf16_f32 v115, v116, v117
	v_lshlrev_b32_e32 v116, 3, v196
	s_lshl_b32 s10, s23, 1
	v_add3_u32 v0, v0, v116, s10
	v_cvt_pk_bf16_f32 v116, v118, v119
	v_cvt_pk_bf16_f32 v117, v120, v121
	v_cvt_pk_bf16_f32 v98, v98, v99
	v_cvt_pk_bf16_f32 v99, v100, v101
	v_cvt_pk_bf16_f32 v100, v102, v103
	v_cvt_pk_bf16_f32 v101, v104, v105
	v_cvt_pk_bf16_f32 v82, v82, v83
	v_cvt_pk_bf16_f32 v83, v84, v85
	v_cvt_pk_bf16_f32 v84, v86, v87
	v_cvt_pk_bf16_f32 v85, v88, v89
	v_cvt_pk_bf16_f32 v50, v50, v51
	v_cvt_pk_bf16_f32 v51, v52, v53
	v_cvt_pk_bf16_f32 v52, v54, v55
	v_cvt_pk_bf16_f32 v53, v56, v57
	s_waitcnt vmcnt(0)
	s_barrier
; DI unsigned pk2(float a, float b) { f32x2 v = {a, b}; bf2_t r = __builtin_convertvector(v, bf2_t); return __builtin_bit_cast(unsigned, r); }
;     ...
;   {
;     const int h = lane >> 5, cl = lane & 31;
; #pragma unroll
;     for (int i = 0; i < 2; ++i)
; #pragma unroll
;       for (int j = 0; j < 4; ++j)
; #pragma unroll
;         for (int g = 0; g < 4; ++g) {
;           u32x2 w; w.x = pk2(acc[i][j][4 * g], acc[i][j][4 * g + 1]); w.y = pk2(acc[i][j][4 * g + 2], acc[i][j][4 * g + 3]);
;           *(u32x2*)(smem + (wr * 64 + i * 32 + cl) * 528 + (wc * 128 + j * 32 + 8 * g + 4 * h) * 2) = w;
;         }
;   }
;   __syncthreads();
	ds_write2_b64 v0, v[114:115], v[116:117] offset1:2
	v_cvt_pk_bf16_f32 v114, v122, v123
	v_cvt_pk_bf16_f32 v115, v124, v125
	v_cvt_pk_bf16_f32 v116, v126, v127
	v_cvt_pk_bf16_f32 v117, v128, v129
	ds_write2_b64 v0, v[98:99], v[100:101] offset0:8 offset1:10
	v_cvt_pk_bf16_f32 v98, v106, v107
	v_cvt_pk_bf16_f32 v99, v108, v109
	v_cvt_pk_bf16_f32 v100, v110, v111
	v_cvt_pk_bf16_f32 v101, v112, v113
	ds_write2_b64 v0, v[82:83], v[84:85] offset0:16 offset1:18
	v_cvt_pk_bf16_f32 v82, v90, v91
	v_cvt_pk_bf16_f32 v83, v92, v93
	v_cvt_pk_bf16_f32 v84, v94, v95
	v_cvt_pk_bf16_f32 v85, v96, v97
	ds_write2_b64 v0, v[50:51], v[52:53] offset0:24 offset1:26
	v_cvt_pk_bf16_f32 v50, v58, v59
	v_cvt_pk_bf16_f32 v51, v60, v61
	v_cvt_pk_bf16_f32 v52, v62, v63
	v_cvt_pk_bf16_f32 v53, v64, v65
	ds_write2_b64 v0, v[114:115], v[116:117] offset0:4 offset1:6
	ds_write2_b64 v0, v[98:99], v[100:101] offset0:12 offset1:14
	ds_write2_b64 v0, v[82:83], v[84:85] offset0:20 offset1:22
	ds_write2_b64 v0, v[50:51], v[52:53] offset0:28 offset1:30
	v_cvt_pk_bf16_f32 v50, v66, v67
	v_cvt_pk_bf16_f32 v51, v68, v69
	v_cvt_pk_bf16_f32 v52, v70, v71
	v_cvt_pk_bf16_f32 v53, v72, v73
	v_add_u32_e32 v0, 0x4000, v0
	v_cvt_pk_bf16_f32 v34, v34, v35
	v_cvt_pk_bf16_f32 v35, v36, v37
	v_cvt_pk_bf16_f32 v36, v38, v39
	v_cvt_pk_bf16_f32 v37, v40, v41
	v_cvt_pk_bf16_f32 v18, v18, v19
	v_cvt_pk_bf16_f32 v19, v20, v21
	v_cvt_pk_bf16_f32 v20, v22, v23
	v_cvt_pk_bf16_f32 v21, v24, v25
	v_cvt_pk_bf16_f32 v2, v2, v3
	v_cvt_pk_bf16_f32 v3, v4, v5
	v_cvt_pk_bf16_f32 v4, v6, v7
	v_cvt_pk_bf16_f32 v5, v8, v9
	ds_write2_b64 v0, v[50:51], v[52:53] offset0:64 offset1:66
	v_cvt_pk_bf16_f32 v50, v74, v75
	v_cvt_pk_bf16_f32 v51, v76, v77
	v_cvt_pk_bf16_f32 v52, v78, v79
	v_cvt_pk_bf16_f32 v53, v80, v81
	ds_write2_b64 v0, v[34:35], v[36:37] offset0:72 offset1:74
	v_cvt_pk_bf16_f32 v34, v42, v43
	v_cvt_pk_bf16_f32 v35, v44, v45
	v_cvt_pk_bf16_f32 v36, v46, v47
	v_cvt_pk_bf16_f32 v37, v48, v49
	ds_write2_b64 v0, v[18:19], v[20:21] offset0:80 offset1:82
	v_cvt_pk_bf16_f32 v18, v26, v27
	v_cvt_pk_bf16_f32 v19, v28, v29
	v_cvt_pk_bf16_f32 v20, v30, v31
	v_cvt_pk_bf16_f32 v21, v32, v33
	ds_write2_b64 v0, v[2:3], v[4:5] offset0:88 offset1:90
	v_cvt_pk_bf16_f32 v2, v10, v11
	v_cvt_pk_bf16_f32 v3, v12, v13
	v_cvt_pk_bf16_f32 v4, v14, v15
	v_cvt_pk_bf16_f32 v5, v16, v17
	s_lshl_b64 s[10:11], s[14:15], 1
	ds_write2_b64 v0, v[50:51], v[52:53] offset0:68 offset1:70
	ds_write2_b64 v0, v[34:35], v[36:37] offset0:76 offset1:78
	ds_write2_b64 v0, v[18:19], v[20:21] offset0:84 offset1:86
	ds_write2_b64 v0, v[2:3], v[4:5] offset0:92 offset1:94
	s_waitcnt vmcnt(0) lgkmcnt(0)
	s_barrier
; #define GAS __attribute__((address_space(1)))
;     ...
;   if (EPI == 0) {
; #pragma unroll
;     for (int i = 0; i < 16; ++i) {
;       const int id = tid2 + 256 * i, r = id >> 5, c8 = (id & 31) * 8;
;       const u32x4 v = *(const u32x4*)(smem + r * 528 + c8 * 2);
;       *(GAS u32x4*)(ea.out + (size_t)(m0 + r) * ea.ldo + n0 + c8) = v;
;     }
	s_add_u32 s10, s16, s10
	v_lshlrev_b32_e32 v0, 4, v189
	v_and_b32_e32 v0, 0x1f0, v0
	s_addc_u32 s11, s17, s11
	v_add_u32_e32 v10, 16, v0
	v_lshl_add_u64 v[12:13], s[10:11], 0, v[0:1]
	v_ashrrev_i32_e32 v0, 5, v189
	v_mad_u64_u32 v[2:3], s[10:11], v0, s55, v[10:11]
	v_add_u32_e32 v0, s12, v0
	v_mad_i64_i32 v[14:15], s[10:11], v0, s35, v[12:13]
	v_add_u32_e32 v0, 0x100, v189
	ds_read_b128 v[2:5], v2
	v_ashrrev_i32_e32 v0, 5, v0
	v_mad_u64_u32 v[6:7], s[10:11], v0, s55, v[10:11]
	ds_read_b128 v[6:9], v6
	v_add_u32_e32 v0, s12, v0
	s_waitcnt lgkmcnt(1)
	global_store_dwordx4 v[14:15], v[2:5], off nt
	s_nop 1
	v_mad_i64_i32 v[2:3], s[10:11], v0, s35, v[12:13]
	v_add_u32_e32 v0, 0x200, v189
	v_ashrrev_i32_e32 v0, 5, v0
	s_waitcnt lgkmcnt(0)
	global_store_dwordx4 v[2:3], v[6:9], off nt
	v_mad_u64_u32 v[2:3], s[10:11], v0, s55, v[10:11]
	v_add_u32_e32 v0, s12, v0
	v_mad_i64_i32 v[14:15], s[10:11], v0, s35, v[12:13]
	v_add_u32_e32 v0, 0x300, v189
	ds_read_b128 v[2:5], v2
	v_ashrrev_i32_e32 v0, 5, v0
	v_mad_u64_u32 v[6:7], s[10:11], v0, s55, v[10:11]
	ds_read_b128 v[6:9], v6
	v_add_u32_e32 v0, s12, v0
	s_waitcnt lgkmcnt(1)
	global_store_dwordx4 v[14:15], v[2:5], off nt
	s_nop 1
	v_mad_i64_i32 v[2:3], s[10:11], v0, s35, v[12:13]
	v_add_u32_e32 v0, 0x400, v189
	v_ashrrev_i32_e32 v0, 5, v0
	s_waitcnt lgkmcnt(0)
	global_store_dwordx4 v[2:3], v[6:9], off nt
	v_mad_u64_u32 v[2:3], s[10:11], v0, s55, v[10:11]
	v_add_u32_e32 v0, s12, v0
	v_mad_i64_i32 v[14:15], s[10:11], v0, s35, v[12:13]
	v_add_u32_e32 v0, 0x500, v189
	ds_read_b128 v[2:5], v2
	v_ashrrev_i32_e32 v0, 5, v0
	v_mad_u64_u32 v[6:7], s[10:11], v0, s55, v[10:11]
	ds_read_b128 v[6:9], v6
	v_add_u32_e32 v0, s12, v0
	s_waitcnt lgkmcnt(1)
	global_store_dwordx4 v[14:15], v[2:5], off nt
	s_nop 1
	v_mad_i64_i32 v[2:3], s[10:11], v0, s35, v[12:13]
	v_add_u32_e32 v0, 0x600, v189
	v_ashrrev_i32_e32 v0, 5, v0
	s_waitcnt lgkmcnt(0)
	global_store_dwordx4 v[2:3], v[6:9], off nt
	v_mad_u64_u32 v[2:3], s[10:11], v0, s55, v[10:11]
	v_add_u32_e32 v0, s12, v0
	v_mad_i64_i32 v[14:15], s[10:11], v0, s35, v[12:13]
	v_add_u32_e32 v0, 0x700, v189
	ds_read_b128 v[2:5], v2
	v_ashrrev_i32_e32 v0, 5, v0
	v_mad_u64_u32 v[6:7], s[10:11], v0, s55, v[10:11]
	ds_read_b128 v[6:9], v6
	v_add_u32_e32 v0, s12, v0
	s_waitcnt lgkmcnt(1)
	global_store_dwordx4 v[14:15], v[2:5], off nt
	s_nop 1
	v_mad_i64_i32 v[2:3], s[10:11], v0, s35, v[12:13]
	v_add_u32_e32 v0, 0x800, v189
	v_ashrrev_i32_e32 v0, 5, v0
	s_waitcnt lgkmcnt(0)
	global_store_dwordx4 v[2:3], v[6:9], off nt
	v_mad_u64_u32 v[2:3], s[10:11], v0, s55, v[10:11]
	v_add_u32_e32 v0, s12, v0
	v_mad_i64_i32 v[14:15], s[10:11], v0, s35, v[12:13]
	v_add_u32_e32 v0, 0x900, v189
	ds_read_b128 v[2:5], v2
	v_ashrrev_i32_e32 v0, 5, v0
	v_mad_u64_u32 v[6:7], s[10:11], v0, s55, v[10:11]
	ds_read_b128 v[6:9], v6
	v_add_u32_e32 v0, s12, v0
	s_waitcnt lgkmcnt(1)
	global_store_dwordx4 v[14:15], v[2:5], off nt
	s_nop 1
	v_mad_i64_i32 v[2:3], s[10:11], v0, s35, v[12:13]
	v_add_u32_e32 v0, 0xa00, v189
	v_ashrrev_i32_e32 v0, 5, v0
	s_waitcnt lgkmcnt(0)
	global_store_dwordx4 v[2:3], v[6:9], off nt
	v_mad_u64_u32 v[2:3], s[10:11], v0, s55, v[10:11]
	v_add_u32_e32 v0, s12, v0
	v_mad_i64_i32 v[14:15], s[10:11], v0, s35, v[12:13]
	v_add_u32_e32 v0, 0xb00, v189
	ds_read_b128 v[2:5], v2
	v_ashrrev_i32_e32 v0, 5, v0
	v_mad_u64_u32 v[6:7], s[10:11], v0, s55, v[10:11]
	ds_read_b128 v[6:9], v6
	v_add_u32_e32 v0, s12, v0
	s_waitcnt lgkmcnt(1)
	global_store_dwordx4 v[14:15], v[2:5], off nt
	s_nop 1
	v_mad_i64_i32 v[2:3], s[10:11], v0, s35, v[12:13]
	v_add_u32_e32 v0, 0xc00, v189
	v_ashrrev_i32_e32 v0, 5, v0
	s_waitcnt lgkmcnt(0)
	global_store_dwordx4 v[2:3], v[6:9], off nt
	v_mad_u64_u32 v[2:3], s[10:11], v0, s55, v[10:11]
	v_add_u32_e32 v0, s12, v0
	v_mad_i64_i32 v[14:15], s[10:11], v0, s35, v[12:13]
	v_add_u32_e32 v0, 0xd00, v189
	ds_read_b128 v[2:5], v2
	v_ashrrev_i32_e32 v0, 5, v0
	v_mad_u64_u32 v[6:7], s[10:11], v0, s55, v[10:11]
	ds_read_b128 v[6:9], v6
	v_add_u32_e32 v0, s12, v0
	s_waitcnt lgkmcnt(1)
	global_store_dwordx4 v[14:15], v[2:5], off nt
	s_nop 1
	v_mad_i64_i32 v[2:3], s[10:11], v0, s35, v[12:13]
	v_add_u32_e32 v0, 0xe00, v189
	v_ashrrev_i32_e32 v0, 5, v0
	s_waitcnt lgkmcnt(0)
	global_store_dwordx4 v[2:3], v[6:9], off nt
	v_mad_u64_u32 v[2:3], s[10:11], v0, s55, v[10:11]
	ds_read_b128 v[2:5], v2
	v_add_u32_e32 v0, s12, v0
	v_mad_i64_i32 v[14:15], s[10:11], v0, s35, v[12:13]
	v_add_u32_e32 v0, 0xf00, v189
	v_ashrrev_i32_e32 v0, 5, v0
	v_mad_u64_u32 v[6:7], s[10:11], v0, s55, v[10:11]
	ds_read_b128 v[6:9], v6
	v_add_u32_e32 v0, s12, v0
	s_waitcnt lgkmcnt(1)
	global_store_dwordx4 v[14:15], v[2:5], off nt
	s_nop 1
	v_mad_i64_i32 v[2:3], s[10:11], v0, s35, v[12:13]
	v_readlane_b32 s10, v252, 12
	s_add_i32 s22, s22, s10
	v_readlane_b32 s10, v252, 38
	s_cmp_ge_i32 s22, s10
	s_waitcnt lgkmcnt(0)
	global_store_dwordx4 v[2:3], v[6:9], off nt
	s_barrier
	s_cbranch_scc0 .LBB0_230

; #define LAS __attribute__((address_space(3)))
;     ...
;   const int lane = tid & 63, wid = __builtin_amdgcn_readfirstlane(tid >> 6), wr = wid >> 1, wc = wid & 1;
;   const int m0 = mt * 128, n0 = nt * 256;
;   const int r = lane & 31, h = lane >> 5, key = (r >> 2) & 3;
;   constexpr int STG = 24576;
;   const int rowl = lane >> 2, cch = (lane & 3) ^ ((lane >> 4) & 3);
;   const unsigned voffA = (unsigned)(rowl * lda * 2 + cch * 16), voffB = (unsigned)(rowl * K * 2 + cch * 16);
;   const char* Abase = (const char*)(A + (size_t)m0 * lda) + (size_t)(wid * 2) * 32 * lda;
;   const char* Bbase = (const char*)(Bt + (size_t)n0 * K) + (size_t)(wid * 4) * 32 * K;
;   const size_t ablk = (size_t)32 * lda, bblk = (size_t)32 * K;
;   LAS char* lds = (LAS char*)smem;
;   LAS char* ldsA = lds + (wid * 2) * 1024;
;   LAS char* ldsB = lds + 8192 + (wid * 4) * 1024;
;     ...
;   const int x0 = ((0 + h) ^ key) * 16, x1 = ((2 + h) ^ key) * 16;
;   const int a_rd = (wr * 64 + r) * 64, b_rd = 8192 + (wc * 128 + r) * 64;
;   f32x16 acc[2][4];
; #pragma unroll
;   for (int i = 0; i < 2; ++i)
; #pragma unroll
;     for (int j = 0; j < 4; ++j)
; #pragma unroll
;       for (int e = 0; e < 16; ++e) acc[i][j][e] = 0.f;
;   const int nk = K >> 5;
;   DMA_STEP_(0, 0);
;   DMA_STEP_(1, STG);
;   asm volatile("s_waitcnt vmcnt(6)" ::: "memory");
;   __builtin_amdgcn_s_barrier();
;   asm volatile("" ::: "memory");
;   int s0 = 0, s2 = 2 * STG;
.LBB0_271:
	s_mul_hi_i32 s10, s14, 0x2e8ba2e9
	s_lshr_b32 s11, s10, 31
	s_ashr_i32 s10, s10, 4
	s_add_i32 s10, s10, s11
	v_readlane_b32 s15, v252, 18
	s_mul_i32 s11, s10, 0xffffffa8
	s_lshl_b32 s10, s10, s15
	v_readlane_b32 s15, v252, 41
	s_add_i32 s10, s10, s15
	s_lshr_b32 s15, s10, 31
	s_add_i32 s15, s10, s15
	s_and_b32 s18, s15, -2
	s_add_i32 s11, s11, s14
	s_sub_i32 s10, s10, s18
	s_mul_i32 s22, s10, 11
	s_ashr_i32 s10, s11, 3
	v_mov_b32_e32 v189, v188
	s_lshl_b32 s15, s15, 2
	s_add_i32 s22, s22, s10
	s_and_b32 s15, s15, -8
	v_readfirstlane_b32 s10, v189
	s_and_b32 s18, s14, 7
	s_ashr_i32 s11, s10, 6
	s_or_b32 s15, s15, s18
	s_lshl_b32 s18, s11, 1
	s_ashr_i32 s19, s18, 31
	s_lshl_b64 s[28:29], s[18:19], 10
	s_lshl_b32 s18, s11, 2
	s_ashr_i32 s19, s18, 31
	s_ashr_i32 s10, s10, 1
	s_lshl_b32 s46, s15, 7
	s_lshl_b32 s66, s22, 8
	v_and_b32_e32 v0, 31, v189
	s_lshl_b64 s[74:75], s[18:19], 10
	s_lshl_b32 s18, s11, 12
	s_andn2_b32 s10, s10, 63
	v_lshlrev_b32_e32 v3, 4, v189
	s_ashr_i32 s47, s46, 31
	s_ashr_i32 s67, s66, 31
	s_add_i32 s19, s18, 16
	v_or_b32_e32 v197, s10, v0
	s_lshl_b32 s10, s11, 7
	v_lshlrev_b32_e32 v2, 9, v189
	v_bitop3_b32 v3, v3, 48, v189 bitop3:0x48
	s_lshl_b64 s[20:21], s[46:47], 6
	s_lshl_b64 s[40:41], s[66:67], 6
	s_add_i32 s23, s19, 0x2000
	s_and_b32 s18, s10, 0x80
	s_movk_i32 s10, 0x7800
	v_or_b32_e32 v4, s18, v0
	v_and_or_b32 v0, v2, s10, v3
	v_lshlrev_b32_e32 v10, 4, v189
	v_and_b32_e32 v10, 0x3c0, v10
	v_or_b32_e32 v10, v10, v3
	v_mov_b32_e32 v11, 0
	s_add_u32 s10, s42, s20
	s_addc_u32 s20, s43, s21
	s_add_u32 s28, s10, s28
	s_addc_u32 s29, s20, s29
	s_add_u32 s10, s87, s40
	s_addc_u32 s21, s76, s41
	s_lshl_b32 s11, s11, 11
	s_sub_i32 s20, s19, s11
	s_mov_b32 m0, s20
	v_lshl_add_u64 v[192:193], s[28:29], 0, v[10:11]
	global_load_lds_dwordx4 v[192:193], off
	global_load_lds_dwordx4 v[192:193], off offset:1024
	s_add_u32 s28, s10, s74
	s_addc_u32 s29, s21, s75
	v_lshl_add_u64 v[194:195], s[28:29], 0, v[10:11]
	s_mov_b32 m0, s23
	s_nop 0
	global_load_lds_dwordx4 v[194:195], off
	global_load_lds_dwordx4 v[194:195], off offset:1024
	global_load_lds_dwordx4 v[194:195], off offset:2048
	global_load_lds_dwordx4 v[194:195], off offset:3072
	s_mov_b64 s[10:11], 0x10000
	s_mov_b64 s[10:11], 0x18000
	s_mov_b64 s[10:11], 0x8040
	s_add_i32 m0, s20, 0x6000
	s_mov_b32 vcc_lo, 0x480000
	s_mov_b32 vcc_hi, 0
	v_lshl_add_u64 v[2:3], v[192:193], 0, vcc
	global_load_lds_dwordx4 v[2:3], off
	global_load_lds_dwordx4 v[2:3], off offset:1024
	v_lshrrev_b32_e32 v5, 5, v189
	s_add_i32 m0, s19, 0x8000
	s_mov_b32 s100, 0x58000
	v_lshl_add_u64 v[2:3], v[194:195], 0, s[100:101]
	global_load_lds_dwordx4 v[2:3], off
	global_load_lds_dwordx4 v[2:3], off offset:1024
	global_load_lds_dwordx4 v[2:3], off offset:2048
	global_load_lds_dwordx4 v[2:3], off offset:3072
	s_mov_b64 s[10:11], 0x10040
	s_mov_b64 s[10:11], 0x18040
	v_bfe_u32 v6, v189, 2, 2
	v_bfe_u32 v196, v189, 5, 1
	s_lshl_b32 s100, s100, 1
	v_lshl_add_u64 v[194:195], v[194:195], 0, s[100:101]
	s_lshl_b32 vcc_lo, vcc_lo, 1
	v_lshl_add_u64 v[192:193], v[192:193], 0, vcc
	s_waitcnt vmcnt(6)
	s_barrier
	v_bitop3_b32 v2, v5, v6, 1 bitop3:0x6c
	v_lshlrev_b32_e32 v219, 4, v2
	v_bitop3_b32 v2, v196, v6, 2 bitop3:0x36
	v_mov_b32_e32 v66, 0
	v_lshlrev_b32_e32 v218, 6, v197
	v_lshlrev_b32_e32 v0, 6, v4
	v_lshlrev_b32_e32 v220, 4, v2
	s_mov_b32 s23, 0xc000
	s_mov_b32 s28, 0
	s_mov_b32 s21, 0
	v_mov_b32_e32 v67, v66
	v_mov_b32_e32 v68, v66
	v_mov_b32_e32 v69, v66
	v_mov_b32_e32 v70, v66
	v_mov_b32_e32 v71, v66
	v_mov_b32_e32 v72, v66
	v_mov_b32_e32 v73, v66
	v_mov_b32_e32 v74, v66
	v_mov_b32_e32 v75, v66
	v_mov_b32_e32 v76, v66
	v_mov_b32_e32 v77, v66
	v_mov_b32_e32 v78, v66
	v_mov_b32_e32 v79, v66
	v_mov_b32_e32 v80, v66
	v_mov_b32_e32 v81, v66
	v_mov_b32_e32 v82, v66
	v_mov_b32_e32 v83, v66
	v_mov_b32_e32 v84, v66
	v_mov_b32_e32 v85, v66
	v_mov_b32_e32 v86, v66
	v_mov_b32_e32 v87, v66
	v_mov_b32_e32 v88, v66
	v_mov_b32_e32 v89, v66
	s_waitcnt vmcnt(0)
	v_mov_b32_e32 v90, v66
	v_mov_b32_e32 v91, v66
	v_mov_b32_e32 v92, v66
	v_mov_b32_e32 v93, v66
	v_mov_b32_e32 v94, v66
	v_mov_b32_e32 v95, v66
	v_mov_b32_e32 v96, v66
	v_mov_b32_e32 v97, v66
	v_mov_b32_e32 v18, v66
	v_mov_b32_e32 v19, v66
	v_mov_b32_e32 v20, v66
	v_mov_b32_e32 v21, v66
	v_mov_b32_e32 v22, v66
	v_mov_b32_e32 v23, v66
	v_mov_b32_e32 v24, v66
	v_mov_b32_e32 v25, v66
	v_mov_b32_e32 v26, v66
	v_mov_b32_e32 v27, v66
	v_mov_b32_e32 v28, v66
	v_mov_b32_e32 v29, v66
	v_mov_b32_e32 v30, v66
	v_mov_b32_e32 v31, v66
	v_mov_b32_e32 v32, v66
	v_mov_b32_e32 v33, v66
	v_mov_b32_e32 v2, v66
	v_mov_b32_e32 v3, v66
	v_mov_b32_e32 v4, v66
	v_mov_b32_e32 v5, v66
	v_mov_b32_e32 v6, v66
	v_mov_b32_e32 v7, v66
	v_mov_b32_e32 v8, v66
	v_mov_b32_e32 v9, v66
	v_mov_b32_e32 v10, v66
	v_mov_b32_e32 v11, v66
	v_mov_b32_e32 v12, v66
	v_mov_b32_e32 v13, v66
	v_mov_b32_e32 v14, v66
	v_mov_b32_e32 v15, v66
	v_mov_b32_e32 v16, v66
	v_mov_b32_e32 v17, v66
	v_mov_b32_e32 v114, v66
	v_mov_b32_e32 v115, v66
	v_mov_b32_e32 v116, v66
	v_mov_b32_e32 v117, v66
	v_mov_b32_e32 v118, v66
	v_mov_b32_e32 v119, v66
	v_mov_b32_e32 v120, v66
	v_mov_b32_e32 v121, v66
	v_mov_b32_e32 v122, v66
	v_mov_b32_e32 v123, v66
	v_mov_b32_e32 v124, v66
	v_mov_b32_e32 v125, v66
	v_mov_b32_e32 v126, v66
	v_mov_b32_e32 v127, v66
	v_mov_b32_e32 v128, v66
	v_mov_b32_e32 v129, v66
	v_mov_b32_e32 v98, v66
	v_mov_b32_e32 v99, v66
	v_mov_b32_e32 v100, v66
	v_mov_b32_e32 v101, v66
	v_mov_b32_e32 v102, v66
	v_mov_b32_e32 v103, v66
	v_mov_b32_e32 v104, v66
	v_mov_b32_e32 v105, v66
	v_mov_b32_e32 v106, v66
	v_mov_b32_e32 v107, v66
	v_mov_b32_e32 v108, v66
	v_mov_b32_e32 v109, v66
	v_mov_b32_e32 v110, v66
; #define LAS __attribute__((address_space(3)))
; DI f32x16 mfma32(bf16x8 a, bf16x8 b, f32x16 c) { return __builtin_amdgcn_mfma_f32_32x32x16_bf16(a, b, c, 0, 0, 0); }
;     ...
;   f32x16 acc[2][4];
; #pragma unroll
;   for (int i = 0; i < 2; ++i)
; #pragma unroll
;     for (int j = 0; j < 4; ++j)
; #pragma unroll
;       for (int e = 0; e < 16; ++e) acc[i][j][e] = 0.f;
;   const int nk = K >> 5;
;   DMA_STEP_(0, 0);
;   DMA_STEP_(1, STG);
;   asm volatile("s_waitcnt vmcnt(6)" ::: "memory");
;   __builtin_amdgcn_s_barrier();
;   asm volatile("" ::: "memory");
;   int s0 = 0, s2 = 2 * STG;
;   for (int kt = 0; kt < nk; ++kt) {
;     const int kn = (kt + 2 < nk) ? (kt + 2) : (nk - 1);
;     const LAS char* cur = lds + s0;
;     bf16x8 af[2][2], bfr[2][4];
; #pragma unroll
;     for (int kk = 0; kk < 2; ++kk) {
;       const int xo = kk ? x1 : x0;
;       af[kk][0] = *(const LAS bf16x8*)(cur + a_rd + xo);
;       bfr[kk][0] = *(const LAS bf16x8*)(cur + b_rd + xo);
;       bfr[kk][1] = *(const LAS bf16x8*)(cur + b_rd + 2048 + xo);
;       af[kk][1] = *(const LAS bf16x8*)(cur + a_rd + 2048 + xo);
;       bfr[kk][2] = *(const LAS bf16x8*)(cur + b_rd + 4096 + xo);
;       bfr[kk][3] = *(const LAS bf16x8*)(cur + b_rd + 6144 + xo);
;     }
;     DMA_STEP_(kn, s2);
; #pragma unroll
;     for (int kk = 0; kk < 2; ++kk) {
;       acc[0][0] = mfma32(bfr[kk][0], af[kk][0], acc[0][0]); acc[0][1] = mfma32(bfr[kk][1], af[kk][0], acc[0][1]);
;       acc[1][0] = mfma32(bfr[kk][0], af[kk][1], acc[1][0]); acc[1][1] = mfma32(bfr[kk][1], af[kk][1], acc[1][1]);
;       acc[0][2] = mfma32(bfr[kk][2], af[kk][0], acc[0][2]); acc[0][3] = mfma32(bfr[kk][3], af[kk][0], acc[0][3]);
;       acc[1][2] = mfma32(bfr[kk][2], af[kk][1], acc[1][2]); acc[1][3] = mfma32(bfr[kk][3], af[kk][1], acc[1][3]);
;     }
;     __builtin_amdgcn_sched_group_barrier(0x100, 12, 0);
;     __builtin_amdgcn_sched_group_barrier(0x010, 6, 0);
;     __builtin_amdgcn_sched_group_barrier(0x008, 16, 0);
;     asm volatile("s_waitcnt vmcnt(6) lgkmcnt(0)" ::: "memory");
;     __builtin_amdgcn_s_barrier();
;     asm volatile("" ::: "memory");
;     s0 = (s0 == 2 * STG) ? 0 : s0 + STG;
;     s2 = (s2 == 2 * STG) ? 0 : s2 + STG;
;   }
	v_mov_b32_e32 v111, v66
	v_mov_b32_e32 v112, v66
	v_mov_b32_e32 v113, v66
	v_mov_b32_e32 v50, v66
	v_mov_b32_e32 v51, v66
	v_mov_b32_e32 v52, v66
	v_mov_b32_e32 v53, v66
	v_mov_b32_e32 v54, v66
	v_mov_b32_e32 v55, v66
	v_mov_b32_e32 v56, v66
	v_mov_b32_e32 v57, v66
	v_mov_b32_e32 v58, v66
	v_mov_b32_e32 v59, v66
	v_mov_b32_e32 v60, v66
	v_mov_b32_e32 v61, v66
	v_mov_b32_e32 v62, v66
	v_mov_b32_e32 v63, v66
	v_mov_b32_e32 v64, v66
	v_mov_b32_e32 v65, v66
	v_mov_b32_e32 v34, v66
	v_mov_b32_e32 v35, v66
	v_mov_b32_e32 v36, v66
	v_mov_b32_e32 v37, v66
	v_mov_b32_e32 v38, v66
	v_mov_b32_e32 v39, v66
	v_mov_b32_e32 v40, v66
	v_mov_b32_e32 v41, v66
	v_mov_b32_e32 v42, v66
	v_mov_b32_e32 v43, v66
	v_mov_b32_e32 v44, v66
	v_mov_b32_e32 v45, v66
	v_mov_b32_e32 v46, v66
	v_mov_b32_e32 v47, v66
	v_mov_b32_e32 v48, v66
	v_mov_b32_e32 v49, v66
	v_readfirstlane_b32 vcc_lo, v192
	v_readfirstlane_b32 vcc_hi, v193
	v_readfirstlane_b32 s100, v194
	v_readfirstlane_b32 s101, v195
	s_sub_u32 vcc_lo, vcc_lo, 0x100000
	s_subb_u32 vcc_hi, vcc_hi, 0
	s_sub_u32 s100, s100, 0x100000
	s_subb_u32 s101, s101, 0
	v_subrev_u32_e32 v238, vcc_lo, v192
	v_subrev_u32_e32 v239, s100, v194
	v_add3_u32 v226, v218, v219, 16
	v_add3_u32 v227, v0, v219, 16
	v_add3_u32 v228, v218, v220, 16
	v_add3_u32 v229, v0, v220, 16
	ds_read_b128 v[154:157], v226 offset:0
	ds_read_b128 v[182:185], v227 offset:8192
	ds_read_b128 v[178:181], v227 offset:10240
	ds_read_b128 v[158:161], v226 offset:2048
	ds_read_b128 v[174:177], v227 offset:12288
	ds_read_b128 v[170:173], v227 offset:14336
	s_setprio 1
.LBB0_272:
	ds_read_b128 v[138:141], v228 offset:0
	ds_read_b128 v[162:165], v229 offset:8192
	ds_read_b128 v[166:169], v229 offset:10240
	ds_read_b128 v[142:145], v228 offset:2048
	ds_read_b128 v[146:149], v229 offset:12288
	ds_read_b128 v[150:153], v229 offset:14336
	s_add_i32 m0, s20, 0xc000
	s_waitcnt lgkmcnt(6)
	v_mfma_f32_32x32x16_bf16 v[66:81], v[182:185], v[154:157], v[66:81]
	global_load_lds_dwordx4 v238, vcc
	v_mfma_f32_32x32x16_bf16 v[82:97], v[178:181], v[154:157], v[82:97]
	global_load_lds_dwordx4 v238, vcc offset:1024
	s_add_i32 m0, s19, 0xe000
	s_add_u32 vcc_lo, vcc_lo, 0x480000
	s_addc_u32 vcc_hi, vcc_hi, 0
	v_mfma_f32_32x32x16_bf16 v[18:33], v[182:185], v[158:161], v[18:33]
	global_load_lds_dwordx4 v239, s[100:101]
	v_mfma_f32_32x32x16_bf16 v[2:17], v[178:181], v[158:161], v[2:17]
	global_load_lds_dwordx4 v239, s[100:101] offset:1024
	v_mfma_f32_32x32x16_bf16 v[114:129], v[174:177], v[154:157], v[114:129]
	global_load_lds_dwordx4 v239, s[100:101] offset:2048
	v_mfma_f32_32x32x16_bf16 v[98:113], v[170:173], v[154:157], v[98:113]
	global_load_lds_dwordx4 v239, s[100:101] offset:3072
	s_add_u32 s100, s100, 0x58000
	s_addc_u32 s101, s101, 0
	v_mfma_f32_32x32x16_bf16 v[50:65], v[174:177], v[158:161], v[50:65]
	v_mfma_f32_32x32x16_bf16 v[34:49], v[170:173], v[158:161], v[34:49]
	s_waitcnt vmcnt(6) lgkmcnt(0)
	s_barrier
	ds_read_b128 v[154:157], v226 offset:24576
	ds_read_b128 v[182:185], v227 offset:32768
	ds_read_b128 v[178:181], v227 offset:34816
	ds_read_b128 v[158:161], v226 offset:26624
	ds_read_b128 v[174:177], v227 offset:36864
	ds_read_b128 v[170:173], v227 offset:38912
	v_mfma_f32_32x32x16_bf16 v[66:81], v[162:165], v[138:141], v[66:81]
	v_mfma_f32_32x32x16_bf16 v[82:97], v[166:169], v[138:141], v[82:97]
	v_mfma_f32_32x32x16_bf16 v[18:33], v[162:165], v[142:145], v[18:33]
	v_mfma_f32_32x32x16_bf16 v[2:17], v[166:169], v[142:145], v[2:17]
	v_mfma_f32_32x32x16_bf16 v[114:129], v[146:149], v[138:141], v[114:129]
	v_mfma_f32_32x32x16_bf16 v[98:113], v[150:153], v[138:141], v[98:113]
	v_mfma_f32_32x32x16_bf16 v[50:65], v[146:149], v[142:145], v[50:65]
	v_mfma_f32_32x32x16_bf16 v[34:49], v[150:153], v[142:145], v[34:49]
	ds_read_b128 v[138:141], v228 offset:24576
	ds_read_b128 v[162:165], v229 offset:32768
	ds_read_b128 v[166:169], v229 offset:34816
	ds_read_b128 v[142:145], v228 offset:26624
	ds_read_b128 v[146:149], v229 offset:36864
	ds_read_b128 v[150:153], v229 offset:38912
	s_add_i32 m0, s20, 0x0
	s_waitcnt lgkmcnt(6)
	v_mfma_f32_32x32x16_bf16 v[66:81], v[182:185], v[154:157], v[66:81]
	global_load_lds_dwordx4 v238, vcc
	v_mfma_f32_32x32x16_bf16 v[82:97], v[178:181], v[154:157], v[82:97]
	global_load_lds_dwordx4 v238, vcc offset:1024
	s_add_i32 m0, s19, 0x2000
	s_add_u32 vcc_lo, vcc_lo, 0x480000
	s_addc_u32 vcc_hi, vcc_hi, 0
	v_mfma_f32_32x32x16_bf16 v[18:33], v[182:185], v[158:161], v[18:33]
	global_load_lds_dwordx4 v239, s[100:101]
	v_mfma_f32_32x32x16_bf16 v[2:17], v[178:181], v[158:161], v[2:17]
	global_load_lds_dwordx4 v239, s[100:101] offset:1024
	v_mfma_f32_32x32x16_bf16 v[114:129], v[174:177], v[154:157], v[114:129]
	global_load_lds_dwordx4 v239, s[100:101] offset:2048
	v_mfma_f32_32x32x16_bf16 v[98:113], v[170:173], v[154:157], v[98:113]
	global_load_lds_dwordx4 v239, s[100:101] offset:3072
	s_add_u32 s100, s100, 0x58000
	s_addc_u32 s101, s101, 0
	v_mfma_f32_32x32x16_bf16 v[50:65], v[174:177], v[158:161], v[50:65]
	v_mfma_f32_32x32x16_bf16 v[34:49], v[170:173], v[158:161], v[34:49]
	s_waitcnt vmcnt(6) lgkmcnt(0)
	s_barrier
; #define LAS __attribute__((address_space(3)))
; DI f32x16 mfma32(bf16x8 a, bf16x8 b, f32x16 c) { return __builtin_amdgcn_mfma_f32_32x32x16_bf16(a, b, c, 0, 0, 0); }
;     ...
;   for (int kt = 0; kt < nk; ++kt) {
;     const int kn = (kt + 2 < nk) ? (kt + 2) : (nk - 1);
;     const LAS char* cur = lds + s0;
;     bf16x8 af[2][2], bfr[2][4];
; #pragma unroll
;     for (int kk = 0; kk < 2; ++kk) {
;       const int xo = kk ? x1 : x0;
;       af[kk][0] = *(const LAS bf16x8*)(cur + a_rd + xo);
;       bfr[kk][0] = *(const LAS bf16x8*)(cur + b_rd + xo);
;       bfr[kk][1] = *(const LAS bf16x8*)(cur + b_rd + 2048 + xo);
;       af[kk][1] = *(const LAS bf16x8*)(cur + a_rd + 2048 + xo);
;       bfr[kk][2] = *(const LAS bf16x8*)(cur + b_rd + 4096 + xo);
;       bfr[kk][3] = *(const LAS bf16x8*)(cur + b_rd + 6144 + xo);
;     }
;     DMA_STEP_(kn, s2);
; #pragma unroll
;     for (int kk = 0; kk < 2; ++kk) {
;       acc[0][0] = mfma32(bfr[kk][0], af[kk][0], acc[0][0]); acc[0][1] = mfma32(bfr[kk][1], af[kk][0], acc[0][1]);
;       acc[1][0] = mfma32(bfr[kk][0], af[kk][1], acc[1][0]); acc[1][1] = mfma32(bfr[kk][1], af[kk][1], acc[1][1]);
;       acc[0][2] = mfma32(bfr[kk][2], af[kk][0], acc[0][2]); acc[0][3] = mfma32(bfr[kk][3], af[kk][0], acc[0][3]);
;       acc[1][2] = mfma32(bfr[kk][2], af[kk][1], acc[1][2]); acc[1][3] = mfma32(bfr[kk][3], af[kk][1], acc[1][3]);
;     }
;     __builtin_amdgcn_sched_group_barrier(0x100, 12, 0);
;     __builtin_amdgcn_sched_group_barrier(0x010, 6, 0);
;     __builtin_amdgcn_sched_group_barrier(0x008, 16, 0);
;     asm volatile("s_waitcnt vmcnt(6) lgkmcnt(0)" ::: "memory");
;     __builtin_amdgcn_s_barrier();
;     asm volatile("" ::: "memory");
;     s0 = (s0 == 2 * STG) ? 0 : s0 + STG;
;     s2 = (s2 == 2 * STG) ? 0 : s2 + STG;
;   }
	ds_read_b128 v[154:157], v226 offset:49152
	ds_read_b128 v[182:185], v227 offset:57344
	ds_read_b128 v[178:181], v227 offset:59392
	ds_read_b128 v[158:161], v226 offset:51200
	ds_read_b128 v[174:177], v227 offset:61440
	ds_read_b128 v[170:173], v227 offset:63488
	v_mfma_f32_32x32x16_bf16 v[66:81], v[162:165], v[138:141], v[66:81]
	v_mfma_f32_32x32x16_bf16 v[82:97], v[166:169], v[138:141], v[82:97]
	v_mfma_f32_32x32x16_bf16 v[18:33], v[162:165], v[142:145], v[18:33]
	v_mfma_f32_32x32x16_bf16 v[2:17], v[166:169], v[142:145], v[2:17]
	v_mfma_f32_32x32x16_bf16 v[114:129], v[146:149], v[138:141], v[114:129]
	v_mfma_f32_32x32x16_bf16 v[98:113], v[150:153], v[138:141], v[98:113]
	v_mfma_f32_32x32x16_bf16 v[50:65], v[146:149], v[142:145], v[50:65]
	v_mfma_f32_32x32x16_bf16 v[34:49], v[150:153], v[142:145], v[34:49]
	ds_read_b128 v[138:141], v228 offset:49152
	ds_read_b128 v[162:165], v229 offset:57344
	ds_read_b128 v[166:169], v229 offset:59392
	ds_read_b128 v[142:145], v228 offset:51200
	ds_read_b128 v[146:149], v229 offset:61440
	ds_read_b128 v[150:153], v229 offset:63488
	s_add_i32 m0, s20, 0x6000
	s_waitcnt lgkmcnt(6)
	v_mfma_f32_32x32x16_bf16 v[66:81], v[182:185], v[154:157], v[66:81]
	global_load_lds_dwordx4 v238, vcc
	v_mfma_f32_32x32x16_bf16 v[82:97], v[178:181], v[154:157], v[82:97]
	global_load_lds_dwordx4 v238, vcc offset:1024
	s_add_i32 m0, s19, 0x8000
	s_add_u32 vcc_lo, vcc_lo, 0x480000
	s_addc_u32 vcc_hi, vcc_hi, 0
	v_mfma_f32_32x32x16_bf16 v[18:33], v[182:185], v[158:161], v[18:33]
	global_load_lds_dwordx4 v239, s[100:101]
	v_mfma_f32_32x32x16_bf16 v[2:17], v[178:181], v[158:161], v[2:17]
	global_load_lds_dwordx4 v239, s[100:101] offset:1024
	v_mfma_f32_32x32x16_bf16 v[114:129], v[174:177], v[154:157], v[114:129]
	global_load_lds_dwordx4 v239, s[100:101] offset:2048
	v_mfma_f32_32x32x16_bf16 v[98:113], v[170:173], v[154:157], v[98:113]
	global_load_lds_dwordx4 v239, s[100:101] offset:3072
	s_add_u32 s100, s100, 0x58000
	s_addc_u32 s101, s101, 0
	v_mfma_f32_32x32x16_bf16 v[50:65], v[174:177], v[158:161], v[50:65]
	v_mfma_f32_32x32x16_bf16 v[34:49], v[170:173], v[158:161], v[34:49]
	s_waitcnt vmcnt(6) lgkmcnt(0)
	s_barrier
	ds_read_b128 v[154:157], v226 offset:0
	ds_read_b128 v[182:185], v227 offset:8192
	ds_read_b128 v[178:181], v227 offset:10240
	ds_read_b128 v[158:161], v226 offset:2048
	ds_read_b128 v[174:177], v227 offset:12288
	ds_read_b128 v[170:173], v227 offset:14336
	v_mfma_f32_32x32x16_bf16 v[66:81], v[162:165], v[138:141], v[66:81]
	v_mfma_f32_32x32x16_bf16 v[82:97], v[166:169], v[138:141], v[82:97]
	v_mfma_f32_32x32x16_bf16 v[18:33], v[162:165], v[142:145], v[18:33]
	v_mfma_f32_32x32x16_bf16 v[2:17], v[166:169], v[142:145], v[2:17]
	v_mfma_f32_32x32x16_bf16 v[114:129], v[146:149], v[138:141], v[114:129]
	v_mfma_f32_32x32x16_bf16 v[98:113], v[150:153], v[138:141], v[98:113]
	v_mfma_f32_32x32x16_bf16 v[50:65], v[146:149], v[142:145], v[50:65]
	v_mfma_f32_32x32x16_bf16 v[34:49], v[150:153], v[142:145], v[34:49]
	ds_read_b128 v[138:141], v228 offset:0
	ds_read_b128 v[162:165], v229 offset:8192
	ds_read_b128 v[166:169], v229 offset:10240
	ds_read_b128 v[142:145], v228 offset:2048
	ds_read_b128 v[146:149], v229 offset:12288
	ds_read_b128 v[150:153], v229 offset:14336
	s_add_i32 m0, s20, 0xc000
	s_waitcnt lgkmcnt(6)
	v_mfma_f32_32x32x16_bf16 v[66:81], v[182:185], v[154:157], v[66:81]
	global_load_lds_dwordx4 v238, vcc
	v_mfma_f32_32x32x16_bf16 v[82:97], v[178:181], v[154:157], v[82:97]
	global_load_lds_dwordx4 v238, vcc offset:1024
	s_add_i32 m0, s19, 0xe000
	s_add_u32 vcc_lo, vcc_lo, 0x480000
	s_addc_u32 vcc_hi, vcc_hi, 0
	v_mfma_f32_32x32x16_bf16 v[18:33], v[182:185], v[158:161], v[18:33]
	global_load_lds_dwordx4 v239, s[100:101]
	v_mfma_f32_32x32x16_bf16 v[2:17], v[178:181], v[158:161], v[2:17]
	global_load_lds_dwordx4 v239, s[100:101] offset:1024
	v_mfma_f32_32x32x16_bf16 v[114:129], v[174:177], v[154:157], v[114:129]
	global_load_lds_dwordx4 v239, s[100:101] offset:2048
	v_mfma_f32_32x32x16_bf16 v[98:113], v[170:173], v[154:157], v[98:113]
	global_load_lds_dwordx4 v239, s[100:101] offset:3072
	s_add_u32 s100, s100, 0x58000
	s_addc_u32 s101, s101, 0
	v_mfma_f32_32x32x16_bf16 v[50:65], v[174:177], v[158:161], v[50:65]
	v_mfma_f32_32x32x16_bf16 v[34:49], v[170:173], v[158:161], v[34:49]
	s_waitcnt vmcnt(6) lgkmcnt(0)
	s_barrier
	ds_read_b128 v[154:157], v226 offset:24576
	ds_read_b128 v[182:185], v227 offset:32768
	ds_read_b128 v[178:181], v227 offset:34816
	ds_read_b128 v[158:161], v226 offset:26624
	ds_read_b128 v[174:177], v227 offset:36864
	ds_read_b128 v[170:173], v227 offset:38912
	v_mfma_f32_32x32x16_bf16 v[66:81], v[162:165], v[138:141], v[66:81]
	v_mfma_f32_32x32x16_bf16 v[82:97], v[166:169], v[138:141], v[82:97]
	v_mfma_f32_32x32x16_bf16 v[18:33], v[162:165], v[142:145], v[18:33]
	v_mfma_f32_32x32x16_bf16 v[2:17], v[166:169], v[142:145], v[2:17]
	v_mfma_f32_32x32x16_bf16 v[114:129], v[146:149], v[138:141], v[114:129]
	v_mfma_f32_32x32x16_bf16 v[98:113], v[150:153], v[138:141], v[98:113]
	v_mfma_f32_32x32x16_bf16 v[50:65], v[146:149], v[142:145], v[50:65]
	v_mfma_f32_32x32x16_bf16 v[34:49], v[150:153], v[142:145], v[34:49]
	ds_read_b128 v[138:141], v228 offset:24576
	ds_read_b128 v[162:165], v229 offset:32768
	ds_read_b128 v[166:169], v229 offset:34816
	ds_read_b128 v[142:145], v228 offset:26624
	ds_read_b128 v[146:149], v229 offset:36864
	ds_read_b128 v[150:153], v229 offset:38912
	s_add_i32 m0, s20, 0x0
	s_waitcnt lgkmcnt(6)
	v_mfma_f32_32x32x16_bf16 v[66:81], v[182:185], v[154:157], v[66:81]
	global_load_lds_dwordx4 v238, vcc
	v_mfma_f32_32x32x16_bf16 v[82:97], v[178:181], v[154:157], v[82:97]
	global_load_lds_dwordx4 v238, vcc offset:1024
	s_add_i32 m0, s19, 0x2000
	s_add_u32 vcc_lo, vcc_lo, 0x480000
	s_addc_u32 vcc_hi, vcc_hi, 0
	v_mfma_f32_32x32x16_bf16 v[18:33], v[182:185], v[158:161], v[18:33]
	global_load_lds_dwordx4 v239, s[100:101]
	v_mfma_f32_32x32x16_bf16 v[2:17], v[178:181], v[158:161], v[2:17]
	global_load_lds_dwordx4 v239, s[100:101] offset:1024
	v_mfma_f32_32x32x16_bf16 v[114:129], v[174:177], v[154:157], v[114:129]
	global_load_lds_dwordx4 v239, s[100:101] offset:2048
	v_mfma_f32_32x32x16_bf16 v[98:113], v[170:173], v[154:157], v[98:113]
	global_load_lds_dwordx4 v239, s[100:101] offset:3072
	s_add_u32 s100, s100, 0x58000
	s_addc_u32 s101, s101, 0
	v_mfma_f32_32x32x16_bf16 v[50:65], v[174:177], v[158:161], v[50:65]
	v_mfma_f32_32x32x16_bf16 v[34:49], v[170:173], v[158:161], v[34:49]
	s_waitcnt vmcnt(6) lgkmcnt(0)
	s_barrier
; #define LAS __attribute__((address_space(3)))
; DI f32x16 mfma32(bf16x8 a, bf16x8 b, f32x16 c) { return __builtin_amdgcn_mfma_f32_32x32x16_bf16(a, b, c, 0, 0, 0); }
;     ...
;   for (int kt = 0; kt < nk; ++kt) {
;     const int kn = (kt + 2 < nk) ? (kt + 2) : (nk - 1);
;     const LAS char* cur = lds + s0;
;     bf16x8 af[2][2], bfr[2][4];
; #pragma unroll
;     for (int kk = 0; kk < 2; ++kk) {
;       const int xo = kk ? x1 : x0;
;       af[kk][0] = *(const LAS bf16x8*)(cur + a_rd + xo);
;       bfr[kk][0] = *(const LAS bf16x8*)(cur + b_rd + xo);
;       bfr[kk][1] = *(const LAS bf16x8*)(cur + b_rd + 2048 + xo);
;       af[kk][1] = *(const LAS bf16x8*)(cur + a_rd + 2048 + xo);
;       bfr[kk][2] = *(const LAS bf16x8*)(cur + b_rd + 4096 + xo);
;       bfr[kk][3] = *(const LAS bf16x8*)(cur + b_rd + 6144 + xo);
;     }
;     DMA_STEP_(kn, s2);
; #pragma unroll
;     for (int kk = 0; kk < 2; ++kk) {
;       acc[0][0] = mfma32(bfr[kk][0], af[kk][0], acc[0][0]); acc[0][1] = mfma32(bfr[kk][1], af[kk][0], acc[0][1]);
;       acc[1][0] = mfma32(bfr[kk][0], af[kk][1], acc[1][0]); acc[1][1] = mfma32(bfr[kk][1], af[kk][1], acc[1][1]);
;       acc[0][2] = mfma32(bfr[kk][2], af[kk][0], acc[0][2]); acc[0][3] = mfma32(bfr[kk][3], af[kk][0], acc[0][3]);
;       acc[1][2] = mfma32(bfr[kk][2], af[kk][1], acc[1][2]); acc[1][3] = mfma32(bfr[kk][3], af[kk][1], acc[1][3]);
;     }
;     __builtin_amdgcn_sched_group_barrier(0x100, 12, 0);
;     __builtin_amdgcn_sched_group_barrier(0x010, 6, 0);
;     __builtin_amdgcn_sched_group_barrier(0x008, 16, 0);
;     asm volatile("s_waitcnt vmcnt(6) lgkmcnt(0)" ::: "memory");
;     __builtin_amdgcn_s_barrier();
;     asm volatile("" ::: "memory");
;     s0 = (s0 == 2 * STG) ? 0 : s0 + STG;
;     s2 = (s2 == 2 * STG) ? 0 : s2 + STG;
;   }
	ds_read_b128 v[154:157], v226 offset:49152
	ds_read_b128 v[182:185], v227 offset:57344
	ds_read_b128 v[178:181], v227 offset:59392
	ds_read_b128 v[158:161], v226 offset:51200
	ds_read_b128 v[174:177], v227 offset:61440
	ds_read_b128 v[170:173], v227 offset:63488
	v_mfma_f32_32x32x16_bf16 v[66:81], v[162:165], v[138:141], v[66:81]
	v_mfma_f32_32x32x16_bf16 v[82:97], v[166:169], v[138:141], v[82:97]
	v_mfma_f32_32x32x16_bf16 v[18:33], v[162:165], v[142:145], v[18:33]
	v_mfma_f32_32x32x16_bf16 v[2:17], v[166:169], v[142:145], v[2:17]
	v_mfma_f32_32x32x16_bf16 v[114:129], v[146:149], v[138:141], v[114:129]
	v_mfma_f32_32x32x16_bf16 v[98:113], v[150:153], v[138:141], v[98:113]
	v_mfma_f32_32x32x16_bf16 v[50:65], v[146:149], v[142:145], v[50:65]
	v_mfma_f32_32x32x16_bf16 v[34:49], v[150:153], v[142:145], v[34:49]
	ds_read_b128 v[138:141], v228 offset:49152
	ds_read_b128 v[162:165], v229 offset:57344
	ds_read_b128 v[166:169], v229 offset:59392
	ds_read_b128 v[142:145], v228 offset:51200
	ds_read_b128 v[146:149], v229 offset:61440
	ds_read_b128 v[150:153], v229 offset:63488
	s_add_i32 m0, s20, 0x6000
	s_waitcnt lgkmcnt(6)
	v_mfma_f32_32x32x16_bf16 v[66:81], v[182:185], v[154:157], v[66:81]
	global_load_lds_dwordx4 v238, vcc
	v_mfma_f32_32x32x16_bf16 v[82:97], v[178:181], v[154:157], v[82:97]
	global_load_lds_dwordx4 v238, vcc offset:1024
	s_add_i32 m0, s19, 0x8000
	s_add_u32 vcc_lo, vcc_lo, 0x480000
	s_addc_u32 vcc_hi, vcc_hi, 0
	v_mfma_f32_32x32x16_bf16 v[18:33], v[182:185], v[158:161], v[18:33]
	global_load_lds_dwordx4 v239, s[100:101]
	v_mfma_f32_32x32x16_bf16 v[2:17], v[178:181], v[158:161], v[2:17]
	global_load_lds_dwordx4 v239, s[100:101] offset:1024
	v_mfma_f32_32x32x16_bf16 v[114:129], v[174:177], v[154:157], v[114:129]
	global_load_lds_dwordx4 v239, s[100:101] offset:2048
	v_mfma_f32_32x32x16_bf16 v[98:113], v[170:173], v[154:157], v[98:113]
	global_load_lds_dwordx4 v239, s[100:101] offset:3072
	s_add_u32 s100, s100, 0x58000
	s_addc_u32 s101, s101, 0
	v_mfma_f32_32x32x16_bf16 v[50:65], v[174:177], v[158:161], v[50:65]
	v_mfma_f32_32x32x16_bf16 v[34:49], v[170:173], v[158:161], v[34:49]
	s_waitcnt vmcnt(6) lgkmcnt(0)
	s_barrier
	ds_read_b128 v[154:157], v226 offset:0
	ds_read_b128 v[182:185], v227 offset:8192
	ds_read_b128 v[178:181], v227 offset:10240
	ds_read_b128 v[158:161], v226 offset:2048
	ds_read_b128 v[174:177], v227 offset:12288
	ds_read_b128 v[170:173], v227 offset:14336
	v_mfma_f32_32x32x16_bf16 v[66:81], v[162:165], v[138:141], v[66:81]
	v_mfma_f32_32x32x16_bf16 v[82:97], v[166:169], v[138:141], v[82:97]
	v_mfma_f32_32x32x16_bf16 v[18:33], v[162:165], v[142:145], v[18:33]
	v_mfma_f32_32x32x16_bf16 v[2:17], v[166:169], v[142:145], v[2:17]
	v_mfma_f32_32x32x16_bf16 v[114:129], v[146:149], v[138:141], v[114:129]
	v_mfma_f32_32x32x16_bf16 v[98:113], v[150:153], v[138:141], v[98:113]
	v_mfma_f32_32x32x16_bf16 v[50:65], v[146:149], v[142:145], v[50:65]
	v_mfma_f32_32x32x16_bf16 v[34:49], v[150:153], v[142:145], v[34:49]
	s_add_i32 s21, s21, 6
	s_cmp_eq_u32 s21, 30
	s_cbranch_scc0 .LBB0_272
	ds_read_b128 v[138:141], v228 offset:0
	ds_read_b128 v[162:165], v229 offset:8192
	ds_read_b128 v[166:169], v229 offset:10240
	ds_read_b128 v[142:145], v228 offset:2048
	ds_read_b128 v[146:149], v229 offset:12288
	ds_read_b128 v[150:153], v229 offset:14336
	s_waitcnt lgkmcnt(6)
	v_mfma_f32_32x32x16_bf16 v[66:81], v[182:185], v[154:157], v[66:81]
	v_mfma_f32_32x32x16_bf16 v[82:97], v[178:181], v[154:157], v[82:97]
	v_mfma_f32_32x32x16_bf16 v[18:33], v[182:185], v[158:161], v[18:33]
	v_mfma_f32_32x32x16_bf16 v[2:17], v[178:181], v[158:161], v[2:17]
	v_mfma_f32_32x32x16_bf16 v[114:129], v[174:177], v[154:157], v[114:129]
	v_mfma_f32_32x32x16_bf16 v[98:113], v[170:173], v[154:157], v[98:113]
	v_mfma_f32_32x32x16_bf16 v[50:65], v[174:177], v[158:161], v[50:65]
	v_mfma_f32_32x32x16_bf16 v[34:49], v[170:173], v[158:161], v[34:49]
	s_waitcnt vmcnt(0) lgkmcnt(0)
	s_barrier
;     ...
;   for (int kt = 0; kt < nk; ++kt) {
;     const int kn = (kt + 2 < nk) ? (kt + 2) : (nk - 1);
;     const LAS char* cur = lds + s0;
;     bf16x8 af[2][2], bfr[2][4];
; #pragma unroll
;     for (int kk = 0; kk < 2; ++kk) {
;       const int xo = kk ? x1 : x0;
;       af[kk][0] = *(const LAS bf16x8*)(cur + a_rd + xo);
;       bfr[kk][0] = *(const LAS bf16x8*)(cur + b_rd + xo);
;       bfr[kk][1] = *(const LAS bf16x8*)(cur + b_rd + 2048 + xo);
;       af[kk][1] = *(const LAS bf16x8*)(cur + a_rd + 2048 + xo);
;       bfr[kk][2] = *(const LAS bf16x8*)(cur + b_rd + 4096 + xo);
;       bfr[kk][3] = *(const LAS bf16x8*)(cur + b_rd + 6144 + xo);
;     }
;     DMA_STEP_(kn, s2);
; #pragma unroll
;     for (int kk = 0; kk < 2; ++kk) {
;       acc[0][0] = mfma32(bfr[kk][0], af[kk][0], acc[0][0]); acc[0][1] = mfma32(bfr[kk][1], af[kk][0], acc[0][1]);
;       acc[1][0] = mfma32(bfr[kk][0], af[kk][1], acc[1][0]); acc[1][1] = mfma32(bfr[kk][1], af[kk][1], acc[1][1]);
;       acc[0][2] = mfma32(bfr[kk][2], af[kk][0], acc[0][2]); acc[0][3] = mfma32(bfr[kk][3], af[kk][0], acc[0][3]);
;       acc[1][2] = mfma32(bfr[kk][2], af[kk][1], acc[1][2]); acc[1][3] = mfma32(bfr[kk][3], af[kk][1], acc[1][3]);
;     }
;     __builtin_amdgcn_sched_group_barrier(0x100, 12, 0);
;     __builtin_amdgcn_sched_group_barrier(0x010, 6, 0);
;     __builtin_amdgcn_sched_group_barrier(0x008, 16, 0);
;     asm volatile("s_waitcnt vmcnt(6) lgkmcnt(0)" ::: "memory");
;     __builtin_amdgcn_s_barrier();
;     asm volatile("" ::: "memory");
;     s0 = (s0 == 2 * STG) ? 0 : s0 + STG;
;     s2 = (s2 == 2 * STG) ? 0 : s2 + STG;
;   }
;   asm volatile("s_waitcnt vmcnt(0)" ::: "memory");
;   __builtin_amdgcn_s_barrier();
;   asm volatile("" ::: "memory");
;     ...
;   {
;     const int h = lane >> 5, cl = lane & 31;
; #pragma unroll
;     for (int i = 0; i < 2; ++i)
; #pragma unroll
;       for (int j = 0; j < 4; ++j)
; #pragma unroll
;         for (int g = 0; g < 4; ++g) {
;           u32x2 w; w.x = pk2(acc[i][j][4 * g], acc[i][j][4 * g + 1]); w.y = pk2(acc[i][j][4 * g + 2], acc[i][j][4 * g + 3]);
;           *(u32x2*)(smem + (wr * 64 + i * 32 + cl) * 528 + (wc * 128 + j * 32 + 8 * g + 4 * h) * 2) = w;
;         }
;   }
;   __syncthreads();
;     ...
;     const int L = (mt < 512) ? 2048 : 256;
;     const bool first = (m0 % L) == 0, last = ((m0 + 128) % L) == 0;
;     const float* cw = ea.cw; const float* cb = ea.cb;
	ds_read_b128 v[154:157], v226 offset:24576
	ds_read_b128 v[182:185], v227 offset:32768
	ds_read_b128 v[178:181], v227 offset:34816
	ds_read_b128 v[158:161], v226 offset:26624
	ds_read_b128 v[174:177], v227 offset:36864
	ds_read_b128 v[170:173], v227 offset:38912
	v_mfma_f32_32x32x16_bf16 v[66:81], v[162:165], v[138:141], v[66:81]
	v_mfma_f32_32x32x16_bf16 v[82:97], v[166:169], v[138:141], v[82:97]
	v_mfma_f32_32x32x16_bf16 v[18:33], v[162:165], v[142:145], v[18:33]
	v_mfma_f32_32x32x16_bf16 v[2:17], v[166:169], v[142:145], v[2:17]
	v_mfma_f32_32x32x16_bf16 v[114:129], v[146:149], v[138:141], v[114:129]
	v_mfma_f32_32x32x16_bf16 v[98:113], v[150:153], v[138:141], v[98:113]
	v_mfma_f32_32x32x16_bf16 v[50:65], v[146:149], v[142:145], v[50:65]
	v_mfma_f32_32x32x16_bf16 v[34:49], v[150:153], v[142:145], v[34:49]
	ds_read_b128 v[138:141], v228 offset:24576
	ds_read_b128 v[162:165], v229 offset:32768
	ds_read_b128 v[166:169], v229 offset:34816
	ds_read_b128 v[142:145], v228 offset:26624
	ds_read_b128 v[146:149], v229 offset:36864
	ds_read_b128 v[150:153], v229 offset:38912
	s_waitcnt lgkmcnt(6)
	v_mfma_f32_32x32x16_bf16 v[66:81], v[182:185], v[154:157], v[66:81]
	v_mfma_f32_32x32x16_bf16 v[82:97], v[178:181], v[154:157], v[82:97]
	v_mfma_f32_32x32x16_bf16 v[18:33], v[182:185], v[158:161], v[18:33]
	v_mfma_f32_32x32x16_bf16 v[2:17], v[178:181], v[158:161], v[2:17]
	v_mfma_f32_32x32x16_bf16 v[114:129], v[174:177], v[154:157], v[114:129]
	v_mfma_f32_32x32x16_bf16 v[98:113], v[170:173], v[154:157], v[98:113]
	v_mfma_f32_32x32x16_bf16 v[50:65], v[174:177], v[158:161], v[50:65]
	v_mfma_f32_32x32x16_bf16 v[34:49], v[170:173], v[158:161], v[34:49]
	s_waitcnt lgkmcnt(0)
	v_mfma_f32_32x32x16_bf16 v[66:81], v[162:165], v[138:141], v[66:81]
	v_mfma_f32_32x32x16_bf16 v[82:97], v[166:169], v[138:141], v[82:97]
	v_mfma_f32_32x32x16_bf16 v[18:33], v[162:165], v[142:145], v[18:33]
	v_mfma_f32_32x32x16_bf16 v[2:17], v[166:169], v[142:145], v[2:17]
	v_mfma_f32_32x32x16_bf16 v[114:129], v[146:149], v[138:141], v[114:129]
	v_mfma_f32_32x32x16_bf16 v[98:113], v[150:153], v[138:141], v[98:113]
	v_mfma_f32_32x32x16_bf16 v[50:65], v[146:149], v[142:145], v[50:65]
	v_mfma_f32_32x32x16_bf16 v[34:49], v[150:153], v[142:145], v[34:49]
	s_waitcnt lgkmcnt(0)
	s_mov_b32 s101, 0
	s_setprio 0
	v_mul_lo_u32 v0, v197, s55
	v_add_u32_e32 v0, 16, v0
	s_nop 1
	v_cvt_pk_bf16_f32 v66, v66, v67
	v_cvt_pk_bf16_f32 v67, v68, v69
	v_lshlrev_b32_e32 v68, 3, v196
	s_lshl_b32 s10, s18, 1
	v_add3_u32 v0, v0, v68, s10
	v_cvt_pk_bf16_f32 v68, v70, v71
	v_cvt_pk_bf16_f32 v69, v72, v73
	s_waitcnt vmcnt(0)
	s_barrier
	ds_write2_b64 v0, v[66:67], v[68:69] offset1:2
	v_cvt_pk_bf16_f32 v66, v74, v75
	v_cvt_pk_bf16_f32 v67, v76, v77
	v_cvt_pk_bf16_f32 v68, v78, v79
	v_cvt_pk_bf16_f32 v69, v80, v81
	ds_write2_b64 v0, v[66:67], v[68:69] offset0:4 offset1:6
	v_cvt_pk_bf16_f32 v66, v82, v83
	v_cvt_pk_bf16_f32 v67, v84, v85
	v_cvt_pk_bf16_f32 v68, v86, v87
	v_cvt_pk_bf16_f32 v69, v88, v89
	ds_write2_b64 v0, v[66:67], v[68:69] offset0:8 offset1:10
	v_cvt_pk_bf16_f32 v66, v90, v91
	v_cvt_pk_bf16_f32 v67, v92, v93
	v_cvt_pk_bf16_f32 v68, v94, v95
	v_cvt_pk_bf16_f32 v69, v96, v97
	ds_write2_b64 v0, v[66:67], v[68:69] offset0:12 offset1:14
	v_cvt_pk_bf16_f32 v66, v114, v115
	v_cvt_pk_bf16_f32 v67, v116, v117
	v_cvt_pk_bf16_f32 v68, v118, v119
	v_cvt_pk_bf16_f32 v69, v120, v121
	ds_write2_b64 v0, v[66:67], v[68:69] offset0:16 offset1:18
	v_cvt_pk_bf16_f32 v66, v122, v123
	v_cvt_pk_bf16_f32 v67, v124, v125
	v_cvt_pk_bf16_f32 v68, v126, v127
	v_cvt_pk_bf16_f32 v69, v128, v129
	ds_write2_b64 v0, v[66:67], v[68:69] offset0:20 offset1:22
	v_cvt_pk_bf16_f32 v66, v98, v99
	v_cvt_pk_bf16_f32 v67, v100, v101
	v_cvt_pk_bf16_f32 v68, v102, v103
	v_cvt_pk_bf16_f32 v69, v104, v105
	ds_write2_b64 v0, v[66:67], v[68:69] offset0:24 offset1:26
	v_cvt_pk_bf16_f32 v66, v106, v107
	v_cvt_pk_bf16_f32 v67, v108, v109
	v_cvt_pk_bf16_f32 v68, v110, v111
	v_cvt_pk_bf16_f32 v69, v112, v113
	ds_write2_b64 v0, v[66:67], v[68:69] offset0:28 offset1:30
	v_add_u32_e32 v0, 0x4000, v0
	v_cvt_pk_bf16_f32 v2, v2, v3
	v_cvt_pk_bf16_f32 v3, v4, v5
	v_cvt_pk_bf16_f32 v4, v6, v7
	v_cvt_pk_bf16_f32 v5, v8, v9
	ds_write2_b64 v0, v[2:3], v[4:5] offset0:72 offset1:74
	v_cvt_pk_bf16_f32 v2, v10, v11
	v_cvt_pk_bf16_f32 v3, v12, v13
	v_cvt_pk_bf16_f32 v4, v14, v15
	v_cvt_pk_bf16_f32 v5, v16, v17
	ds_write2_b64 v0, v[2:3], v[4:5] offset0:76 offset1:78
	v_cvt_pk_bf16_f32 v2, v50, v51
	v_cvt_pk_bf16_f32 v3, v52, v53
	v_cvt_pk_bf16_f32 v4, v54, v55
	v_cvt_pk_bf16_f32 v5, v56, v57
	s_cmpk_lt_i32 s15, 0x200
	ds_write2_b64 v0, v[2:3], v[4:5] offset0:80 offset1:82
	v_cvt_pk_bf16_f32 v2, v58, v59
	v_cvt_pk_bf16_f32 v3, v60, v61
	v_cvt_pk_bf16_f32 v4, v62, v63
	v_cvt_pk_bf16_f32 v5, v64, v65
	s_cselect_b32 s10, 0x7ff, s78
	v_cvt_pk_bf16_f32 v18, v18, v19
	v_cvt_pk_bf16_f32 v19, v20, v21
	v_cvt_pk_bf16_f32 v20, v22, v23
	v_cvt_pk_bf16_f32 v21, v24, v25
	ds_write2_b64 v0, v[2:3], v[4:5] offset0:84 offset1:86
	v_cvt_pk_bf16_f32 v2, v34, v35
	v_cvt_pk_bf16_f32 v3, v36, v37
	v_cvt_pk_bf16_f32 v4, v38, v39
	v_cvt_pk_bf16_f32 v5, v40, v41
	s_and_b32 s11, s10, s46
	ds_write2_b64 v0, v[18:19], v[20:21] offset0:64 offset1:66
	v_cvt_pk_bf16_f32 v18, v26, v27
	v_cvt_pk_bf16_f32 v19, v28, v29
	v_cvt_pk_bf16_f32 v20, v30, v31
	v_cvt_pk_bf16_f32 v21, v32, v33
	ds_write2_b64 v0, v[2:3], v[4:5] offset0:88 offset1:90
	v_cvt_pk_bf16_f32 v2, v42, v43
	v_cvt_pk_bf16_f32 v3, v44, v45
	v_cvt_pk_bf16_f32 v4, v46, v47
	v_cvt_pk_bf16_f32 v5, v48, v49
	s_cmp_eq_u32 s11, 0
	ds_write2_b64 v0, v[18:19], v[20:21] offset0:68 offset1:70
	ds_write2_b64 v0, v[2:3], v[4:5] offset0:92 offset1:94
	s_waitcnt vmcnt(0) lgkmcnt(0)
	s_barrier
	s_cselect_b64 s[18:19], -1, 0
	s_add_i32 s11, s46, 0x80
	v_lshlrev_b32_e32 v0, 3, v189
	s_and_b32 s10, s11, s10
	v_and_b32_e32 v96, 56, v0
	s_cmp_eq_u32 s10, 0
	v_lshlrev_b32_e32 v0, 1, v96
	v_lshrrev_b32_e32 v98, 7, v189
	s_nop 0
	v_readfirstlane_b32 s40, v98
	s_cselect_b64 s[20:21], -1, 0
	s_lshl_b32 s47, s22, 7
	v_add_u32_e32 v97, 16, v0
	v_lshl_add_u64 v[90:91], s[44:45], 0, v[0:1]
	s_mov_b64 s[28:29], 0
	s_branch .LBB0_275
